# K-loops: post-MFMA barrier executed 1 MFMA early; setprio flips + duplicate lgkmcnt removed
# speedup vs baseline: 1.0296x; 1.0296x over previous
; #define PG8_STAGE(bufoff, gbase, voff) do { _Pragma("unroll") for (int _i = 0; _i < 2; ++_i) \
;         __builtin_amdgcn_global_load_lds((const unsigned*)((const char*)(gbase) + (voff)[_i]), (LAS unsigned*)(lds + (bufoff) + ldsw + _i * 8192), 16, 0, 0); } while (0)
; #define PG8_WAIT_V(n) asm volatile("s_waitcnt vmcnt(" #n ")" ::: "memory")
; #define PG8_WAIT_L(n) asm volatile("s_waitcnt lgkmcnt(" #n ")" ::: "memory")
; template <int MODE, class EpiT, class Sched>
; __device__ __forceinline__ void gemm_phase(LAS unsigned char* lds, const Gemm g, const Sched& S, const EpiT& E) {
;     ...
;         const bool has_next = S.next(ui + 1, nxt);
;         const char* nA = has_next ? (const char*)g.A + (size_t)nxt.pm * tstep : cA; const char* nB = has_next ? (const char*)g.Bt + (size_t)nxt.pn * tstep : cB;
;         for (int t = 0; t < nt; t += 2) {
;             const bool last = (t == nt - 2);
;             const char* a1 = cA + (size_t)(t + 1) * kstep;
;             const char* a2 = last ? nA : cA + (size_t)(t + 2) * kstep; const char* b2 = last ? nB : cB + (size_t)(t + 2) * kstep;
;             const char* a3 = a2 + kstep; const char* b3 = b2 + kstep;
;             PG8_LDB(B0, 0, 0); PG8_SCHED; PG8_LDA(At, 0, 0); PG8_STAGE(PG8_SA(1, 1), a1 + hstep, voffA);
;             PG8_WAIT_L(8); PG8_BAR; PG8_WAIT_L(0); PG8_MMA(0, 0, At, B0); PG8_BAR; PG8_SCHED;
;             PG8_LDB(B1, 0, 1); PG8_STAGE(PG8_SB(0, 0), b2, voffB);
;             PG8_BAR; PG8_WAIT_L(0); PG8_MMA(0, 1, At, B1); PG8_BAR;
;             PG8_LDA(At, 0, 1); PG8_STAGE(PG8_SA(0, 0), a2, voffA);
;             PG8_BAR; PG8_WAIT_L(0); PG8_MMA(1, 0, At, B0); PG8_BAR; PG8_SCHED;
;             PG8_STAGE(PG8_SB(0, 1), b2 + hstep, voffB);
;             PG8_WAIT_V(6); PG8_BAR; PG8_MMA(1, 1, At, B1); PG8_BAR;
;             PG8_LDB(B0, 1, 0); PG8_SCHED; PG8_LDA(At, 1, 0); PG8_STAGE(PG8_SA(0, 1), a2 + hstep, voffA);
;             PG8_WAIT_L(8); PG8_BAR; PG8_WAIT_L(0); PG8_MMA(0, 0, At, B0); PG8_BAR; PG8_SCHED;
;             PG8_LDB(B1, 1, 1); PG8_STAGE(PG8_SB(1, 0), b3, voffB);
;             PG8_BAR; PG8_WAIT_L(0); PG8_MMA(0, 1, At, B1); PG8_BAR;
;             PG8_LDA(At, 1, 1); PG8_STAGE(PG8_SA(1, 0), a3, voffA);
;             PG8_BAR; PG8_WAIT_L(0); PG8_MMA(1, 0, At, B0); PG8_BAR; PG8_SCHED;
;             PG8_STAGE(PG8_SB(1, 1), b3 + hstep, voffB);
;             PG8_WAIT_V(6); PG8_BAR; PG8_MMA(1, 1, At, B1); PG8_BAR;
.LBB0_115:
	s_add_i32 s58, s52, 2
	s_add_u32 s59, s44, 0x80
	s_addc_u32 s53, s45, 0
	s_add_i32 s91, 0, 0x10000
	v_add_u32_e32 v86, s91, v192
	ds_read_b128 v[70:73], v86
	ds_read_b128 v[74:77], v86 offset:1024
	ds_read_b128 v[82:85], v86 offset:2048
	ds_read_b128 v[86:89], v86 offset:3072
	s_cmp_eq_u32 s57, s52
	s_cselect_b32 s52, s4, s59
	s_cselect_b32 s53, s5, s53
	s_cselect_b32 s75, s47, vcc_hi
	s_cselect_b32 s74, s46, vcc_lo
	v_lshl_add_u64 v[188:189], s[44:45], 0, v[176:177]
	s_add_i32 m0, s20, 0xc000
	ds_read_b128 v[138:141], v194
	ds_read_b128 v[142:145], v194 offset:1024
	ds_read_b128 v[146:149], v194 offset:2048
	ds_read_b128 v[154:157], v194 offset:3072
	ds_read_b128 v[162:165], v194 offset:4096
	ds_read_b128 v[166:169], v194 offset:5120
	ds_read_b128 v[170:173], v194 offset:6144
	ds_read_b128 v[184:187], v194 offset:7168
	global_load_lds_dwordx4 v[188:189], off
	v_lshl_add_u64 v[188:189], s[44:45], 0, v[182:183]
	s_add_i32 m0, s20, 0xe000
	s_nop 0
	global_load_lds_dwordx4 v[188:189], off
	s_waitcnt lgkmcnt(8)
	s_barrier
	s_waitcnt lgkmcnt(0)
	v_mfma_f32_16x16x32_bf16 v[158:161], v[70:73], v[138:141], v[158:161]
	v_mfma_f32_16x16x32_bf16 v[150:153], v[82:85], v[138:141], v[150:153]
	v_mfma_f32_16x16x32_bf16 v[126:129], v[70:73], v[146:149], v[126:129]
	v_mfma_f32_16x16x32_bf16 v[122:125], v[82:85], v[146:149], v[122:125]
	v_mfma_f32_16x16x32_bf16 v[110:113], v[70:73], v[162:165], v[110:113]
	v_mfma_f32_16x16x32_bf16 v[106:109], v[82:85], v[162:165], v[106:109]
	v_mfma_f32_16x16x32_bf16 v[94:97], v[70:73], v[170:173], v[94:97]
	v_mfma_f32_16x16x32_bf16 v[90:93], v[82:85], v[170:173], v[90:93]
	v_mfma_f32_16x16x32_bf16 v[158:161], v[74:77], v[142:145], v[158:161]
	v_mfma_f32_16x16x32_bf16 v[150:153], v[86:89], v[142:145], v[150:153]
	v_mfma_f32_16x16x32_bf16 v[126:129], v[74:77], v[154:157], v[126:129]
	v_mfma_f32_16x16x32_bf16 v[122:125], v[86:89], v[154:157], v[122:125]
	v_mfma_f32_16x16x32_bf16 v[110:113], v[74:77], v[166:169], v[110:113]
	v_mfma_f32_16x16x32_bf16 v[106:109], v[86:89], v[166:169], v[106:109]
	v_mfma_f32_16x16x32_bf16 v[94:97], v[74:77], v[184:187], v[94:97]
	s_barrier
	v_mfma_f32_16x16x32_bf16 v[90:93], v[86:89], v[184:187], v[90:93]
	s_add_i32 s59, 0, 0x14000
	s_add_i32 s91, s91, s9
	v_add_u32_e32 v195, s59, v192
	v_lshl_add_u64 v[228:229], s[74:75], 0, v[0:1]
	s_mov_b32 m0, s91
	ds_read_b128 v[188:191], v195
	ds_read_b128 v[196:199], v195 offset:1024
	ds_read_b128 v[220:223], v195 offset:2048
	ds_read_b128 v[224:227], v195 offset:3072
	global_load_lds_dwordx4 v[228:229], off
	v_lshl_add_u64 v[230:231], s[74:75], 0, v[174:175]
	s_add_i32 m0, s91, 0x2000
	s_nop 0
	global_load_lds_dwordx4 v[230:231], off
	s_barrier
	s_waitcnt lgkmcnt(0)
	v_mfma_f32_16x16x32_bf16 v[134:137], v[188:191], v[138:141], v[134:137]
	v_mfma_f32_16x16x32_bf16 v[130:133], v[220:223], v[138:141], v[130:133]
	v_mfma_f32_16x16x32_bf16 v[118:121], v[188:191], v[146:149], v[118:121]
	v_mfma_f32_16x16x32_bf16 v[114:117], v[220:223], v[146:149], v[114:117]
	v_mfma_f32_16x16x32_bf16 v[102:105], v[188:191], v[162:165], v[102:105]
	v_mfma_f32_16x16x32_bf16 v[98:101], v[220:223], v[162:165], v[98:101]
	v_mfma_f32_16x16x32_bf16 v[78:81], v[188:191], v[170:173], v[78:81]
	v_mfma_f32_16x16x32_bf16 v[66:69], v[220:223], v[170:173], v[66:69]
	v_mfma_f32_16x16x32_bf16 v[134:137], v[196:199], v[142:145], v[134:137]
	v_mfma_f32_16x16x32_bf16 v[130:133], v[224:227], v[142:145], v[130:133]
	v_mfma_f32_16x16x32_bf16 v[118:121], v[196:199], v[154:157], v[118:121]
	v_mfma_f32_16x16x32_bf16 v[114:117], v[224:227], v[154:157], v[114:117]
	v_mfma_f32_16x16x32_bf16 v[102:105], v[196:199], v[166:169], v[102:105]
	v_mfma_f32_16x16x32_bf16 v[98:101], v[224:227], v[166:169], v[98:101]
	v_mfma_f32_16x16x32_bf16 v[78:81], v[196:199], v[184:187], v[78:81]
	s_barrier
	v_mfma_f32_16x16x32_bf16 v[66:69], v[224:227], v[184:187], v[66:69]
	s_mov_b32 m0, s20
	v_lshl_add_u64 v[232:233], s[52:53], 0, v[0:1]
	ds_read_b128 v[138:141], v194 offset:16384
	ds_read_b128 v[142:145], v194 offset:17408
	ds_read_b128 v[146:149], v194 offset:18432
	ds_read_b128 v[154:157], v194 offset:19456
	ds_read_b128 v[162:165], v194 offset:20480
	ds_read_b128 v[166:169], v194 offset:21504
	ds_read_b128 v[170:173], v194 offset:22528
	ds_read_b128 v[184:187], v194 offset:23552
	global_load_lds_dwordx4 v[232:233], off
	v_lshl_add_u64 v[234:235], s[52:53], 0, v[174:175]
	s_mov_b32 m0, s21
	s_nop 0
	global_load_lds_dwordx4 v[234:235], off
	s_barrier
	s_waitcnt lgkmcnt(0)
	v_mfma_f32_16x16x32_bf16 v[62:65], v[70:73], v[138:141], v[62:65]
	v_mfma_f32_16x16x32_bf16 v[58:61], v[82:85], v[138:141], v[58:61]
	v_mfma_f32_16x16x32_bf16 v[46:49], v[70:73], v[146:149], v[46:49]
	v_mfma_f32_16x16x32_bf16 v[42:45], v[82:85], v[146:149], v[42:45]
	v_mfma_f32_16x16x32_bf16 v[30:33], v[70:73], v[162:165], v[30:33]
	v_mfma_f32_16x16x32_bf16 v[26:29], v[82:85], v[162:165], v[26:29]
	v_mfma_f32_16x16x32_bf16 v[14:17], v[70:73], v[170:173], v[14:17]
	v_mfma_f32_16x16x32_bf16 v[10:13], v[82:85], v[170:173], v[10:13]
	v_mfma_f32_16x16x32_bf16 v[62:65], v[74:77], v[142:145], v[62:65]
	v_mfma_f32_16x16x32_bf16 v[58:61], v[86:89], v[142:145], v[58:61]
	v_mfma_f32_16x16x32_bf16 v[46:49], v[74:77], v[154:157], v[46:49]
	v_mfma_f32_16x16x32_bf16 v[42:45], v[86:89], v[154:157], v[42:45]
	v_mfma_f32_16x16x32_bf16 v[30:33], v[74:77], v[166:169], v[30:33]
	v_mfma_f32_16x16x32_bf16 v[26:29], v[86:89], v[166:169], v[26:29]
	v_mfma_f32_16x16x32_bf16 v[14:17], v[74:77], v[184:187], v[14:17]
	s_barrier
; #define PG8_STAGE(bufoff, gbase, voff) do { _Pragma("unroll") for (int _i = 0; _i < 2; ++_i) \
;         __builtin_amdgcn_global_load_lds((const unsigned*)((const char*)(gbase) + (voff)[_i]), (LAS unsigned*)(lds + (bufoff) + ldsw + _i * 8192), 16, 0, 0); } while (0)
; #define PG8_LDA(dst, b, h) do { _Pragma("unroll") for (int m = 0; m < 4; ++m) _Pragma("unroll") for (int k = 0; k < 2; ++k) dst[m][k] = *(const LAS bf16x8*)(lds + PG8_SA(b, h) + aoff + m * 2048 + k * 1024); } while (0)
; #define PG8_LDB(dst, b, h) do { _Pragma("unroll") for (int n = 0; n < 2; ++n) _Pragma("unroll") for (int k = 0; k < 2; ++k) dst[n][k] = *(const LAS bf16x8*)(lds + PG8_SB(b, h) + boff + n * 2048 + k * 1024); } while (0)
; #define PG8_WAIT_V(n) asm volatile("s_waitcnt vmcnt(" #n ")" ::: "memory")
; #define PG8_WAIT_L(n) asm volatile("s_waitcnt lgkmcnt(" #n ")" ::: "memory")
; #define PG8_BAR __builtin_amdgcn_s_barrier()
; #define PG8_SCHED __builtin_amdgcn_sched_barrier(0)
; template <int MODE, class EpiT, class Sched>
; __device__ __forceinline__ void gemm_phase(LAS unsigned char* lds, const Gemm g, const Sched& S, const EpiT& E) {
;     ...
;             PG8_LDB(B0, 0, 0); PG8_SCHED; PG8_LDA(At, 0, 0); PG8_STAGE(PG8_SA(1, 1), a1 + hstep, voffA);
;             PG8_WAIT_L(8); PG8_BAR; PG8_WAIT_L(0); PG8_MMA(0, 0, At, B0); PG8_BAR; PG8_SCHED;
;             PG8_LDB(B1, 0, 1); PG8_STAGE(PG8_SB(0, 0), b2, voffB);
;             PG8_BAR; PG8_WAIT_L(0); PG8_MMA(0, 1, At, B1); PG8_BAR;
;             PG8_LDA(At, 0, 1); PG8_STAGE(PG8_SA(0, 0), a2, voffA);
;             PG8_BAR; PG8_WAIT_L(0); PG8_MMA(1, 0, At, B0); PG8_BAR; PG8_SCHED;
;             PG8_STAGE(PG8_SB(0, 1), b2 + hstep, voffB);
;             PG8_WAIT_V(6); PG8_BAR; PG8_MMA(1, 1, At, B1); PG8_BAR;
;             PG8_LDB(B0, 1, 0); PG8_SCHED; PG8_LDA(At, 1, 0); PG8_STAGE(PG8_SA(0, 1), a2 + hstep, voffA);
;             PG8_WAIT_L(8); PG8_BAR; PG8_WAIT_L(0); PG8_MMA(0, 0, At, B0); PG8_BAR; PG8_SCHED;
;             PG8_LDB(B1, 1, 1); PG8_STAGE(PG8_SB(1, 0), b3, voffB);
;             PG8_BAR; PG8_WAIT_L(0); PG8_MMA(0, 1, At, B1); PG8_BAR;
;             PG8_LDA(At, 1, 1); PG8_STAGE(PG8_SA(1, 0), a3, voffA);
;             PG8_BAR; PG8_WAIT_L(0); PG8_MMA(1, 0, At, B0); PG8_BAR; PG8_SCHED;
;             PG8_STAGE(PG8_SB(1, 1), b3 + hstep, voffB);
;             PG8_WAIT_V(6); PG8_BAR; PG8_MMA(1, 1, At, B1); PG8_BAR;
	v_mfma_f32_16x16x32_bf16 v[10:13], v[86:89], v[184:187], v[10:13]
	s_add_u32 s74, s74, s78
	s_addc_u32 s75, s75, 0
	s_add_i32 s59, s59, s9
	v_lshl_add_u64 v[236:237], s[74:75], 0, v[0:1]
	s_mov_b32 m0, s59
	v_lshl_add_u64 v[238:239], s[74:75], 0, v[174:175]
	global_load_lds_dwordx4 v[236:237], off
	s_add_i32 m0, s59, 0x2000
	s_nop 0
	global_load_lds_dwordx4 v[238:239], off
	s_waitcnt vmcnt(6)
	s_barrier
	v_mfma_f32_16x16x32_bf16 v[54:57], v[188:191], v[138:141], v[54:57]
	v_mfma_f32_16x16x32_bf16 v[50:53], v[220:223], v[138:141], v[50:53]
	v_mfma_f32_16x16x32_bf16 v[38:41], v[188:191], v[146:149], v[38:41]
	v_mfma_f32_16x16x32_bf16 v[34:37], v[220:223], v[146:149], v[34:37]
	v_mfma_f32_16x16x32_bf16 v[22:25], v[188:191], v[162:165], v[22:25]
	v_mfma_f32_16x16x32_bf16 v[18:21], v[220:223], v[162:165], v[18:21]
	v_mfma_f32_16x16x32_bf16 v[6:9], v[188:191], v[170:173], v[6:9]
	v_mfma_f32_16x16x32_bf16 v[2:5], v[220:223], v[170:173], v[2:5]
	v_mfma_f32_16x16x32_bf16 v[54:57], v[196:199], v[142:145], v[54:57]
	v_mfma_f32_16x16x32_bf16 v[50:53], v[224:227], v[142:145], v[50:53]
	v_mfma_f32_16x16x32_bf16 v[38:41], v[196:199], v[154:157], v[38:41]
	v_mfma_f32_16x16x32_bf16 v[34:37], v[224:227], v[154:157], v[34:37]
	v_mfma_f32_16x16x32_bf16 v[22:25], v[196:199], v[166:169], v[22:25]
	v_mfma_f32_16x16x32_bf16 v[18:21], v[224:227], v[166:169], v[18:21]
	v_mfma_f32_16x16x32_bf16 v[6:9], v[196:199], v[184:187], v[6:9]
	s_barrier
	v_mfma_f32_16x16x32_bf16 v[2:5], v[224:227], v[184:187], v[2:5]
	s_add_i32 s59, 0, 0x18000
	v_add_u32_e32 v86, s59, v192
	ds_read_b128 v[70:73], v86
	ds_read_b128 v[74:77], v86 offset:1024
	ds_read_b128 v[82:85], v86 offset:2048
	ds_read_b128 v[86:89], v86 offset:3072
	s_add_u32 s52, s52, s78
	s_addc_u32 s53, s53, 0
	s_mov_b32 m0, s22
	v_lshl_add_u64 v[188:189], s[52:53], 0, v[0:1]
	ds_read_b128 v[138:141], v194 offset:32768
	ds_read_b128 v[142:145], v194 offset:33792
	ds_read_b128 v[146:149], v194 offset:34816
	ds_read_b128 v[154:157], v194 offset:35840
	ds_read_b128 v[162:165], v194 offset:36864
	ds_read_b128 v[166:169], v194 offset:37888
	ds_read_b128 v[170:173], v194 offset:38912
	ds_read_b128 v[184:187], v194 offset:39936
	global_load_lds_dwordx4 v[188:189], off
	v_lshl_add_u64 v[188:189], s[52:53], 0, v[174:175]
	s_mov_b32 m0, s23
	s_nop 0
	global_load_lds_dwordx4 v[188:189], off
	s_waitcnt lgkmcnt(8)
	s_barrier
	s_waitcnt lgkmcnt(0)
	v_mfma_f32_16x16x32_bf16 v[158:161], v[70:73], v[138:141], v[158:161]
	v_mfma_f32_16x16x32_bf16 v[150:153], v[82:85], v[138:141], v[150:153]
	v_mfma_f32_16x16x32_bf16 v[126:129], v[70:73], v[146:149], v[126:129]
	v_mfma_f32_16x16x32_bf16 v[122:125], v[82:85], v[146:149], v[122:125]
	v_mfma_f32_16x16x32_bf16 v[110:113], v[70:73], v[162:165], v[110:113]
	v_mfma_f32_16x16x32_bf16 v[106:109], v[82:85], v[162:165], v[106:109]
	v_mfma_f32_16x16x32_bf16 v[94:97], v[70:73], v[170:173], v[94:97]
	v_mfma_f32_16x16x32_bf16 v[90:93], v[82:85], v[170:173], v[90:93]
	v_mfma_f32_16x16x32_bf16 v[158:161], v[74:77], v[142:145], v[158:161]
	v_mfma_f32_16x16x32_bf16 v[150:153], v[86:89], v[142:145], v[150:153]
	v_mfma_f32_16x16x32_bf16 v[126:129], v[74:77], v[154:157], v[126:129]
	v_mfma_f32_16x16x32_bf16 v[122:125], v[86:89], v[154:157], v[122:125]
	v_mfma_f32_16x16x32_bf16 v[110:113], v[74:77], v[166:169], v[110:113]
	v_mfma_f32_16x16x32_bf16 v[106:109], v[86:89], v[166:169], v[106:109]
	v_mfma_f32_16x16x32_bf16 v[94:97], v[74:77], v[184:187], v[94:97]
	s_barrier
	v_mfma_f32_16x16x32_bf16 v[90:93], v[86:89], v[184:187], v[90:93]
	s_add_i32 s52, 0, 0x1c000
	s_add_i32 s53, s59, s9
	v_add_u32_e32 v195, s52, v192
	v_lshl_add_u64 v[228:229], v[228:229], 0, s[76:77]
	s_mov_b32 m0, s53
	ds_read_b128 v[188:191], v195
	ds_read_b128 v[196:199], v195 offset:1024
	ds_read_b128 v[220:223], v195 offset:2048
	ds_read_b128 v[224:227], v195 offset:3072
	global_load_lds_dwordx4 v[228:229], off
	v_lshl_add_u64 v[228:229], v[230:231], 0, s[76:77]
	s_add_i32 m0, s53, 0x2000
	s_nop 0
	global_load_lds_dwordx4 v[228:229], off
	s_barrier
; #define PG8_STAGE(bufoff, gbase, voff) do { _Pragma("unroll") for (int _i = 0; _i < 2; ++_i) \
;         __builtin_amdgcn_global_load_lds((const unsigned*)((const char*)(gbase) + (voff)[_i]), (LAS unsigned*)(lds + (bufoff) + ldsw + _i * 8192), 16, 0, 0); } while (0)
; #define PG8_LDA(dst, b, h) do { _Pragma("unroll") for (int m = 0; m < 4; ++m) _Pragma("unroll") for (int k = 0; k < 2; ++k) dst[m][k] = *(const LAS bf16x8*)(lds + PG8_SA(b, h) + aoff + m * 2048 + k * 1024); } while (0)
; #define PG8_LDB(dst, b, h) do { _Pragma("unroll") for (int n = 0; n < 2; ++n) _Pragma("unroll") for (int k = 0; k < 2; ++k) dst[n][k] = *(const LAS bf16x8*)(lds + PG8_SB(b, h) + boff + n * 2048 + k * 1024); } while (0)
; #define PG8_WAIT_V(n) asm volatile("s_waitcnt vmcnt(" #n ")" ::: "memory")
; #define PG8_WAIT_L(n) asm volatile("s_waitcnt lgkmcnt(" #n ")" ::: "memory")
; #define PG8_BAR __builtin_amdgcn_s_barrier()
; #define PG8_SCHED __builtin_amdgcn_sched_barrier(0)
;     template <int mode> __device__ __forceinline__ void run(const f32x4 (&acc)[2][2][4][2], const Unit& u, int wr, int wc, int fr, int fq, const LAS float* sc) const {
;     ...
;             const int col0 = u.pn * BM + wc * 32 + 8 * fq;
;             float sA = 1.f, sB = 1.f;
;             if (mode == 4) scales2(u, wr, fr, fq, sA, sB);
;             f32x4 bvv[4];
; #pragma unroll
;             for (int q = 0; q < 4; ++q) bvv[q] = (mode != 4 && bias) ? *(const f32x4*)(bias + col0 + (q >> 1) * HALF + (q & 1) * 4) : (f32x4){0.f, 0.f, 0.f, 0.f};
; template <int MODE, class EpiT, class Sched>
; __device__ __forceinline__ void gemm_phase(LAS unsigned char* lds, const Gemm g, const Sched& S, const EpiT& E) {
;     ...
;             PG8_WAIT_V(6); PG8_BAR; PG8_MMA(1, 1, At, B1); PG8_BAR;
;             PG8_LDB(B0, 1, 0); PG8_SCHED; PG8_LDA(At, 1, 0); PG8_STAGE(PG8_SA(0, 1), a2 + hstep, voffA);
;             PG8_WAIT_L(8); PG8_BAR; PG8_WAIT_L(0); PG8_MMA(0, 0, At, B0); PG8_BAR; PG8_SCHED;
;             PG8_LDB(B1, 1, 1); PG8_STAGE(PG8_SB(1, 0), b3, voffB);
;             PG8_BAR; PG8_WAIT_L(0); PG8_MMA(0, 1, At, B1); PG8_BAR;
;             PG8_LDA(At, 1, 1); PG8_STAGE(PG8_SA(1, 0), a3, voffA);
;             PG8_BAR; PG8_WAIT_L(0); PG8_MMA(1, 0, At, B0); PG8_BAR; PG8_SCHED;
;             PG8_STAGE(PG8_SB(1, 1), b3 + hstep, voffB);
;             PG8_WAIT_V(6); PG8_BAR; PG8_MMA(1, 1, At, B1); PG8_BAR;
	s_waitcnt lgkmcnt(0)
	v_mfma_f32_16x16x32_bf16 v[134:137], v[188:191], v[138:141], v[134:137]
	v_mfma_f32_16x16x32_bf16 v[130:133], v[220:223], v[138:141], v[130:133]
	v_mfma_f32_16x16x32_bf16 v[118:121], v[188:191], v[146:149], v[118:121]
	v_mfma_f32_16x16x32_bf16 v[114:117], v[220:223], v[146:149], v[114:117]
	v_mfma_f32_16x16x32_bf16 v[102:105], v[188:191], v[162:165], v[102:105]
	v_mfma_f32_16x16x32_bf16 v[98:101], v[220:223], v[162:165], v[98:101]
	v_mfma_f32_16x16x32_bf16 v[78:81], v[188:191], v[170:173], v[78:81]
	v_mfma_f32_16x16x32_bf16 v[66:69], v[220:223], v[170:173], v[66:69]
	v_mfma_f32_16x16x32_bf16 v[134:137], v[196:199], v[142:145], v[134:137]
	v_mfma_f32_16x16x32_bf16 v[130:133], v[224:227], v[142:145], v[130:133]
	v_mfma_f32_16x16x32_bf16 v[118:121], v[196:199], v[154:157], v[118:121]
	v_mfma_f32_16x16x32_bf16 v[114:117], v[224:227], v[154:157], v[114:117]
	v_mfma_f32_16x16x32_bf16 v[102:105], v[196:199], v[166:169], v[102:105]
	v_mfma_f32_16x16x32_bf16 v[98:101], v[224:227], v[166:169], v[98:101]
	v_mfma_f32_16x16x32_bf16 v[78:81], v[196:199], v[184:187], v[78:81]
	s_barrier
	v_mfma_f32_16x16x32_bf16 v[66:69], v[224:227], v[184:187], v[66:69]
	s_mov_b32 m0, s51
	v_lshl_add_u64 v[228:229], v[232:233], 0, s[76:77]
	ds_read_b128 v[138:141], v194 offset:49152
	ds_read_b128 v[142:145], v194 offset:50176
	ds_read_b128 v[146:149], v194 offset:51200
	ds_read_b128 v[154:157], v194 offset:52224
	ds_read_b128 v[162:165], v194 offset:53248
	ds_read_b128 v[166:169], v194 offset:54272
	ds_read_b128 v[170:173], v194 offset:55296
	ds_read_b128 v[184:187], v194 offset:56320
	global_load_lds_dwordx4 v[228:229], off
	v_lshl_add_u64 v[228:229], v[234:235], 0, s[76:77]
	s_mov_b32 m0, s56
	s_nop 0
	global_load_lds_dwordx4 v[228:229], off
	s_barrier
	s_waitcnt lgkmcnt(0)
	v_mfma_f32_16x16x32_bf16 v[62:65], v[70:73], v[138:141], v[62:65]
	v_mfma_f32_16x16x32_bf16 v[58:61], v[82:85], v[138:141], v[58:61]
	v_mfma_f32_16x16x32_bf16 v[46:49], v[70:73], v[146:149], v[46:49]
	v_mfma_f32_16x16x32_bf16 v[42:45], v[82:85], v[146:149], v[42:45]
	v_mfma_f32_16x16x32_bf16 v[30:33], v[70:73], v[162:165], v[30:33]
	v_mfma_f32_16x16x32_bf16 v[26:29], v[82:85], v[162:165], v[26:29]
	v_mfma_f32_16x16x32_bf16 v[14:17], v[70:73], v[170:173], v[14:17]
	v_mfma_f32_16x16x32_bf16 v[10:13], v[82:85], v[170:173], v[10:13]
	v_mfma_f32_16x16x32_bf16 v[62:65], v[74:77], v[142:145], v[62:65]
	v_mfma_f32_16x16x32_bf16 v[58:61], v[86:89], v[142:145], v[58:61]
	v_mfma_f32_16x16x32_bf16 v[46:49], v[74:77], v[154:157], v[46:49]
	v_mfma_f32_16x16x32_bf16 v[42:45], v[86:89], v[154:157], v[42:45]
	v_mfma_f32_16x16x32_bf16 v[30:33], v[74:77], v[166:169], v[30:33]
	v_mfma_f32_16x16x32_bf16 v[26:29], v[86:89], v[166:169], v[26:29]
	v_mfma_f32_16x16x32_bf16 v[14:17], v[74:77], v[184:187], v[14:17]
	s_barrier
	v_mfma_f32_16x16x32_bf16 v[10:13], v[86:89], v[184:187], v[10:13]
	s_add_i32 s52, s52, s9
	v_lshl_add_u64 v[70:71], v[236:237], 0, s[76:77]
	s_mov_b32 m0, s52
	s_nop 0
	global_load_lds_dwordx4 v[70:71], off
	v_lshl_add_u64 v[70:71], v[238:239], 0, s[76:77]
	s_add_i32 m0, s52, 0x2000
	s_nop 0
	global_load_lds_dwordx4 v[70:71], off
	s_waitcnt vmcnt(6)
	s_barrier
	v_mfma_f32_16x16x32_bf16 v[54:57], v[188:191], v[138:141], v[54:57]
	v_mfma_f32_16x16x32_bf16 v[50:53], v[220:223], v[138:141], v[50:53]
	v_mfma_f32_16x16x32_bf16 v[38:41], v[188:191], v[146:149], v[38:41]
	v_mfma_f32_16x16x32_bf16 v[34:37], v[220:223], v[146:149], v[34:37]
	v_mfma_f32_16x16x32_bf16 v[22:25], v[188:191], v[162:165], v[22:25]
	v_mfma_f32_16x16x32_bf16 v[18:21], v[220:223], v[162:165], v[18:21]
	v_mfma_f32_16x16x32_bf16 v[6:9], v[188:191], v[170:173], v[6:9]
	v_mfma_f32_16x16x32_bf16 v[2:5], v[220:223], v[170:173], v[2:5]
	v_mfma_f32_16x16x32_bf16 v[54:57], v[196:199], v[142:145], v[54:57]
	v_mfma_f32_16x16x32_bf16 v[50:53], v[224:227], v[142:145], v[50:53]
	v_mfma_f32_16x16x32_bf16 v[38:41], v[196:199], v[154:157], v[38:41]
	v_mfma_f32_16x16x32_bf16 v[34:37], v[224:227], v[154:157], v[34:37]
	v_mfma_f32_16x16x32_bf16 v[22:25], v[196:199], v[166:169], v[22:25]
	v_mfma_f32_16x16x32_bf16 v[18:21], v[224:227], v[166:169], v[18:21]
	v_mfma_f32_16x16x32_bf16 v[6:9], v[196:199], v[184:187], v[6:9]
	s_barrier
	v_mfma_f32_16x16x32_bf16 v[2:5], v[224:227], v[184:187], v[2:5]
	s_add_u32 s44, s44, 0x100
	s_addc_u32 s45, s45, 0
	s_add_u32 vcc_lo, vcc_lo, 0x100
	s_addc_u32 vcc_hi, vcc_hi, 0
	s_cmp_ge_u32 s58, s50
	s_mov_b32 s52, s58
	s_cbranch_scc0 .LBB0_115
	v_lshl_or_b32 v184, s24, 8, v193
	v_ashrrev_i32_e32 v185, 31, v184
	v_mov_b32_e32 v74, 0
	v_cndmask_b32_e64 v70, 0, 1, s[68:69]
	v_lshl_add_u64 v[138:139], v[184:185], 2, s[12:13]
	v_cmp_ne_u32_e64 s[44:45], 1, v70
	s_andn2_b64 vcc, exec, s[68:69]
	v_mov_b32_e32 v86, 0
	v_mov_b32_e32 v87, v74
	v_mov_b32_e32 v186, 0
	v_mov_b32_e32 v187, v74
	s_cbranch_vccnz .LBB0_118
	global_load_dwordx4 v[86:89], v[138:139], off
	s_waitcnt vmcnt(0)
	v_mov_b32_e32 v186, v88
	v_mov_b32_e32 v187, v89

; #define PG8_STAGE(bufoff, gbase, voff) do { _Pragma("unroll") for (int _i = 0; _i < 2; ++_i) \
;         __builtin_amdgcn_global_load_lds((const unsigned*)((const char*)(gbase) + (voff)[_i]), (LAS unsigned*)(lds + (bufoff) + ldsw + _i * 8192), 16, 0, 0); } while (0)
; #define PG8_LDA(dst, b, h) do { _Pragma("unroll") for (int m = 0; m < 4; ++m) _Pragma("unroll") for (int k = 0; k < 2; ++k) dst[m][k] = *(const LAS bf16x8*)(lds + PG8_SA(b, h) + aoff + m * 2048 + k * 1024); } while (0)
; #define PG8_LDB(dst, b, h) do { _Pragma("unroll") for (int n = 0; n < 2; ++n) _Pragma("unroll") for (int k = 0; k < 2; ++k) dst[n][k] = *(const LAS bf16x8*)(lds + PG8_SB(b, h) + boff + n * 2048 + k * 1024); } while (0)
; #define PG8_WAIT_V(n) asm volatile("s_waitcnt vmcnt(" #n ")" ::: "memory")
; #define PG8_WAIT_L(n) asm volatile("s_waitcnt lgkmcnt(" #n ")" ::: "memory")
; #define PG8_BAR __builtin_amdgcn_s_barrier()
; #define PG8_SCHED __builtin_amdgcn_sched_barrier(0)
; template <int MODE, class EpiT, class Sched>
; __device__ __forceinline__ void gemm_phase(LAS unsigned char* lds, const Gemm g, const Sched& S, const EpiT& E) {
;     ...
;             PG8_LDB(B0, 0, 0); PG8_SCHED; PG8_LDA(At, 0, 0); PG8_STAGE(PG8_SA(1, 1), a1 + hstep, voffA);
;             PG8_WAIT_L(8); PG8_BAR; PG8_WAIT_L(0); PG8_MMA(0, 0, At, B0); PG8_BAR; PG8_SCHED;
;             PG8_LDB(B1, 0, 1); PG8_STAGE(PG8_SB(0, 0), b2, voffB);
;             PG8_BAR; PG8_WAIT_L(0); PG8_MMA(0, 1, At, B1); PG8_BAR;
;             PG8_LDA(At, 0, 1); PG8_STAGE(PG8_SA(0, 0), a2, voffA);
;             PG8_BAR; PG8_WAIT_L(0); PG8_MMA(1, 0, At, B0); PG8_BAR; PG8_SCHED;
;             PG8_STAGE(PG8_SB(0, 1), b2 + hstep, voffB);
;             PG8_WAIT_V(6); PG8_BAR; PG8_MMA(1, 1, At, B1); PG8_BAR;
;             PG8_LDB(B0, 1, 0); PG8_SCHED; PG8_LDA(At, 1, 0); PG8_STAGE(PG8_SA(0, 1), a2 + hstep, voffA);
;             PG8_WAIT_L(8); PG8_BAR; PG8_WAIT_L(0); PG8_MMA(0, 0, At, B0); PG8_BAR; PG8_SCHED;
;             PG8_LDB(B1, 1, 1); PG8_STAGE(PG8_SB(1, 0), b3, voffB);
;             PG8_BAR; PG8_WAIT_L(0); PG8_MMA(0, 1, At, B1); PG8_BAR;
;             PG8_LDA(At, 1, 1); PG8_STAGE(PG8_SA(1, 0), a3, voffA);
;             PG8_BAR; PG8_WAIT_L(0); PG8_MMA(1, 0, At, B0); PG8_BAR; PG8_SCHED;
;             PG8_STAGE(PG8_SB(1, 1), b3 + hstep, voffB);
;             PG8_WAIT_V(6); PG8_BAR; PG8_MMA(1, 1, At, B1); PG8_BAR;
.LBB0_159:
	s_add_i32 s89, s30, 2
	s_add_u32 s44, s4, 0x80
	s_addc_u32 s45, s5, 0
	s_add_i32 s58, 0, 0x10000
	v_add_u32_e32 v142, s58, v220
	ds_read_b128 v[130:133], v142
	ds_read_b128 v[134:137], v142 offset:1024
	ds_read_b128 v[138:141], v142 offset:2048
	ds_read_b128 v[142:145], v142 offset:3072
	s_cmp_eq_u32 s61, s30
	s_cselect_b32 s45, s79, s45
	s_cselect_b32 s44, s78, s44
	s_cselect_b32 s53, s47, s24
	s_cselect_b32 s52, s46, s23
	v_lshl_add_u64 v[188:189], s[4:5], 0, v[184:185]
	s_add_i32 m0, s69, 0xc000
	ds_read_b128 v[146:149], v223
	ds_read_b128 v[150:153], v223 offset:1024
	ds_read_b128 v[154:157], v223 offset:2048
	ds_read_b128 v[158:161], v223 offset:3072
	ds_read_b128 v[162:165], v223 offset:4096
	ds_read_b128 v[166:169], v223 offset:5120
	ds_read_b128 v[170:173], v223 offset:6144
	ds_read_b128 v[174:177], v223 offset:7168
	global_load_lds_dwordx4 v[188:189], off
	v_lshl_add_u64 v[188:189], s[4:5], 0, v[186:187]
	s_add_i32 m0, s69, 0xe000
	s_nop 0
	global_load_lds_dwordx4 v[188:189], off
	s_waitcnt lgkmcnt(8)
	s_barrier
	s_waitcnt lgkmcnt(0)
	v_mfma_f32_16x16x32_bf16 v[126:129], v[130:133], v[146:149], v[126:129]
	v_mfma_f32_16x16x32_bf16 v[122:125], v[138:141], v[146:149], v[122:125]
	v_mfma_f32_16x16x32_bf16 v[110:113], v[130:133], v[154:157], v[110:113]
	v_mfma_f32_16x16x32_bf16 v[106:109], v[138:141], v[154:157], v[106:109]
	v_mfma_f32_16x16x32_bf16 v[94:97], v[130:133], v[162:165], v[94:97]
	v_mfma_f32_16x16x32_bf16 v[90:93], v[138:141], v[162:165], v[90:93]
	v_mfma_f32_16x16x32_bf16 v[78:81], v[130:133], v[170:173], v[78:81]
	v_mfma_f32_16x16x32_bf16 v[74:77], v[138:141], v[170:173], v[74:77]
	v_mfma_f32_16x16x32_bf16 v[126:129], v[134:137], v[150:153], v[126:129]
	v_mfma_f32_16x16x32_bf16 v[122:125], v[142:145], v[150:153], v[122:125]
	v_mfma_f32_16x16x32_bf16 v[110:113], v[134:137], v[158:161], v[110:113]
	v_mfma_f32_16x16x32_bf16 v[106:109], v[142:145], v[158:161], v[106:109]
	v_mfma_f32_16x16x32_bf16 v[94:97], v[134:137], v[166:169], v[94:97]
	v_mfma_f32_16x16x32_bf16 v[90:93], v[142:145], v[166:169], v[90:93]
	v_mfma_f32_16x16x32_bf16 v[78:81], v[134:137], v[174:177], v[78:81]
	s_barrier
	v_mfma_f32_16x16x32_bf16 v[74:77], v[142:145], v[174:177], v[74:77]
	s_add_i32 s30, 0, 0x14000
	s_add_i32 s58, s58, s68
	v_add_u32_e32 v200, s30, v220
	v_lshl_add_u64 v[228:229], s[52:53], 0, v[0:1]
	s_mov_b32 m0, s58
	ds_read_b128 v[188:191], v200
	ds_read_b128 v[192:195], v200 offset:1024
	ds_read_b128 v[196:199], v200 offset:2048
	ds_read_b128 v[224:227], v200 offset:3072
	global_load_lds_dwordx4 v[228:229], off
	v_lshl_add_u64 v[230:231], s[52:53], 0, v[182:183]
	s_add_i32 m0, s58, 0x2000
	s_nop 0
	global_load_lds_dwordx4 v[230:231], off
	s_barrier
	s_waitcnt lgkmcnt(0)
	v_mfma_f32_16x16x32_bf16 v[118:121], v[188:191], v[146:149], v[118:121]
	v_mfma_f32_16x16x32_bf16 v[114:117], v[196:199], v[146:149], v[114:117]
	v_mfma_f32_16x16x32_bf16 v[102:105], v[188:191], v[154:157], v[102:105]
	v_mfma_f32_16x16x32_bf16 v[98:101], v[196:199], v[154:157], v[98:101]
	v_mfma_f32_16x16x32_bf16 v[86:89], v[188:191], v[162:165], v[86:89]
	v_mfma_f32_16x16x32_bf16 v[82:85], v[196:199], v[162:165], v[82:85]
	v_mfma_f32_16x16x32_bf16 v[70:73], v[188:191], v[170:173], v[70:73]
	v_mfma_f32_16x16x32_bf16 v[66:69], v[196:199], v[170:173], v[66:69]
	v_mfma_f32_16x16x32_bf16 v[118:121], v[192:195], v[150:153], v[118:121]
	v_mfma_f32_16x16x32_bf16 v[114:117], v[224:227], v[150:153], v[114:117]
	v_mfma_f32_16x16x32_bf16 v[102:105], v[192:195], v[158:161], v[102:105]
	v_mfma_f32_16x16x32_bf16 v[98:101], v[224:227], v[158:161], v[98:101]
	v_mfma_f32_16x16x32_bf16 v[86:89], v[192:195], v[166:169], v[86:89]
	v_mfma_f32_16x16x32_bf16 v[82:85], v[224:227], v[166:169], v[82:85]
	v_mfma_f32_16x16x32_bf16 v[70:73], v[192:195], v[174:177], v[70:73]
	s_barrier
	v_mfma_f32_16x16x32_bf16 v[66:69], v[224:227], v[174:177], v[66:69]
	s_mov_b32 m0, s69
	v_lshl_add_u64 v[232:233], s[44:45], 0, v[0:1]
	ds_read_b128 v[146:149], v223 offset:16384
	ds_read_b128 v[150:153], v223 offset:17408
	ds_read_b128 v[154:157], v223 offset:18432
	ds_read_b128 v[158:161], v223 offset:19456
	ds_read_b128 v[162:165], v223 offset:20480
	ds_read_b128 v[166:169], v223 offset:21504
	ds_read_b128 v[170:173], v223 offset:22528
	ds_read_b128 v[174:177], v223 offset:23552
	global_load_lds_dwordx4 v[232:233], off
	v_lshl_add_u64 v[234:235], s[44:45], 0, v[182:183]
	s_mov_b32 m0, s74
	s_nop 0
	global_load_lds_dwordx4 v[234:235], off
	s_barrier
	s_waitcnt lgkmcnt(0)
	v_mfma_f32_16x16x32_bf16 v[62:65], v[130:133], v[146:149], v[62:65]
	v_mfma_f32_16x16x32_bf16 v[58:61], v[138:141], v[146:149], v[58:61]
	v_mfma_f32_16x16x32_bf16 v[46:49], v[130:133], v[154:157], v[46:49]
	v_mfma_f32_16x16x32_bf16 v[42:45], v[138:141], v[154:157], v[42:45]
	v_mfma_f32_16x16x32_bf16 v[30:33], v[130:133], v[162:165], v[30:33]
	v_mfma_f32_16x16x32_bf16 v[26:29], v[138:141], v[162:165], v[26:29]
	v_mfma_f32_16x16x32_bf16 v[14:17], v[130:133], v[170:173], v[14:17]
	v_mfma_f32_16x16x32_bf16 v[10:13], v[138:141], v[170:173], v[10:13]
	v_mfma_f32_16x16x32_bf16 v[62:65], v[134:137], v[150:153], v[62:65]
	v_mfma_f32_16x16x32_bf16 v[58:61], v[142:145], v[150:153], v[58:61]
	v_mfma_f32_16x16x32_bf16 v[46:49], v[134:137], v[158:161], v[46:49]
	v_mfma_f32_16x16x32_bf16 v[42:45], v[142:145], v[158:161], v[42:45]
	v_mfma_f32_16x16x32_bf16 v[30:33], v[134:137], v[166:169], v[30:33]
	v_mfma_f32_16x16x32_bf16 v[26:29], v[142:145], v[166:169], v[26:29]
	v_mfma_f32_16x16x32_bf16 v[14:17], v[134:137], v[174:177], v[14:17]
	s_barrier
; #define PG8_STAGE(bufoff, gbase, voff) do { _Pragma("unroll") for (int _i = 0; _i < 2; ++_i) \
;         __builtin_amdgcn_global_load_lds((const unsigned*)((const char*)(gbase) + (voff)[_i]), (LAS unsigned*)(lds + (bufoff) + ldsw + _i * 8192), 16, 0, 0); } while (0)
; #define PG8_LDA(dst, b, h) do { _Pragma("unroll") for (int m = 0; m < 4; ++m) _Pragma("unroll") for (int k = 0; k < 2; ++k) dst[m][k] = *(const LAS bf16x8*)(lds + PG8_SA(b, h) + aoff + m * 2048 + k * 1024); } while (0)
; #define PG8_LDB(dst, b, h) do { _Pragma("unroll") for (int n = 0; n < 2; ++n) _Pragma("unroll") for (int k = 0; k < 2; ++k) dst[n][k] = *(const LAS bf16x8*)(lds + PG8_SB(b, h) + boff + n * 2048 + k * 1024); } while (0)
; #define PG8_WAIT_V(n) asm volatile("s_waitcnt vmcnt(" #n ")" ::: "memory")
; #define PG8_WAIT_L(n) asm volatile("s_waitcnt lgkmcnt(" #n ")" ::: "memory")
; #define PG8_BAR __builtin_amdgcn_s_barrier()
; #define PG8_SCHED __builtin_amdgcn_sched_barrier(0)
; template <int MODE, class EpiT, class Sched>
; __device__ __forceinline__ void gemm_phase(LAS unsigned char* lds, const Gemm g, const Sched& S, const EpiT& E) {
;     ...
;             PG8_LDB(B0, 0, 0); PG8_SCHED; PG8_LDA(At, 0, 0); PG8_STAGE(PG8_SA(1, 1), a1 + hstep, voffA);
;             PG8_WAIT_L(8); PG8_BAR; PG8_WAIT_L(0); PG8_MMA(0, 0, At, B0); PG8_BAR; PG8_SCHED;
;             PG8_LDB(B1, 0, 1); PG8_STAGE(PG8_SB(0, 0), b2, voffB);
;             PG8_BAR; PG8_WAIT_L(0); PG8_MMA(0, 1, At, B1); PG8_BAR;
;             PG8_LDA(At, 0, 1); PG8_STAGE(PG8_SA(0, 0), a2, voffA);
;             PG8_BAR; PG8_WAIT_L(0); PG8_MMA(1, 0, At, B0); PG8_BAR; PG8_SCHED;
;             PG8_STAGE(PG8_SB(0, 1), b2 + hstep, voffB);
;             PG8_WAIT_V(6); PG8_BAR; PG8_MMA(1, 1, At, B1); PG8_BAR;
;             PG8_LDB(B0, 1, 0); PG8_SCHED; PG8_LDA(At, 1, 0); PG8_STAGE(PG8_SA(0, 1), a2 + hstep, voffA);
;             PG8_WAIT_L(8); PG8_BAR; PG8_WAIT_L(0); PG8_MMA(0, 0, At, B0); PG8_BAR; PG8_SCHED;
;             PG8_LDB(B1, 1, 1); PG8_STAGE(PG8_SB(1, 0), b3, voffB);
;             PG8_BAR; PG8_WAIT_L(0); PG8_MMA(0, 1, At, B1); PG8_BAR;
;             PG8_LDA(At, 1, 1); PG8_STAGE(PG8_SA(1, 0), a3, voffA);
;             PG8_BAR; PG8_WAIT_L(0); PG8_MMA(1, 0, At, B0); PG8_BAR; PG8_SCHED;
;             PG8_STAGE(PG8_SB(1, 1), b3 + hstep, voffB);
;             PG8_WAIT_V(6); PG8_BAR; PG8_MMA(1, 1, At, B1); PG8_BAR;
	v_mfma_f32_16x16x32_bf16 v[10:13], v[142:145], v[174:177], v[10:13]
	s_add_u32 s52, s52, s38
	s_addc_u32 s53, s53, 0
	s_add_i32 s30, s30, s68
	v_lshl_add_u64 v[236:237], s[52:53], 0, v[0:1]
	s_mov_b32 m0, s30
	v_lshl_add_u64 v[238:239], s[52:53], 0, v[182:183]
	global_load_lds_dwordx4 v[236:237], off
	s_add_i32 m0, s30, 0x2000
	s_nop 0
	global_load_lds_dwordx4 v[238:239], off
	s_waitcnt vmcnt(6)
	s_barrier
	v_mfma_f32_16x16x32_bf16 v[54:57], v[188:191], v[146:149], v[54:57]
	v_mfma_f32_16x16x32_bf16 v[50:53], v[196:199], v[146:149], v[50:53]
	v_mfma_f32_16x16x32_bf16 v[38:41], v[188:191], v[154:157], v[38:41]
	v_mfma_f32_16x16x32_bf16 v[34:37], v[196:199], v[154:157], v[34:37]
	v_mfma_f32_16x16x32_bf16 v[22:25], v[188:191], v[162:165], v[22:25]
	v_mfma_f32_16x16x32_bf16 v[18:21], v[196:199], v[162:165], v[18:21]
	v_mfma_f32_16x16x32_bf16 v[6:9], v[188:191], v[170:173], v[6:9]
	v_mfma_f32_16x16x32_bf16 v[2:5], v[196:199], v[170:173], v[2:5]
	v_mfma_f32_16x16x32_bf16 v[54:57], v[192:195], v[150:153], v[54:57]
	v_mfma_f32_16x16x32_bf16 v[50:53], v[224:227], v[150:153], v[50:53]
	v_mfma_f32_16x16x32_bf16 v[38:41], v[192:195], v[158:161], v[38:41]
	v_mfma_f32_16x16x32_bf16 v[34:37], v[224:227], v[158:161], v[34:37]
	v_mfma_f32_16x16x32_bf16 v[22:25], v[192:195], v[166:169], v[22:25]
	v_mfma_f32_16x16x32_bf16 v[18:21], v[224:227], v[166:169], v[18:21]
	v_mfma_f32_16x16x32_bf16 v[6:9], v[192:195], v[174:177], v[6:9]
	s_barrier
	v_mfma_f32_16x16x32_bf16 v[2:5], v[224:227], v[174:177], v[2:5]
	s_add_i32 s30, 0, 0x18000
	v_add_u32_e32 v142, s30, v220
	ds_read_b128 v[130:133], v142
	ds_read_b128 v[134:137], v142 offset:1024
	ds_read_b128 v[138:141], v142 offset:2048
	ds_read_b128 v[142:145], v142 offset:3072
	s_add_u32 s44, s44, s38
	s_addc_u32 s45, s45, 0
	s_mov_b32 m0, s75
	v_lshl_add_u64 v[188:189], s[44:45], 0, v[0:1]
	ds_read_b128 v[146:149], v223 offset:32768
	ds_read_b128 v[150:153], v223 offset:33792
	ds_read_b128 v[154:157], v223 offset:34816
	ds_read_b128 v[158:161], v223 offset:35840
	ds_read_b128 v[162:165], v223 offset:36864
	ds_read_b128 v[166:169], v223 offset:37888
	ds_read_b128 v[170:173], v223 offset:38912
	ds_read_b128 v[174:177], v223 offset:39936
	global_load_lds_dwordx4 v[188:189], off
	v_lshl_add_u64 v[188:189], s[44:45], 0, v[182:183]
	s_mov_b32 m0, s9
	s_nop 0
	global_load_lds_dwordx4 v[188:189], off
	s_waitcnt lgkmcnt(8)
	s_barrier
	s_waitcnt lgkmcnt(0)
	v_mfma_f32_16x16x32_bf16 v[126:129], v[130:133], v[146:149], v[126:129]
	v_mfma_f32_16x16x32_bf16 v[122:125], v[138:141], v[146:149], v[122:125]
	v_mfma_f32_16x16x32_bf16 v[110:113], v[130:133], v[154:157], v[110:113]
	v_mfma_f32_16x16x32_bf16 v[106:109], v[138:141], v[154:157], v[106:109]
	v_mfma_f32_16x16x32_bf16 v[94:97], v[130:133], v[162:165], v[94:97]
	v_mfma_f32_16x16x32_bf16 v[90:93], v[138:141], v[162:165], v[90:93]
	v_mfma_f32_16x16x32_bf16 v[78:81], v[130:133], v[170:173], v[78:81]
	v_mfma_f32_16x16x32_bf16 v[74:77], v[138:141], v[170:173], v[74:77]
	v_mfma_f32_16x16x32_bf16 v[126:129], v[134:137], v[150:153], v[126:129]
	v_mfma_f32_16x16x32_bf16 v[122:125], v[142:145], v[150:153], v[122:125]
	v_mfma_f32_16x16x32_bf16 v[110:113], v[134:137], v[158:161], v[110:113]
	v_mfma_f32_16x16x32_bf16 v[106:109], v[142:145], v[158:161], v[106:109]
	v_mfma_f32_16x16x32_bf16 v[94:97], v[134:137], v[166:169], v[94:97]
	v_mfma_f32_16x16x32_bf16 v[90:93], v[142:145], v[166:169], v[90:93]
	v_mfma_f32_16x16x32_bf16 v[78:81], v[134:137], v[174:177], v[78:81]
	s_barrier
	v_mfma_f32_16x16x32_bf16 v[74:77], v[142:145], v[174:177], v[74:77]
	s_add_i32 s44, 0, 0x1c000
	s_add_i32 s30, s30, s68
	v_add_u32_e32 v200, s44, v220
	v_lshl_add_u64 v[228:229], v[228:229], 0, s[76:77]
	s_mov_b32 m0, s30
	ds_read_b128 v[188:191], v200
	ds_read_b128 v[192:195], v200 offset:1024
	ds_read_b128 v[196:199], v200 offset:2048
	ds_read_b128 v[224:227], v200 offset:3072
	global_load_lds_dwordx4 v[228:229], off
	v_lshl_add_u64 v[228:229], v[230:231], 0, s[76:77]
	s_add_i32 m0, s30, 0x2000
	s_nop 0
	global_load_lds_dwordx4 v[228:229], off
	s_barrier
	s_waitcnt lgkmcnt(0)
	v_mfma_f32_16x16x32_bf16 v[118:121], v[188:191], v[146:149], v[118:121]
	v_mfma_f32_16x16x32_bf16 v[114:117], v[196:199], v[146:149], v[114:117]
	v_mfma_f32_16x16x32_bf16 v[102:105], v[188:191], v[154:157], v[102:105]
	v_mfma_f32_16x16x32_bf16 v[98:101], v[196:199], v[154:157], v[98:101]
	v_mfma_f32_16x16x32_bf16 v[86:89], v[188:191], v[162:165], v[86:89]
	v_mfma_f32_16x16x32_bf16 v[82:85], v[196:199], v[162:165], v[82:85]
	v_mfma_f32_16x16x32_bf16 v[70:73], v[188:191], v[170:173], v[70:73]
	v_mfma_f32_16x16x32_bf16 v[66:69], v[196:199], v[170:173], v[66:69]
	v_mfma_f32_16x16x32_bf16 v[118:121], v[192:195], v[150:153], v[118:121]
	v_mfma_f32_16x16x32_bf16 v[114:117], v[224:227], v[150:153], v[114:117]
	v_mfma_f32_16x16x32_bf16 v[102:105], v[192:195], v[158:161], v[102:105]
	v_mfma_f32_16x16x32_bf16 v[98:101], v[224:227], v[158:161], v[98:101]
	v_mfma_f32_16x16x32_bf16 v[86:89], v[192:195], v[166:169], v[86:89]
	v_mfma_f32_16x16x32_bf16 v[82:85], v[224:227], v[166:169], v[82:85]
	v_mfma_f32_16x16x32_bf16 v[70:73], v[192:195], v[174:177], v[70:73]
	s_barrier
	v_mfma_f32_16x16x32_bf16 v[66:69], v[224:227], v[174:177], v[66:69]
	s_mov_b32 m0, s57
	v_lshl_add_u64 v[228:229], v[232:233], 0, s[76:77]
	ds_read_b128 v[146:149], v223 offset:49152
	ds_read_b128 v[150:153], v223 offset:50176
	ds_read_b128 v[154:157], v223 offset:51200
	ds_read_b128 v[158:161], v223 offset:52224
	ds_read_b128 v[162:165], v223 offset:53248
	ds_read_b128 v[166:169], v223 offset:54272
	ds_read_b128 v[170:173], v223 offset:55296
	ds_read_b128 v[174:177], v223 offset:56320
	global_load_lds_dwordx4 v[228:229], off
	v_lshl_add_u64 v[228:229], v[234:235], 0, s[76:77]
	s_mov_b32 m0, s60
	s_nop 0
	global_load_lds_dwordx4 v[228:229], off
	s_barrier
; #define PG8_STAGE(bufoff, gbase, voff) do { _Pragma("unroll") for (int _i = 0; _i < 2; ++_i) \
;         __builtin_amdgcn_global_load_lds((const unsigned*)((const char*)(gbase) + (voff)[_i]), (LAS unsigned*)(lds + (bufoff) + ldsw + _i * 8192), 16, 0, 0); } while (0)
; #define PG8_LDA(dst, b, h) do { _Pragma("unroll") for (int m = 0; m < 4; ++m) _Pragma("unroll") for (int k = 0; k < 2; ++k) dst[m][k] = *(const LAS bf16x8*)(lds + PG8_SA(b, h) + aoff + m * 2048 + k * 1024); } while (0)
; #define PG8_WAIT_V(n) asm volatile("s_waitcnt vmcnt(" #n ")" ::: "memory")
; #define PG8_BAR __builtin_amdgcn_s_barrier()
;     __device__ __forceinline__ void scales2(const Unit& u, int wr, int fr, int fq, float& sA, float& sB) const {
;         const int rowA = u.pm * BM + wr * 64 + fq * 16 + fr;
;         const f32x4* pa = (const f32x4*)(ssq_in + (size_t)rowA * 16); const f32x4* pb = (const f32x4*)(ssq_in + (size_t)(rowA + HALF) * 16);
;         const f32x4 a0 = pa[0], a1 = pa[1], a2 = pa[2], a3 = pa[3], b0 = pb[0], b1 = pb[1], b2 = pb[2], b3 = pb[3];
;         const float ta = (((a0[0] + a0[1]) + (a0[2] + a0[3])) + ((a1[0] + a1[1]) + (a1[2] + a1[3]))) + (((a2[0] + a2[1]) + (a2[2] + a2[3])) + ((a3[0] + a3[1]) + (a3[2] + a3[3])));
;         const float tb = (((b0[0] + b0[1]) + (b0[2] + b0[3])) + ((b1[0] + b1[1]) + (b1[2] + b1[3]))) + (((b2[0] + b2[1]) + (b2[2] + b2[3])) + ((b3[0] + b3[1]) + (b3[2] + b3[3])));
;         sA = rsqrtf(ta * (1.0f / 1024.0f) + EPS); sB = rsqrtf(tb * (1.0f / 1024.0f) + EPS);
;     }
; template <int MODE, class EpiT, class Sched>
; __device__ __forceinline__ void gemm_phase(LAS unsigned char* lds, const Gemm g, const Sched& S, const EpiT& E) {
;     ...
;             PG8_WAIT_V(6); PG8_BAR; PG8_MMA(1, 1, At, B1); PG8_BAR;
;             PG8_LDB(B0, 1, 0); PG8_SCHED; PG8_LDA(At, 1, 0); PG8_STAGE(PG8_SA(0, 1), a2 + hstep, voffA);
;             PG8_WAIT_L(8); PG8_BAR; PG8_WAIT_L(0); PG8_MMA(0, 0, At, B0); PG8_BAR; PG8_SCHED;
;             PG8_LDB(B1, 1, 1); PG8_STAGE(PG8_SB(1, 0), b3, voffB);
;             PG8_BAR; PG8_WAIT_L(0); PG8_MMA(0, 1, At, B1); PG8_BAR;
;             PG8_LDA(At, 1, 1); PG8_STAGE(PG8_SA(1, 0), a3, voffA);
;             PG8_BAR; PG8_WAIT_L(0); PG8_MMA(1, 0, At, B0); PG8_BAR; PG8_SCHED;
;             PG8_STAGE(PG8_SB(1, 1), b3 + hstep, voffB);
;             PG8_WAIT_V(6); PG8_BAR; PG8_MMA(1, 1, At, B1); PG8_BAR;
	s_waitcnt lgkmcnt(0)
	v_mfma_f32_16x16x32_bf16 v[62:65], v[130:133], v[146:149], v[62:65]
	v_mfma_f32_16x16x32_bf16 v[58:61], v[138:141], v[146:149], v[58:61]
	v_mfma_f32_16x16x32_bf16 v[46:49], v[130:133], v[154:157], v[46:49]
	v_mfma_f32_16x16x32_bf16 v[42:45], v[138:141], v[154:157], v[42:45]
	v_mfma_f32_16x16x32_bf16 v[30:33], v[130:133], v[162:165], v[30:33]
	v_mfma_f32_16x16x32_bf16 v[26:29], v[138:141], v[162:165], v[26:29]
	v_mfma_f32_16x16x32_bf16 v[14:17], v[130:133], v[170:173], v[14:17]
	v_mfma_f32_16x16x32_bf16 v[10:13], v[138:141], v[170:173], v[10:13]
	v_mfma_f32_16x16x32_bf16 v[62:65], v[134:137], v[150:153], v[62:65]
	v_mfma_f32_16x16x32_bf16 v[58:61], v[142:145], v[150:153], v[58:61]
	v_mfma_f32_16x16x32_bf16 v[46:49], v[134:137], v[158:161], v[46:49]
	v_mfma_f32_16x16x32_bf16 v[42:45], v[142:145], v[158:161], v[42:45]
	v_mfma_f32_16x16x32_bf16 v[30:33], v[134:137], v[166:169], v[30:33]
	v_mfma_f32_16x16x32_bf16 v[26:29], v[142:145], v[166:169], v[26:29]
	v_mfma_f32_16x16x32_bf16 v[14:17], v[134:137], v[174:177], v[14:17]
	s_barrier
	v_mfma_f32_16x16x32_bf16 v[10:13], v[142:145], v[174:177], v[10:13]
	s_add_i32 s30, s44, s68
	v_lshl_add_u64 v[130:131], v[236:237], 0, s[76:77]
	s_mov_b32 m0, s30
	s_nop 0
	global_load_lds_dwordx4 v[130:131], off
	v_lshl_add_u64 v[130:131], v[238:239], 0, s[76:77]
	s_add_i32 m0, s30, 0x2000
	s_nop 0
	global_load_lds_dwordx4 v[130:131], off
	s_waitcnt vmcnt(6)
	s_barrier
	v_mfma_f32_16x16x32_bf16 v[54:57], v[188:191], v[146:149], v[54:57]
	v_mfma_f32_16x16x32_bf16 v[50:53], v[196:199], v[146:149], v[50:53]
	v_mfma_f32_16x16x32_bf16 v[38:41], v[188:191], v[154:157], v[38:41]
	v_mfma_f32_16x16x32_bf16 v[34:37], v[196:199], v[154:157], v[34:37]
	v_mfma_f32_16x16x32_bf16 v[22:25], v[188:191], v[162:165], v[22:25]
	v_mfma_f32_16x16x32_bf16 v[18:21], v[196:199], v[162:165], v[18:21]
	v_mfma_f32_16x16x32_bf16 v[6:9], v[188:191], v[170:173], v[6:9]
	v_mfma_f32_16x16x32_bf16 v[2:5], v[196:199], v[170:173], v[2:5]
	v_mfma_f32_16x16x32_bf16 v[54:57], v[192:195], v[150:153], v[54:57]
	v_mfma_f32_16x16x32_bf16 v[50:53], v[224:227], v[150:153], v[50:53]
	v_mfma_f32_16x16x32_bf16 v[38:41], v[192:195], v[158:161], v[38:41]
	v_mfma_f32_16x16x32_bf16 v[34:37], v[224:227], v[158:161], v[34:37]
	v_mfma_f32_16x16x32_bf16 v[22:25], v[192:195], v[166:169], v[22:25]
	v_mfma_f32_16x16x32_bf16 v[18:21], v[224:227], v[166:169], v[18:21]
	v_mfma_f32_16x16x32_bf16 v[6:9], v[192:195], v[174:177], v[6:9]
	s_barrier
	v_mfma_f32_16x16x32_bf16 v[2:5], v[224:227], v[174:177], v[2:5]
	s_add_u32 s4, s4, 0x100
	s_addc_u32 s5, s5, 0
	s_add_u32 s23, s23, 0x100
	s_addc_u32 s24, s24, 0
	s_cmp_ge_u32 s89, s21
	s_mov_b32 s30, s89
	s_cbranch_scc0 .LBB0_159
	s_lshl_b32 s4, s22, 8
	s_add_i32 s4, s4, s56
	v_or_b32_e32 v130, s4, v222
	v_ashrrev_i32_e32 v131, 31, v130
	v_lshlrev_b64 v[130:131], 6, v[130:131]
	v_lshl_add_u64 v[146:147], s[66:67], 0, v[130:131]
	global_load_dwordx4 v[130:133], v[146:147], off offset:16
	global_load_dwordx4 v[134:137], v[146:147], off offset:48
	global_load_dwordx4 v[138:141], v[146:147], off
	global_load_dwordx4 v[142:145], v[146:147], off offset:32
	v_or_b32_e32 v192, s4, v181
	s_mov_b64 s[4:5], 0x2000
	v_lshl_add_u64 v[158:159], v[146:147], 0, s[4:5]
	v_add_co_u32_e32 v146, vcc, 0x2000, v146
	s_mov_b32 s4, 0x3a800000
	s_nop 0
	v_addc_co_u32_e32 v147, vcc, 0, v147, vcc
	global_load_dwordx4 v[146:149], v[146:147], off
	s_nop 0
	global_load_dwordx4 v[150:153], v[158:159], off offset:16
	global_load_dwordx4 v[154:157], v[158:159], off offset:48
	s_nop 0
	global_load_dwordx4 v[158:161], v[158:159], off offset:32
	v_lshl_or_b32 v188, s2, 8, v221
	v_ashrrev_i32_e32 v193, 31, v192
	v_ashrrev_i32_e32 v189, 31, v188
	v_or_b32_e32 v194, 16, v192
	v_ashrrev_i32_e32 v195, 31, v194
	s_waitcnt vmcnt(0)
	v_mov_b32_e32 v162, v138
	v_mov_b32_e32 v163, v142
	v_mov_b32_e32 v142, v139
	v_pk_add_f32 v[138:139], v[162:163], v[142:143]
	v_mov_b32_e32 v142, v140
	v_mov_b32_e32 v143, v144
	v_mov_b32_e32 v144, v141
	v_pk_add_f32 v[140:141], v[142:143], v[144:145]
	s_nop 0
	v_pk_add_f32 v[138:139], v[138:139], v[140:141]
	v_mov_b32_e32 v140, v130
	v_mov_b32_e32 v141, v134
	v_mov_b32_e32 v134, v131
	v_pk_add_f32 v[130:131], v[140:141], v[134:135]
	v_mov_b32_e32 v134, v132
	v_mov_b32_e32 v135, v136
	v_mov_b32_e32 v136, v133
	v_pk_add_f32 v[132:133], v[134:135], v[136:137]
	v_mov_b32_e32 v134, v148
	v_pk_add_f32 v[130:131], v[130:131], v[132:133]
	v_mov_b32_e32 v132, v146
	v_mov_b32_e32 v133, v158
	v_mov_b32_e32 v158, v147
	v_mov_b32_e32 v135, v160
	v_mov_b32_e32 v160, v149
	v_pk_add_f32 v[132:133], v[132:133], v[158:159]
	v_pk_add_f32 v[134:135], v[134:135], v[160:161]
	v_mov_b32_e32 v136, v152
	v_pk_add_f32 v[132:133], v[132:133], v[134:135]
	v_mov_b32_e32 v134, v150
	v_mov_b32_e32 v135, v154
	v_mov_b32_e32 v154, v151
	v_mov_b32_e32 v137, v156
	v_mov_b32_e32 v156, v153
	v_pk_add_f32 v[134:135], v[134:135], v[154:155]
	v_pk_add_f32 v[136:137], v[136:137], v[156:157]
	v_pk_add_f32 v[130:131], v[138:139], v[130:131]
	v_pk_add_f32 v[134:135], v[134:135], v[136:137]
	s_nop 0
	v_pk_add_f32 v[132:133], v[132:133], v[134:135]
	v_mov_b32_e32 v135, v130
	v_mov_b32_e32 v134, v132
	v_mov_b32_e32 v130, v133
	v_pk_add_f32 v[130:131], v[134:135], v[130:131]
	s_nop 0
	v_pk_fma_f32 v[190:191], v[130:131], s[4:5], v[178:179] op_sel_hi:[1,0,0]
	s_mov_b32 s4, 0x800000
	v_mul_f32_e32 v130, 0x4b800000, v191
	v_cmp_gt_f32_e64 s[44:45], s4, v191
	v_cmp_gt_f32_e32 vcc, s4, v190
	s_nop 0
	v_cndmask_b32_e64 v130, v191, v130, s[44:45]
	v_rsq_f32_e32 v130, v130
	s_nop 0
	v_mul_f32_e32 v131, 0x45800000, v130
	v_cndmask_b32_e64 v226, v130, v131, s[44:45]
	v_lshlrev_b64 v[130:131], 10, v[192:193]
	v_lshl_add_u64 v[130:131], v[130:131], 0, v[188:189]
	v_lshlrev_b64 v[198:199], 1, v[130:131]
	v_lshl_add_u64 v[130:131], s[34:35], 0, v[198:199]
	v_lshl_add_u64 v[132:133], s[92:93], 0, v[198:199]
	global_load_dwordx4 v[170:173], v[130:131], off
	global_load_dwordx4 v[174:177], v[132:133], off
	v_lshl_add_u64 v[134:135], s[6:7], 0, v[198:199]
	global_load_dwordx4 v[166:169], v[134:135], off
	global_load_dwordx4 v[158:161], v[130:131], off offset:256
	global_load_dwordx4 v[162:165], v[132:133], off offset:256
	global_load_dwordx4 v[146:149], v[134:135], off offset:256
	v_and_b32_e32 v130, 64, v205
	v_or_b32_e32 v200, v130, v181
	v_lshlrev_b32_e32 v225, 2, v200
	ds_bpermute_b32 v200, v225, v226
	v_xor_b32_e32 v131, 16, v205
	v_add_u32_e32 v130, 64, v130
	v_cmp_lt_i32_e64 s[44:45], v131, v130
	s_waitcnt lgkmcnt(0)
; __device__ __forceinline__ float bf_lo(unsigned w) { return __uint_as_float(w << 16); }
; __device__ __forceinline__ float bf_hi(unsigned w) { return __uint_as_float(w & 0xffff0000u); }
;     template <int mode> __device__ __forceinline__ void run(const f32x4 (&acc)[2][2][4][2], const Unit& u, int wr, int wc, int fr, int fq, const LAS float* sc) const {
;     ...
;                 float s = 1.f;
;                 if (mode == 4) s = __shfl(ai ? sB : sA, m * 16 + fr);
;                 float ss = 0.f;
; #pragma unroll
;                 for (int bj = 0; bj < 2; ++bj) {
;                     u32x4 wh, wl;
; #pragma unroll
;                     for (int n = 0; n < 2; ++n) {
;                         const int q = 2 * bj + n;
;                         const unsigned h0 = n ? xh[cb][bj].z : xh[cb][bj].x, h1 = n ? xh[cb][bj].w : xh[cb][bj].y, l0 = n ? xl[cb][bj].z : xl[cb][bj].x, l1 = n ? xl[cb][bj].w : xl[cb][bj].y;
;                         f32x4 xo;
;                         if (mode == 5) xo = xi[cb][q];
;                         else { xo[0] = bf_lo(h0) + bf_lo(l0); xo[1] = bf_hi(h0) + bf_hi(l0); xo[2] = bf_lo(h1) + bf_lo(l1); xo[3] = bf_hi(h1) + bf_hi(l1); }
;                         f32x4 v;
;                         if (mode != 4) v = xo + acc[ai][bj][m][n] * alpha + bvv[q];
;                         else {
;                             const f32x4 a = acc[ai][bj][m][n] * s;
;                             const unsigned p0 = n ? pq[cb][bj].z : pq[cb][bj].x, p1 = n ? pq[cb][bj].w : pq[cb][bj].y;
;                             v[0] = xo[0] + sigmoidf_(a[0]) * bf_lo(p0); v[1] = xo[1] + sigmoidf_(a[1]) * bf_hi(p0);
;                             v[2] = xo[2] + sigmoidf_(a[2]) * bf_lo(p1); v[3] = xo[3] + sigmoidf_(a[3]) * bf_hi(p1);
;                         }
;                         const unsigned w0 = pk2(v[0], v[1]), w1 = pk2(v[2], v[3]);
;                         const unsigned m0 = pk2(v[0] - bf_lo(w0), v[1] - bf_hi(w0)), m1 = pk2(v[2] - bf_lo(w1), v[3] - bf_hi(w1));
;                         if (n == 0) { wh.x = w0; wh.y = w1; wl.x = m0; wl.y = m1; } else { wh.z = w0; wh.w = w1; wl.z = m0; wl.w = m1; }
;                         ss += (v[0] * v[0] + v[1] * v[1]) + (v[2] * v[2] + v[3] * v[3]);
;                     }
;                     *(u32x4*)(xb + off + bj * HALF) = wh;
;                     *(u32x4*)(lout + off + bj * HALF) = wl;
	v_pk_mul_f32 v[126:127], v[126:127], v[200:201] op_sel_hi:[1,0]
	v_cndmask_b32_e64 v131, v205, v131, s[44:45]
	v_lshlrev_b32_e32 v191, 2, v131
	v_xor_b32_e32 v131, 32, v205
	v_mul_f32_e32 v126, 0xbfb8aa3b, v126
	v_cmp_lt_i32_e64 s[44:45], v131, v130
	v_exp_f32_e32 v126, v126
	v_pk_mul_f32 v[128:129], v[128:129], v[200:201] op_sel_hi:[1,0]
	v_cndmask_b32_e64 v130, v205, v131, s[44:45]
	v_lshlrev_b32_e32 v224, 2, v130
	v_lshlrev_b64 v[130:131], 10, v[194:195]
	v_lshl_add_u64 v[130:131], v[130:131], 0, v[188:189]
	v_lshlrev_b64 v[196:197], 1, v[130:131]
	v_add_f32_e32 v126, 1.0, v126
	v_lshl_add_u64 v[130:131], s[34:35], 0, v[196:197]
	v_lshl_add_u64 v[132:133], s[92:93], 0, v[196:197]
	v_lshl_add_u64 v[228:229], s[6:7], 0, v[196:197]
	v_rcp_f32_e32 v126, v126
	global_load_dwordx4 v[150:153], v[130:131], off
	global_load_dwordx4 v[154:157], v[132:133], off
	global_load_dwordx4 v[142:145], v[228:229], off
	global_load_dwordx4 v[134:137], v[130:131], off offset:256
	global_load_dwordx4 v[138:141], v[132:133], off offset:256
	s_nop 0
	global_load_dwordx4 v[130:133], v[228:229], off offset:256
	v_pk_mul_f32 v[122:123], v[122:123], v[200:201] op_sel_hi:[1,0]
	v_pk_mul_f32 v[124:125], v[124:125], v[200:201] op_sel_hi:[1,0]
	v_mul_f32_e32 v122, 0xbfb8aa3b, v122
	v_exp_f32_e32 v122, v122
	v_pk_mul_f32 v[118:119], v[118:119], v[200:201] op_sel_hi:[1,0]
	v_pk_mul_f32 v[120:121], v[120:121], v[200:201] op_sel_hi:[1,0]
	v_mul_f32_e32 v118, 0xbfb8aa3b, v118
	v_add_f32_e32 v122, 1.0, v122
	v_rcp_f32_e32 v122, v122
	v_exp_f32_e32 v118, v118
	v_pk_mul_f32 v[114:115], v[114:115], v[200:201] op_sel_hi:[1,0]
	v_pk_mul_f32 v[116:117], v[116:117], v[200:201] op_sel_hi:[1,0]
	v_mul_f32_e32 v114, 0xbfb8aa3b, v114
	v_add_f32_e32 v118, 1.0, v118
	v_rcp_f32_e32 v118, v118
	v_exp_f32_e32 v114, v114
	s_lshl_b32 s44, s2, 2
	s_ashr_i32 s45, s44, 31
	v_add_f32_e32 v114, 1.0, v114
	v_rcp_f32_e32 v114, v114
	s_waitcnt vmcnt(11)
	v_lshlrev_b32_e32 v227, 16, v170
	s_waitcnt vmcnt(10)
	v_lshlrev_b32_e32 v228, 16, v174
	v_and_b32_e32 v174, 0xffff0000, v174
	v_and_b32_e32 v170, 0xffff0000, v170
	v_add_f32_e32 v227, v228, v227
	v_add_f32_e32 v170, v174, v170
	v_lshlrev_b32_e32 v174, 16, v171
	v_lshlrev_b32_e32 v228, 16, v175
	v_and_b32_e32 v175, 0xffff0000, v175
	v_and_b32_e32 v171, 0xffff0000, v171
	v_add_f32_e32 v171, v175, v171
	s_waitcnt vmcnt(9)
	v_lshlrev_b32_e32 v175, 16, v166
	v_fmac_f32_e32 v227, v126, v175
	v_mul_f32_e32 v126, 0xbfb8aa3b, v127
	v_exp_f32_e32 v126, v126
	v_and_b32_e32 v127, 0xffff0000, v166
	v_add_f32_e32 v174, v228, v174
	v_add_f32_e32 v126, 1.0, v126
	v_rcp_f32_e32 v126, v126
	s_nop 0
	v_fmac_f32_e32 v170, v126, v127
	v_mul_f32_e32 v126, 0xbfb8aa3b, v128
	v_exp_f32_e32 v126, v126
	v_lshlrev_b32_e32 v127, 16, v167
	v_add_f32_e32 v126, 1.0, v126
	v_rcp_f32_e32 v126, v126
	s_nop 0
	v_fmac_f32_e32 v174, v126, v127
	v_mul_f32_e32 v126, 0xbfb8aa3b, v129
	v_exp_f32_e32 v126, v126
	v_and_b32_e32 v127, 0xffff0000, v167
	v_add_f32_e32 v126, 1.0, v126
	v_rcp_f32_e32 v126, v126
	s_nop 0
	v_fmac_f32_e32 v171, v126, v127
	v_cvt_pk_bf16_f32 v126, v227, v170
	v_cvt_pk_bf16_f32 v127, v174, v171
	s_nop 0
	v_lshlrev_b32_e32 v128, 16, v126
	v_and_b32_e32 v129, 0xffff0000, v126
	v_sub_f32_e32 v128, v227, v128
	v_sub_f32_e32 v129, v170, v129
	v_cvt_pk_bf16_f32 v166, v128, v129
	v_lshlrev_b32_e32 v128, 16, v127
	v_and_b32_e32 v129, 0xffff0000, v127
	v_sub_f32_e32 v128, v174, v128
	v_sub_f32_e32 v129, v171, v129
	v_cvt_pk_bf16_f32 v167, v128, v129
	v_mul_f32_e32 v128, v170, v170
	v_mul_f32_e32 v129, v171, v171
	v_fmac_f32_e32 v128, v227, v227
	v_fmac_f32_e32 v129, v174, v174
	v_add_f32_e32 v170, v128, v129
	v_lshlrev_b32_e32 v128, 16, v172
	v_lshlrev_b32_e32 v129, 16, v176
	v_add_f32_e32 v171, v129, v128
	v_and_b32_e32 v128, 0xffff0000, v176
	v_and_b32_e32 v129, 0xffff0000, v172
	v_add_f32_e32 v172, v128, v129
	v_lshlrev_b32_e32 v128, 16, v173
	v_lshlrev_b32_e32 v129, 16, v177
	v_add_f32_e32 v174, v129, v128
	v_and_b32_e32 v128, 0xffff0000, v177
	v_and_b32_e32 v129, 0xffff0000, v173
	v_add_f32_e32 v173, v128, v129
	v_lshlrev_b32_e32 v128, 16, v168
	v_fmac_f32_e32 v171, v122, v128
	v_mul_f32_e32 v122, 0xbfb8aa3b, v123
	v_exp_f32_e32 v122, v122
	v_and_b32_e32 v123, 0xffff0000, v168
	v_add_f32_e32 v122, 1.0, v122
	v_rcp_f32_e32 v122, v122
	s_nop 0
	v_fmac_f32_e32 v172, v122, v123
	v_mul_f32_e32 v122, 0xbfb8aa3b, v124
	v_exp_f32_e32 v122, v122
	v_lshlrev_b32_e32 v123, 16, v169
	v_cvt_pk_bf16_f32 v128, v171, v172
	v_add_f32_e32 v122, 1.0, v122
	v_rcp_f32_e32 v122, v122
	s_nop 0
	v_fmac_f32_e32 v174, v122, v123
	v_mul_f32_e32 v122, 0xbfb8aa3b, v125
	v_exp_f32_e32 v122, v122
	v_and_b32_e32 v123, 0xffff0000, v169
	v_lshl_add_u64 v[124:125], s[28:29], 0, v[198:199]
	v_add_f32_e32 v122, 1.0, v122
	v_rcp_f32_e32 v122, v122
	s_nop 0
	v_fmac_f32_e32 v173, v122, v123
	v_lshlrev_b32_e32 v122, 16, v128
	v_and_b32_e32 v123, 0xffff0000, v128
	v_sub_f32_e32 v122, v171, v122
	v_sub_f32_e32 v123, v172, v123
	v_cvt_pk_bf16_f32 v129, v174, v173
	v_cvt_pk_bf16_f32 v168, v122, v123
	s_nop 0
	v_lshlrev_b32_e32 v122, 16, v129
	v_and_b32_e32 v123, 0xffff0000, v129
	v_sub_f32_e32 v122, v174, v122
	v_sub_f32_e32 v123, v173, v123
	v_cvt_pk_bf16_f32 v169, v122, v123
	v_mul_f32_e32 v122, v172, v172
	v_mul_f32_e32 v123, v173, v173
	v_fmac_f32_e32 v122, v171, v171
	v_fmac_f32_e32 v123, v174, v174
	v_add_f32_e32 v122, v122, v123
	v_add_f32_e32 v170, v170, v122
	v_lshl_add_u64 v[122:123], s[10:11], 0, v[198:199]
	global_store_dwordx4 v[122:123], v[126:129], off
	global_store_dwordx4 v[124:125], v[166:169], off
	s_waitcnt vmcnt(10)
; __device__ __forceinline__ float bf_lo(unsigned w) { return __uint_as_float(w << 16); }
; __device__ __forceinline__ float bf_hi(unsigned w) { return __uint_as_float(w & 0xffff0000u); }
;     template <int mode> __device__ __forceinline__ void run(const f32x4 (&acc)[2][2][4][2], const Unit& u, int wr, int wc, int fr, int fq, const LAS float* sc) const {
;     ...
;                 for (int bj = 0; bj < 2; ++bj) {
;                     u32x4 wh, wl;
; #pragma unroll
;                     for (int n = 0; n < 2; ++n) {
;                         const int q = 2 * bj + n;
;                         const unsigned h0 = n ? xh[cb][bj].z : xh[cb][bj].x, h1 = n ? xh[cb][bj].w : xh[cb][bj].y, l0 = n ? xl[cb][bj].z : xl[cb][bj].x, l1 = n ? xl[cb][bj].w : xl[cb][bj].y;
;                         f32x4 xo;
;                         if (mode == 5) xo = xi[cb][q];
;                         else { xo[0] = bf_lo(h0) + bf_lo(l0); xo[1] = bf_hi(h0) + bf_hi(l0); xo[2] = bf_lo(h1) + bf_lo(l1); xo[3] = bf_hi(h1) + bf_hi(l1); }
;                         f32x4 v;
;                         if (mode != 4) v = xo + acc[ai][bj][m][n] * alpha + bvv[q];
;                         else {
;                             const f32x4 a = acc[ai][bj][m][n] * s;
;                             const unsigned p0 = n ? pq[cb][bj].z : pq[cb][bj].x, p1 = n ? pq[cb][bj].w : pq[cb][bj].y;
;                             v[0] = xo[0] + sigmoidf_(a[0]) * bf_lo(p0); v[1] = xo[1] + sigmoidf_(a[1]) * bf_hi(p0);
;                             v[2] = xo[2] + sigmoidf_(a[2]) * bf_lo(p1); v[3] = xo[3] + sigmoidf_(a[3]) * bf_hi(p1);
;                         }
;                         const unsigned w0 = pk2(v[0], v[1]), w1 = pk2(v[2], v[3]);
;                         const unsigned m0 = pk2(v[0] - bf_lo(w0), v[1] - bf_hi(w0)), m1 = pk2(v[2] - bf_lo(w1), v[3] - bf_hi(w1));
;                         if (n == 0) { wh.x = w0; wh.y = w1; wl.x = m0; wl.y = m1; } else { wh.z = w0; wh.w = w1; wl.z = m0; wl.w = m1; }
;                         ss += (v[0] * v[0] + v[1] * v[1]) + (v[2] * v[2] + v[3] * v[3]);
;                     }
;                     *(u32x4*)(xb + off + bj * HALF) = wh;
;                     *(u32x4*)(lout + off + bj * HALF) = wl;
;                 }
;                 ss += __shfl_xor(ss, 16); ss += __shfl_xor(ss, 32);
;                 if (fq == 0) ssq_out[(size_t)row * 16 + u.pn * 4 + wc] = ss;
	v_lshlrev_b32_e32 v126, 16, v158
	s_waitcnt vmcnt(9)
	v_lshlrev_b32_e32 v127, 16, v162
	v_add_f32_e32 v128, v127, v126
	v_and_b32_e32 v126, 0xffff0000, v162
	v_and_b32_e32 v127, 0xffff0000, v158
	v_add_f32_e32 v129, v126, v127
	v_lshlrev_b32_e32 v126, 16, v159
	v_lshlrev_b32_e32 v127, 16, v163
	v_add_f32_e32 v158, v127, v126
	v_and_b32_e32 v126, 0xffff0000, v163
	v_and_b32_e32 v127, 0xffff0000, v159
	v_add_f32_e32 v159, v126, v127
	s_waitcnt vmcnt(8)
	v_lshlrev_b32_e32 v126, 16, v146
	v_fmac_f32_e32 v128, v118, v126
	v_mul_f32_e32 v118, 0xbfb8aa3b, v119
	v_exp_f32_e32 v118, v118
	v_and_b32_e32 v119, 0xffff0000, v146
	v_add_f32_e32 v118, 1.0, v118
	v_rcp_f32_e32 v118, v118
	s_nop 0
	v_fmac_f32_e32 v129, v118, v119
	v_mul_f32_e32 v118, 0xbfb8aa3b, v120
	v_exp_f32_e32 v118, v118
	v_lshlrev_b32_e32 v119, 16, v147
	v_add_f32_e32 v118, 1.0, v118
	v_rcp_f32_e32 v118, v118
	s_nop 0
	v_fmac_f32_e32 v158, v118, v119
	v_mul_f32_e32 v118, 0xbfb8aa3b, v121
	v_exp_f32_e32 v118, v118
	v_and_b32_e32 v119, 0xffff0000, v147
	v_add_f32_e32 v118, 1.0, v118
	v_rcp_f32_e32 v118, v118
	s_nop 0
	v_fmac_f32_e32 v159, v118, v119
	v_cvt_pk_bf16_f32 v118, v128, v129
	v_cvt_pk_bf16_f32 v119, v158, v159
	s_nop 0
	v_lshlrev_b32_e32 v120, 16, v118
	v_and_b32_e32 v121, 0xffff0000, v118
	v_sub_f32_e32 v120, v128, v120
	v_sub_f32_e32 v121, v129, v121
	v_cvt_pk_bf16_f32 v126, v120, v121
	v_lshlrev_b32_e32 v120, 16, v119
	v_and_b32_e32 v121, 0xffff0000, v119
	v_sub_f32_e32 v120, v158, v120
	v_sub_f32_e32 v121, v159, v121
	v_cvt_pk_bf16_f32 v127, v120, v121
	v_mul_f32_e32 v120, v129, v129
	v_mul_f32_e32 v121, v159, v159
	v_fmac_f32_e32 v120, v128, v128
	v_fmac_f32_e32 v121, v158, v158
	v_add_f32_e32 v120, v120, v121
	v_add_f32_e32 v146, v120, v170
	v_lshlrev_b32_e32 v120, 16, v160
	v_lshlrev_b32_e32 v121, 16, v164
	v_add_f32_e32 v147, v121, v120
	v_and_b32_e32 v120, 0xffff0000, v164
	v_and_b32_e32 v121, 0xffff0000, v160
	v_add_f32_e32 v158, v120, v121
	v_lshlrev_b32_e32 v120, 16, v161
	v_lshlrev_b32_e32 v121, 16, v165
	v_add_f32_e32 v159, v121, v120
	v_and_b32_e32 v120, 0xffff0000, v165
	v_and_b32_e32 v121, 0xffff0000, v161
	v_add_f32_e32 v160, v120, v121
	v_lshlrev_b32_e32 v120, 16, v148
	v_fmac_f32_e32 v147, v114, v120
	v_mul_f32_e32 v114, 0xbfb8aa3b, v115
	v_exp_f32_e32 v114, v114
	v_and_b32_e32 v115, 0xffff0000, v148
	v_add_f32_e32 v114, 1.0, v114
	v_rcp_f32_e32 v114, v114
	s_nop 0
	v_fmac_f32_e32 v158, v114, v115
	v_mul_f32_e32 v114, 0xbfb8aa3b, v116
	v_exp_f32_e32 v114, v114
	v_lshlrev_b32_e32 v115, 16, v149
	v_cvt_pk_bf16_f32 v120, v147, v158
	v_add_f32_e32 v114, 1.0, v114
	v_rcp_f32_e32 v114, v114
	s_nop 0
	v_fmac_f32_e32 v159, v114, v115
	v_mul_f32_e32 v114, 0xbfb8aa3b, v117
	v_exp_f32_e32 v114, v114
	v_and_b32_e32 v115, 0xffff0000, v149
	v_add_f32_e32 v114, 1.0, v114
	v_rcp_f32_e32 v114, v114
	s_nop 0
	v_fmac_f32_e32 v160, v114, v115
	v_lshlrev_b32_e32 v114, 16, v120
	v_and_b32_e32 v115, 0xffff0000, v120
	v_sub_f32_e32 v114, v147, v114
	v_sub_f32_e32 v115, v158, v115
	v_cvt_pk_bf16_f32 v121, v159, v160
	v_cvt_pk_bf16_f32 v128, v114, v115
	s_nop 0
	v_lshlrev_b32_e32 v114, 16, v121
	v_and_b32_e32 v115, 0xffff0000, v121
	v_sub_f32_e32 v114, v159, v114
	v_sub_f32_e32 v115, v160, v115
	v_cvt_pk_bf16_f32 v129, v114, v115
	v_mul_f32_e32 v114, v158, v158
	v_mul_f32_e32 v115, v160, v160
	v_fmac_f32_e32 v114, v147, v147
	v_fmac_f32_e32 v115, v159, v159
	v_add_f32_e32 v114, v114, v115
	v_add_f32_e32 v114, v114, v146
	ds_bpermute_b32 v115, v191, v114
	global_store_dwordx4 v[122:123], v[118:121], off offset:256
	global_store_dwordx4 v[124:125], v[126:129], off offset:256
	s_waitcnt lgkmcnt(0)
	v_add_f32_e32 v114, v114, v115
	ds_bpermute_b32 v115, v224, v114
	s_and_saveexec_b64 s[4:5], s[40:41]
	s_cbranch_execz .LBB0_162
	v_lshlrev_b64 v[116:117], 6, v[192:193]
	v_lshl_add_u64 v[116:117], s[62:63], 0, v[116:117]
	v_lshl_add_u64 v[116:117], s[44:45], 2, v[116:117]
	s_lshl_b32 s24, s20, 2
	v_lshl_add_u64 v[116:117], v[116:117], 0, s[24:25]
	s_waitcnt lgkmcnt(0)
	v_add_f32_e32 v114, v114, v115
	global_store_dword v[116:117], v114, off

; #define PG8_STAGE(bufoff, gbase, voff) do { _Pragma("unroll") for (int _i = 0; _i < 2; ++_i) \
;         __builtin_amdgcn_global_load_lds((const unsigned*)((const char*)(gbase) + (voff)[_i]), (LAS unsigned*)(lds + (bufoff) + ldsw + _i * 8192), 16, 0, 0); } while (0)
; #define PG8_LDA(dst, b, h) do { _Pragma("unroll") for (int m = 0; m < 4; ++m) _Pragma("unroll") for (int k = 0; k < 2; ++k) dst[m][k] = *(const LAS bf16x8*)(lds + PG8_SA(b, h) + aoff + m * 2048 + k * 1024); } while (0)
; #define PG8_LDB(dst, b, h) do { _Pragma("unroll") for (int n = 0; n < 2; ++n) _Pragma("unroll") for (int k = 0; k < 2; ++k) dst[n][k] = *(const LAS bf16x8*)(lds + PG8_SB(b, h) + boff + n * 2048 + k * 1024); } while (0)
; #define PG8_WAIT_V(n) asm volatile("s_waitcnt vmcnt(" #n ")" ::: "memory")
; #define PG8_WAIT_L(n) asm volatile("s_waitcnt lgkmcnt(" #n ")" ::: "memory")
; #define PG8_BAR __builtin_amdgcn_s_barrier()
; #define PG8_SCHED __builtin_amdgcn_sched_barrier(0)
; template <int MODE, class EpiT, class Sched>
; __device__ __forceinline__ void gemm_phase(LAS unsigned char* lds, const Gemm g, const Sched& S, const EpiT& E) {
;     ...
;             PG8_LDB(B0, 0, 0); PG8_SCHED; PG8_LDA(At, 0, 0); PG8_STAGE(PG8_SA(1, 1), a1 + hstep, voffA);
;             PG8_WAIT_L(8); PG8_BAR; PG8_WAIT_L(0); PG8_MMA(0, 0, At, B0); PG8_BAR; PG8_SCHED;
;             PG8_LDB(B1, 0, 1); PG8_STAGE(PG8_SB(0, 0), b2, voffB);
;             PG8_BAR; PG8_WAIT_L(0); PG8_MMA(0, 1, At, B1); PG8_BAR;
;             PG8_LDA(At, 0, 1); PG8_STAGE(PG8_SA(0, 0), a2, voffA);
;             PG8_BAR; PG8_WAIT_L(0); PG8_MMA(1, 0, At, B0); PG8_BAR; PG8_SCHED;
;             PG8_STAGE(PG8_SB(0, 1), b2 + hstep, voffB);
;             PG8_WAIT_V(6); PG8_BAR; PG8_MMA(1, 1, At, B1); PG8_BAR;
;             PG8_LDB(B0, 1, 0); PG8_SCHED; PG8_LDA(At, 1, 0); PG8_STAGE(PG8_SA(0, 1), a2 + hstep, voffA);
;             PG8_WAIT_L(8); PG8_BAR; PG8_WAIT_L(0); PG8_MMA(0, 0, At, B0); PG8_BAR; PG8_SCHED;
;             PG8_LDB(B1, 1, 1); PG8_STAGE(PG8_SB(1, 0), b3, voffB);
;             PG8_BAR; PG8_WAIT_L(0); PG8_MMA(0, 1, At, B1); PG8_BAR;
;             PG8_LDA(At, 1, 1); PG8_STAGE(PG8_SA(1, 0), a3, voffA);
;             PG8_BAR; PG8_WAIT_L(0); PG8_MMA(1, 0, At, B0); PG8_BAR; PG8_SCHED;
;             PG8_STAGE(PG8_SB(1, 1), b3 + hstep, voffB);
;             PG8_WAIT_V(6); PG8_BAR; PG8_MMA(1, 1, At, B1); PG8_BAR;
.LBB0_195:
	s_add_i32 vcc_lo, s44, 2
	s_add_u32 s52, s4, 0x80
	s_addc_u32 s45, s5, 0
	s_add_i32 s58, 0, 0x10000
	v_add_u32_e32 v74, s58, v194
	ds_read_b128 v[58:61], v74
	ds_read_b128 v[62:65], v74 offset:1024
	ds_read_b128 v[70:73], v74 offset:2048
	ds_read_b128 v[74:77], v74 offset:3072
	s_cmp_eq_u32 s75, s44
	s_cselect_b32 s44, s68, s52
	s_cselect_b32 s45, s69, s45
	s_cselect_b32 s53, s47, s90
	s_cselect_b32 s52, s46, s89
	v_lshl_add_u64 v[188:189], s[4:5], 0, v[176:177]
	s_add_i32 m0, s21, 0xc000
	ds_read_b128 v[138:141], v196
	ds_read_b128 v[142:145], v196 offset:1024
	ds_read_b128 v[146:149], v196 offset:2048
	ds_read_b128 v[150:153], v196 offset:3072
	ds_read_b128 v[162:165], v196 offset:4096
	ds_read_b128 v[166:169], v196 offset:5120
	ds_read_b128 v[170:173], v196 offset:6144
	ds_read_b128 v[184:187], v196 offset:7168
	global_load_lds_dwordx4 v[188:189], off
	v_lshl_add_u64 v[188:189], s[4:5], 0, v[182:183]
	s_add_i32 m0, s21, 0xe000
	s_nop 0
	global_load_lds_dwordx4 v[188:189], off
	s_waitcnt lgkmcnt(8)
	s_barrier
	s_waitcnt lgkmcnt(0)
	v_mfma_f32_16x16x32_bf16 v[158:161], v[58:61], v[138:141], v[158:161]
	v_mfma_f32_16x16x32_bf16 v[154:157], v[70:73], v[138:141], v[154:157]
	v_mfma_f32_16x16x32_bf16 v[126:129], v[58:61], v[146:149], v[126:129]
	v_mfma_f32_16x16x32_bf16 v[122:125], v[70:73], v[146:149], v[122:125]
	v_mfma_f32_16x16x32_bf16 v[110:113], v[58:61], v[162:165], v[110:113]
	v_mfma_f32_16x16x32_bf16 v[106:109], v[70:73], v[162:165], v[106:109]
	v_mfma_f32_16x16x32_bf16 v[94:97], v[58:61], v[170:173], v[94:97]
	v_mfma_f32_16x16x32_bf16 v[90:93], v[70:73], v[170:173], v[90:93]
	v_mfma_f32_16x16x32_bf16 v[158:161], v[62:65], v[142:145], v[158:161]
	v_mfma_f32_16x16x32_bf16 v[154:157], v[74:77], v[142:145], v[154:157]
	v_mfma_f32_16x16x32_bf16 v[126:129], v[62:65], v[150:153], v[126:129]
	v_mfma_f32_16x16x32_bf16 v[122:125], v[74:77], v[150:153], v[122:125]
	v_mfma_f32_16x16x32_bf16 v[110:113], v[62:65], v[166:169], v[110:113]
	v_mfma_f32_16x16x32_bf16 v[106:109], v[74:77], v[166:169], v[106:109]
	v_mfma_f32_16x16x32_bf16 v[94:97], v[62:65], v[184:187], v[94:97]
	s_barrier
	v_mfma_f32_16x16x32_bf16 v[90:93], v[74:77], v[184:187], v[90:93]
	s_add_i32 s59, 0, 0x14000
	v_add_u32_e32 v192, s59, v194
	s_add_i32 s58, s58, s20
	ds_read_b128 v[188:191], v192
	ds_read_b128 v[220:223], v192 offset:1024
	ds_read_b128 v[224:227], v192 offset:2048
	ds_read_b128 v[228:231], v192 offset:3072
	v_lshl_add_u64 v[192:193], s[52:53], 0, v[0:1]
	s_mov_b32 m0, s58
	v_lshl_add_u64 v[198:199], s[52:53], 0, v[174:175]
	global_load_lds_dwordx4 v[192:193], off
	s_add_i32 m0, s58, 0x2000
	s_nop 0
	global_load_lds_dwordx4 v[198:199], off
	s_barrier
	s_waitcnt lgkmcnt(0)
	v_mfma_f32_16x16x32_bf16 v[134:137], v[188:191], v[138:141], v[134:137]
	v_mfma_f32_16x16x32_bf16 v[130:133], v[224:227], v[138:141], v[130:133]
	v_mfma_f32_16x16x32_bf16 v[118:121], v[188:191], v[146:149], v[118:121]
	v_mfma_f32_16x16x32_bf16 v[114:117], v[224:227], v[146:149], v[114:117]
	v_mfma_f32_16x16x32_bf16 v[102:105], v[188:191], v[162:165], v[102:105]
	v_mfma_f32_16x16x32_bf16 v[98:101], v[224:227], v[162:165], v[98:101]
	v_mfma_f32_16x16x32_bf16 v[86:89], v[188:191], v[170:173], v[86:89]
	v_mfma_f32_16x16x32_bf16 v[82:85], v[224:227], v[170:173], v[82:85]
	v_mfma_f32_16x16x32_bf16 v[134:137], v[220:223], v[142:145], v[134:137]
	v_mfma_f32_16x16x32_bf16 v[130:133], v[228:231], v[142:145], v[130:133]
	v_mfma_f32_16x16x32_bf16 v[118:121], v[220:223], v[150:153], v[118:121]
	v_mfma_f32_16x16x32_bf16 v[114:117], v[228:231], v[150:153], v[114:117]
	v_mfma_f32_16x16x32_bf16 v[102:105], v[220:223], v[166:169], v[102:105]
	v_mfma_f32_16x16x32_bf16 v[98:101], v[228:231], v[166:169], v[98:101]
	v_mfma_f32_16x16x32_bf16 v[86:89], v[220:223], v[184:187], v[86:89]
	s_barrier
	v_mfma_f32_16x16x32_bf16 v[82:85], v[228:231], v[184:187], v[82:85]
	s_mov_b32 m0, s21
	v_lshl_add_u64 v[232:233], s[44:45], 0, v[0:1]
	ds_read_b128 v[138:141], v196 offset:16384
	ds_read_b128 v[142:145], v196 offset:17408
	ds_read_b128 v[146:149], v196 offset:18432
	ds_read_b128 v[150:153], v196 offset:19456
	ds_read_b128 v[162:165], v196 offset:20480
	ds_read_b128 v[166:169], v196 offset:21504
	ds_read_b128 v[170:173], v196 offset:22528
	ds_read_b128 v[184:187], v196 offset:23552
	global_load_lds_dwordx4 v[232:233], off
	v_lshl_add_u64 v[234:235], s[44:45], 0, v[174:175]
	s_mov_b32 m0, s50
	s_nop 0
	global_load_lds_dwordx4 v[234:235], off
	s_barrier
	s_waitcnt lgkmcnt(0)
	v_mfma_f32_16x16x32_bf16 v[78:81], v[58:61], v[138:141], v[78:81]
	v_mfma_f32_16x16x32_bf16 v[66:69], v[70:73], v[138:141], v[66:69]
	v_mfma_f32_16x16x32_bf16 v[46:49], v[58:61], v[146:149], v[46:49]
	v_mfma_f32_16x16x32_bf16 v[42:45], v[70:73], v[146:149], v[42:45]
	v_mfma_f32_16x16x32_bf16 v[30:33], v[58:61], v[162:165], v[30:33]
	v_mfma_f32_16x16x32_bf16 v[26:29], v[70:73], v[162:165], v[26:29]
	v_mfma_f32_16x16x32_bf16 v[14:17], v[58:61], v[170:173], v[14:17]
	v_mfma_f32_16x16x32_bf16 v[10:13], v[70:73], v[170:173], v[10:13]
	v_mfma_f32_16x16x32_bf16 v[78:81], v[62:65], v[142:145], v[78:81]
	v_mfma_f32_16x16x32_bf16 v[66:69], v[74:77], v[142:145], v[66:69]
	v_mfma_f32_16x16x32_bf16 v[46:49], v[62:65], v[150:153], v[46:49]
	v_mfma_f32_16x16x32_bf16 v[42:45], v[74:77], v[150:153], v[42:45]
	v_mfma_f32_16x16x32_bf16 v[30:33], v[62:65], v[166:169], v[30:33]
	v_mfma_f32_16x16x32_bf16 v[26:29], v[74:77], v[166:169], v[26:29]
	v_mfma_f32_16x16x32_bf16 v[14:17], v[62:65], v[184:187], v[14:17]
	s_barrier
; #define PG8_STAGE(bufoff, gbase, voff) do { _Pragma("unroll") for (int _i = 0; _i < 2; ++_i) \
;         __builtin_amdgcn_global_load_lds((const unsigned*)((const char*)(gbase) + (voff)[_i]), (LAS unsigned*)(lds + (bufoff) + ldsw + _i * 8192), 16, 0, 0); } while (0)
; #define PG8_LDA(dst, b, h) do { _Pragma("unroll") for (int m = 0; m < 4; ++m) _Pragma("unroll") for (int k = 0; k < 2; ++k) dst[m][k] = *(const LAS bf16x8*)(lds + PG8_SA(b, h) + aoff + m * 2048 + k * 1024); } while (0)
; #define PG8_LDB(dst, b, h) do { _Pragma("unroll") for (int n = 0; n < 2; ++n) _Pragma("unroll") for (int k = 0; k < 2; ++k) dst[n][k] = *(const LAS bf16x8*)(lds + PG8_SB(b, h) + boff + n * 2048 + k * 1024); } while (0)
; #define PG8_WAIT_V(n) asm volatile("s_waitcnt vmcnt(" #n ")" ::: "memory")
; #define PG8_WAIT_L(n) asm volatile("s_waitcnt lgkmcnt(" #n ")" ::: "memory")
; #define PG8_BAR __builtin_amdgcn_s_barrier()
; #define PG8_SCHED __builtin_amdgcn_sched_barrier(0)
; template <int MODE, class EpiT, class Sched>
; __device__ __forceinline__ void gemm_phase(LAS unsigned char* lds, const Gemm g, const Sched& S, const EpiT& E) {
;     ...
;             PG8_LDB(B0, 0, 0); PG8_SCHED; PG8_LDA(At, 0, 0); PG8_STAGE(PG8_SA(1, 1), a1 + hstep, voffA);
;             PG8_WAIT_L(8); PG8_BAR; PG8_WAIT_L(0); PG8_MMA(0, 0, At, B0); PG8_BAR; PG8_SCHED;
;             PG8_LDB(B1, 0, 1); PG8_STAGE(PG8_SB(0, 0), b2, voffB);
;             PG8_BAR; PG8_WAIT_L(0); PG8_MMA(0, 1, At, B1); PG8_BAR;
;             PG8_LDA(At, 0, 1); PG8_STAGE(PG8_SA(0, 0), a2, voffA);
;             PG8_BAR; PG8_WAIT_L(0); PG8_MMA(1, 0, At, B0); PG8_BAR; PG8_SCHED;
;             PG8_STAGE(PG8_SB(0, 1), b2 + hstep, voffB);
;             PG8_WAIT_V(6); PG8_BAR; PG8_MMA(1, 1, At, B1); PG8_BAR;
;             PG8_LDB(B0, 1, 0); PG8_SCHED; PG8_LDA(At, 1, 0); PG8_STAGE(PG8_SA(0, 1), a2 + hstep, voffA);
;             PG8_WAIT_L(8); PG8_BAR; PG8_WAIT_L(0); PG8_MMA(0, 0, At, B0); PG8_BAR; PG8_SCHED;
;             PG8_LDB(B1, 1, 1); PG8_STAGE(PG8_SB(1, 0), b3, voffB);
;             PG8_BAR; PG8_WAIT_L(0); PG8_MMA(0, 1, At, B1); PG8_BAR;
;             PG8_LDA(At, 1, 1); PG8_STAGE(PG8_SA(1, 0), a3, voffA);
;             PG8_BAR; PG8_WAIT_L(0); PG8_MMA(1, 0, At, B0); PG8_BAR; PG8_SCHED;
;             PG8_STAGE(PG8_SB(1, 1), b3 + hstep, voffB);
;             PG8_WAIT_V(6); PG8_BAR; PG8_MMA(1, 1, At, B1); PG8_BAR;
	v_mfma_f32_16x16x32_bf16 v[10:13], v[74:77], v[184:187], v[10:13]
	s_add_u32 s52, s52, s38
	s_addc_u32 s53, s53, 0
	s_add_i32 s58, s59, s20
	v_lshl_add_u64 v[236:237], s[52:53], 0, v[0:1]
	s_mov_b32 m0, s58
	v_lshl_add_u64 v[238:239], s[52:53], 0, v[174:175]
	global_load_lds_dwordx4 v[236:237], off
	s_add_i32 m0, s58, 0x2000
	s_nop 0
	global_load_lds_dwordx4 v[238:239], off
	s_waitcnt vmcnt(6)
	s_barrier
	v_mfma_f32_16x16x32_bf16 v[54:57], v[188:191], v[138:141], v[54:57]
	v_mfma_f32_16x16x32_bf16 v[50:53], v[224:227], v[138:141], v[50:53]
	v_mfma_f32_16x16x32_bf16 v[38:41], v[188:191], v[146:149], v[38:41]
	v_mfma_f32_16x16x32_bf16 v[34:37], v[224:227], v[146:149], v[34:37]
	v_mfma_f32_16x16x32_bf16 v[22:25], v[188:191], v[162:165], v[22:25]
	v_mfma_f32_16x16x32_bf16 v[18:21], v[224:227], v[162:165], v[18:21]
	v_mfma_f32_16x16x32_bf16 v[6:9], v[188:191], v[170:173], v[6:9]
	v_mfma_f32_16x16x32_bf16 v[2:5], v[224:227], v[170:173], v[2:5]
	v_mfma_f32_16x16x32_bf16 v[54:57], v[220:223], v[142:145], v[54:57]
	v_mfma_f32_16x16x32_bf16 v[50:53], v[228:231], v[142:145], v[50:53]
	v_mfma_f32_16x16x32_bf16 v[38:41], v[220:223], v[150:153], v[38:41]
	v_mfma_f32_16x16x32_bf16 v[34:37], v[228:231], v[150:153], v[34:37]
	v_mfma_f32_16x16x32_bf16 v[22:25], v[220:223], v[166:169], v[22:25]
	v_mfma_f32_16x16x32_bf16 v[18:21], v[228:231], v[166:169], v[18:21]
	v_mfma_f32_16x16x32_bf16 v[6:9], v[220:223], v[184:187], v[6:9]
	s_barrier
	v_mfma_f32_16x16x32_bf16 v[2:5], v[228:231], v[184:187], v[2:5]
	s_add_i32 s52, 0, 0x18000
	v_add_u32_e32 v74, s52, v194
	ds_read_b128 v[58:61], v74
	ds_read_b128 v[62:65], v74 offset:1024
	ds_read_b128 v[70:73], v74 offset:2048
	ds_read_b128 v[74:77], v74 offset:3072
	s_add_u32 s44, s44, s38
	s_addc_u32 s45, s45, 0
	s_mov_b32 m0, s51
	v_lshl_add_u64 v[188:189], s[44:45], 0, v[0:1]
	ds_read_b128 v[138:141], v196 offset:32768
	ds_read_b128 v[142:145], v196 offset:33792
	ds_read_b128 v[146:149], v196 offset:34816
	ds_read_b128 v[150:153], v196 offset:35840
	ds_read_b128 v[162:165], v196 offset:36864
	ds_read_b128 v[166:169], v196 offset:37888
	ds_read_b128 v[170:173], v196 offset:38912
	ds_read_b128 v[184:187], v196 offset:39936
	global_load_lds_dwordx4 v[188:189], off
	v_lshl_add_u64 v[188:189], s[44:45], 0, v[174:175]
	s_mov_b32 m0, s56
	s_nop 0
	global_load_lds_dwordx4 v[188:189], off
	s_waitcnt lgkmcnt(8)
	s_barrier
	s_waitcnt lgkmcnt(0)
	v_mfma_f32_16x16x32_bf16 v[158:161], v[58:61], v[138:141], v[158:161]
	v_mfma_f32_16x16x32_bf16 v[154:157], v[70:73], v[138:141], v[154:157]
	v_mfma_f32_16x16x32_bf16 v[126:129], v[58:61], v[146:149], v[126:129]
	v_mfma_f32_16x16x32_bf16 v[122:125], v[70:73], v[146:149], v[122:125]
	v_mfma_f32_16x16x32_bf16 v[110:113], v[58:61], v[162:165], v[110:113]
	v_mfma_f32_16x16x32_bf16 v[106:109], v[70:73], v[162:165], v[106:109]
	v_mfma_f32_16x16x32_bf16 v[94:97], v[58:61], v[170:173], v[94:97]
	v_mfma_f32_16x16x32_bf16 v[90:93], v[70:73], v[170:173], v[90:93]
	v_mfma_f32_16x16x32_bf16 v[158:161], v[62:65], v[142:145], v[158:161]
	v_mfma_f32_16x16x32_bf16 v[154:157], v[74:77], v[142:145], v[154:157]
	v_mfma_f32_16x16x32_bf16 v[126:129], v[62:65], v[150:153], v[126:129]
	v_mfma_f32_16x16x32_bf16 v[122:125], v[74:77], v[150:153], v[122:125]
	v_mfma_f32_16x16x32_bf16 v[110:113], v[62:65], v[166:169], v[110:113]
	v_mfma_f32_16x16x32_bf16 v[106:109], v[74:77], v[166:169], v[106:109]
	v_mfma_f32_16x16x32_bf16 v[94:97], v[62:65], v[184:187], v[94:97]
	s_barrier
	v_mfma_f32_16x16x32_bf16 v[90:93], v[74:77], v[184:187], v[90:93]
	s_add_i32 s44, 0, 0x1c000
	s_add_i32 s45, s52, s20
	v_add_u32_e32 v197, s44, v194
	v_lshl_add_u64 v[192:193], v[192:193], 0, s[76:77]
	s_mov_b32 m0, s45
	ds_read_b128 v[188:191], v197
	ds_read_b128 v[220:223], v197 offset:1024
	ds_read_b128 v[224:227], v197 offset:2048
	ds_read_b128 v[228:231], v197 offset:3072
	global_load_lds_dwordx4 v[192:193], off
	v_lshl_add_u64 v[192:193], v[198:199], 0, s[76:77]
	s_add_i32 m0, s45, 0x2000
	s_nop 0
	global_load_lds_dwordx4 v[192:193], off
	s_barrier
; #define PG8_STAGE(bufoff, gbase, voff) do { _Pragma("unroll") for (int _i = 0; _i < 2; ++_i) \
;         __builtin_amdgcn_global_load_lds((const unsigned*)((const char*)(gbase) + (voff)[_i]), (LAS unsigned*)(lds + (bufoff) + ldsw + _i * 8192), 16, 0, 0); } while (0)
; #define PG8_LDA(dst, b, h) do { _Pragma("unroll") for (int m = 0; m < 4; ++m) _Pragma("unroll") for (int k = 0; k < 2; ++k) dst[m][k] = *(const LAS bf16x8*)(lds + PG8_SA(b, h) + aoff + m * 2048 + k * 1024); } while (0)
; #define PG8_LDB(dst, b, h) do { _Pragma("unroll") for (int n = 0; n < 2; ++n) _Pragma("unroll") for (int k = 0; k < 2; ++k) dst[n][k] = *(const LAS bf16x8*)(lds + PG8_SB(b, h) + boff + n * 2048 + k * 1024); } while (0)
; #define PG8_WAIT_V(n) asm volatile("s_waitcnt vmcnt(" #n ")" ::: "memory")
; #define PG8_WAIT_L(n) asm volatile("s_waitcnt lgkmcnt(" #n ")" ::: "memory")
; #define PG8_BAR __builtin_amdgcn_s_barrier()
; #define PG8_SCHED __builtin_amdgcn_sched_barrier(0)
;     template <int mode> __device__ __forceinline__ void run(const f32x4 (&acc)[2][2][4][2], const Unit& u, int wr, int wc, int fr, int fq, const LAS float* sc) const {
;     ...
;             const int col0 = u.pn * BM + wc * 32 + 8 * fq;
;             float sA = 1.f, sB = 1.f;
;             if (mode == 4) scales2(u, wr, fr, fq, sA, sB);
;             f32x4 bvv[4];
; #pragma unroll
;             for (int q = 0; q < 4; ++q) bvv[q] = (mode != 4 && bias) ? *(const f32x4*)(bias + col0 + (q >> 1) * HALF + (q & 1) * 4) : (f32x4){0.f, 0.f, 0.f, 0.f};
; template <int MODE, class EpiT, class Sched>
; __device__ __forceinline__ void gemm_phase(LAS unsigned char* lds, const Gemm g, const Sched& S, const EpiT& E) {
;     ...
;             PG8_WAIT_V(6); PG8_BAR; PG8_MMA(1, 1, At, B1); PG8_BAR;
;             PG8_LDB(B0, 1, 0); PG8_SCHED; PG8_LDA(At, 1, 0); PG8_STAGE(PG8_SA(0, 1), a2 + hstep, voffA);
;             PG8_WAIT_L(8); PG8_BAR; PG8_WAIT_L(0); PG8_MMA(0, 0, At, B0); PG8_BAR; PG8_SCHED;
;             PG8_LDB(B1, 1, 1); PG8_STAGE(PG8_SB(1, 0), b3, voffB);
;             PG8_BAR; PG8_WAIT_L(0); PG8_MMA(0, 1, At, B1); PG8_BAR;
;             PG8_LDA(At, 1, 1); PG8_STAGE(PG8_SA(1, 0), a3, voffA);
;             PG8_BAR; PG8_WAIT_L(0); PG8_MMA(1, 0, At, B0); PG8_BAR; PG8_SCHED;
;             PG8_STAGE(PG8_SB(1, 1), b3 + hstep, voffB);
;             PG8_WAIT_V(6); PG8_BAR; PG8_MMA(1, 1, At, B1); PG8_BAR;
	s_waitcnt lgkmcnt(0)
	v_mfma_f32_16x16x32_bf16 v[134:137], v[188:191], v[138:141], v[134:137]
	v_mfma_f32_16x16x32_bf16 v[130:133], v[224:227], v[138:141], v[130:133]
	v_mfma_f32_16x16x32_bf16 v[118:121], v[188:191], v[146:149], v[118:121]
	v_mfma_f32_16x16x32_bf16 v[114:117], v[224:227], v[146:149], v[114:117]
	v_mfma_f32_16x16x32_bf16 v[102:105], v[188:191], v[162:165], v[102:105]
	v_mfma_f32_16x16x32_bf16 v[98:101], v[224:227], v[162:165], v[98:101]
	v_mfma_f32_16x16x32_bf16 v[86:89], v[188:191], v[170:173], v[86:89]
	v_mfma_f32_16x16x32_bf16 v[82:85], v[224:227], v[170:173], v[82:85]
	v_mfma_f32_16x16x32_bf16 v[134:137], v[220:223], v[142:145], v[134:137]
	v_mfma_f32_16x16x32_bf16 v[130:133], v[228:231], v[142:145], v[130:133]
	v_mfma_f32_16x16x32_bf16 v[118:121], v[220:223], v[150:153], v[118:121]
	v_mfma_f32_16x16x32_bf16 v[114:117], v[228:231], v[150:153], v[114:117]
	v_mfma_f32_16x16x32_bf16 v[102:105], v[220:223], v[166:169], v[102:105]
	v_mfma_f32_16x16x32_bf16 v[98:101], v[228:231], v[166:169], v[98:101]
	v_mfma_f32_16x16x32_bf16 v[86:89], v[220:223], v[184:187], v[86:89]
	s_barrier
	v_mfma_f32_16x16x32_bf16 v[82:85], v[228:231], v[184:187], v[82:85]
	s_mov_b32 m0, s61
	v_lshl_add_u64 v[192:193], v[232:233], 0, s[76:77]
	ds_read_b128 v[138:141], v196 offset:49152
	ds_read_b128 v[142:145], v196 offset:50176
	ds_read_b128 v[146:149], v196 offset:51200
	ds_read_b128 v[150:153], v196 offset:52224
	ds_read_b128 v[162:165], v196 offset:53248
	ds_read_b128 v[166:169], v196 offset:54272
	ds_read_b128 v[170:173], v196 offset:55296
	ds_read_b128 v[184:187], v196 offset:56320
	global_load_lds_dwordx4 v[192:193], off
	v_lshl_add_u64 v[192:193], v[234:235], 0, s[76:77]
	s_mov_b32 m0, s74
	s_nop 0
	global_load_lds_dwordx4 v[192:193], off
	s_barrier
	s_waitcnt lgkmcnt(0)
	v_mfma_f32_16x16x32_bf16 v[78:81], v[58:61], v[138:141], v[78:81]
	v_mfma_f32_16x16x32_bf16 v[66:69], v[70:73], v[138:141], v[66:69]
	v_mfma_f32_16x16x32_bf16 v[46:49], v[58:61], v[146:149], v[46:49]
	v_mfma_f32_16x16x32_bf16 v[42:45], v[70:73], v[146:149], v[42:45]
	v_mfma_f32_16x16x32_bf16 v[30:33], v[58:61], v[162:165], v[30:33]
	v_mfma_f32_16x16x32_bf16 v[26:29], v[70:73], v[162:165], v[26:29]
	v_mfma_f32_16x16x32_bf16 v[14:17], v[58:61], v[170:173], v[14:17]
	v_mfma_f32_16x16x32_bf16 v[10:13], v[70:73], v[170:173], v[10:13]
	v_mfma_f32_16x16x32_bf16 v[78:81], v[62:65], v[142:145], v[78:81]
	v_mfma_f32_16x16x32_bf16 v[66:69], v[74:77], v[142:145], v[66:69]
	v_mfma_f32_16x16x32_bf16 v[46:49], v[62:65], v[150:153], v[46:49]
	v_mfma_f32_16x16x32_bf16 v[42:45], v[74:77], v[150:153], v[42:45]
	v_mfma_f32_16x16x32_bf16 v[30:33], v[62:65], v[166:169], v[30:33]
	v_mfma_f32_16x16x32_bf16 v[26:29], v[74:77], v[166:169], v[26:29]
	v_mfma_f32_16x16x32_bf16 v[14:17], v[62:65], v[184:187], v[14:17]
	s_barrier
	v_mfma_f32_16x16x32_bf16 v[10:13], v[74:77], v[184:187], v[10:13]
	s_add_i32 s44, s44, s20
	v_lshl_add_u64 v[58:59], v[236:237], 0, s[76:77]
	s_mov_b32 m0, s44
	s_nop 0
	global_load_lds_dwordx4 v[58:59], off
	v_lshl_add_u64 v[58:59], v[238:239], 0, s[76:77]
	s_add_i32 m0, s44, 0x2000
	s_nop 0
	global_load_lds_dwordx4 v[58:59], off
	s_waitcnt vmcnt(6)
	s_barrier
	v_mfma_f32_16x16x32_bf16 v[54:57], v[188:191], v[138:141], v[54:57]
	v_mfma_f32_16x16x32_bf16 v[50:53], v[224:227], v[138:141], v[50:53]
	v_mfma_f32_16x16x32_bf16 v[38:41], v[188:191], v[146:149], v[38:41]
	v_mfma_f32_16x16x32_bf16 v[34:37], v[224:227], v[146:149], v[34:37]
	v_mfma_f32_16x16x32_bf16 v[22:25], v[188:191], v[162:165], v[22:25]
	v_mfma_f32_16x16x32_bf16 v[18:21], v[224:227], v[162:165], v[18:21]
	v_mfma_f32_16x16x32_bf16 v[6:9], v[188:191], v[170:173], v[6:9]
	v_mfma_f32_16x16x32_bf16 v[2:5], v[224:227], v[170:173], v[2:5]
	v_mfma_f32_16x16x32_bf16 v[54:57], v[220:223], v[142:145], v[54:57]
	v_mfma_f32_16x16x32_bf16 v[50:53], v[228:231], v[142:145], v[50:53]
	v_mfma_f32_16x16x32_bf16 v[38:41], v[220:223], v[150:153], v[38:41]
	v_mfma_f32_16x16x32_bf16 v[34:37], v[228:231], v[150:153], v[34:37]
	v_mfma_f32_16x16x32_bf16 v[22:25], v[220:223], v[166:169], v[22:25]
	v_mfma_f32_16x16x32_bf16 v[18:21], v[228:231], v[166:169], v[18:21]
	v_mfma_f32_16x16x32_bf16 v[6:9], v[220:223], v[184:187], v[6:9]
	s_barrier
	v_mfma_f32_16x16x32_bf16 v[2:5], v[228:231], v[184:187], v[2:5]
	s_add_u32 s4, s4, 0x100
	s_addc_u32 s5, s5, 0
	s_add_u32 s89, s89, 0x100
	s_addc_u32 s90, s90, 0
	s_cmp_ge_u32 vcc_lo, s60
	s_mov_b32 s44, vcc_lo
	s_cbranch_scc0 .LBB0_195
	v_lshl_or_b32 v186, s24, 8, v195
	v_ashrrev_i32_e32 v187, 31, v186
	v_mov_b32_e32 v70, 0
	v_cndmask_b32_e64 v58, 0, 1, s[78:79]
	v_lshl_add_u64 v[138:139], v[186:187], 2, s[12:13]
	v_cmp_ne_u32_e64 s[44:45], 1, v58
	s_andn2_b64 vcc, exec, s[78:79]
	v_mov_b32_e32 v74, 0
	v_mov_b32_e32 v75, v70
	v_mov_b32_e32 v184, 0
	v_mov_b32_e32 v185, v70
	s_cbranch_vccnz .LBB0_198
	global_load_dwordx4 v[74:77], v[138:139], off
	s_waitcnt vmcnt(0)
	v_mov_b32_e32 v184, v76
	v_mov_b32_e32 v185, v77

; #define PG8_STAGE(bufoff, gbase, voff) do { _Pragma("unroll") for (int _i = 0; _i < 2; ++_i) \
;         __builtin_amdgcn_global_load_lds((const unsigned*)((const char*)(gbase) + (voff)[_i]), (LAS unsigned*)(lds + (bufoff) + ldsw + _i * 8192), 16, 0, 0); } while (0)
; #define PG8_LDA(dst, b, h) do { _Pragma("unroll") for (int m = 0; m < 4; ++m) _Pragma("unroll") for (int k = 0; k < 2; ++k) dst[m][k] = *(const LAS bf16x8*)(lds + PG8_SA(b, h) + aoff + m * 2048 + k * 1024); } while (0)
; #define PG8_LDB(dst, b, h) do { _Pragma("unroll") for (int n = 0; n < 2; ++n) _Pragma("unroll") for (int k = 0; k < 2; ++k) dst[n][k] = *(const LAS bf16x8*)(lds + PG8_SB(b, h) + boff + n * 2048 + k * 1024); } while (0)
; #define PG8_WAIT_V(n) asm volatile("s_waitcnt vmcnt(" #n ")" ::: "memory")
; #define PG8_WAIT_L(n) asm volatile("s_waitcnt lgkmcnt(" #n ")" ::: "memory")
; #define PG8_BAR __builtin_amdgcn_s_barrier()
; #define PG8_SCHED __builtin_amdgcn_sched_barrier(0)
; template <int MODE, class EpiT, class Sched>
; __device__ __forceinline__ void gemm_phase(LAS unsigned char* lds, const Gemm g, const Sched& S, const EpiT& E) {
;     ...
;             PG8_LDB(B0, 0, 0); PG8_SCHED; PG8_LDA(At, 0, 0); PG8_STAGE(PG8_SA(1, 1), a1 + hstep, voffA);
;             PG8_WAIT_L(8); PG8_BAR; PG8_WAIT_L(0); PG8_MMA(0, 0, At, B0); PG8_BAR; PG8_SCHED;
;             PG8_LDB(B1, 0, 1); PG8_STAGE(PG8_SB(0, 0), b2, voffB);
;             PG8_BAR; PG8_WAIT_L(0); PG8_MMA(0, 1, At, B1); PG8_BAR;
;             PG8_LDA(At, 0, 1); PG8_STAGE(PG8_SA(0, 0), a2, voffA);
;             PG8_BAR; PG8_WAIT_L(0); PG8_MMA(1, 0, At, B0); PG8_BAR; PG8_SCHED;
;             PG8_STAGE(PG8_SB(0, 1), b2 + hstep, voffB);
;             PG8_WAIT_V(6); PG8_BAR; PG8_MMA(1, 1, At, B1); PG8_BAR;
;             PG8_LDB(B0, 1, 0); PG8_SCHED; PG8_LDA(At, 1, 0); PG8_STAGE(PG8_SA(0, 1), a2 + hstep, voffA);
;             PG8_WAIT_L(8); PG8_BAR; PG8_WAIT_L(0); PG8_MMA(0, 0, At, B0); PG8_BAR; PG8_SCHED;
;             PG8_LDB(B1, 1, 1); PG8_STAGE(PG8_SB(1, 0), b3, voffB);
;             PG8_BAR; PG8_WAIT_L(0); PG8_MMA(0, 1, At, B1); PG8_BAR;
;             PG8_LDA(At, 1, 1); PG8_STAGE(PG8_SA(1, 0), a3, voffA);
;             PG8_BAR; PG8_WAIT_L(0); PG8_MMA(1, 0, At, B0); PG8_BAR; PG8_SCHED;
;             PG8_STAGE(PG8_SB(1, 1), b3 + hstep, voffB);
;             PG8_WAIT_V(6); PG8_BAR; PG8_MMA(1, 1, At, B1); PG8_BAR;
.LBB0_236:
	s_add_i32 s44, s34, 2
	s_add_u32 s38, s28, 0x80
	s_addc_u32 s35, s29, 0
	s_add_i32 s45, 0, 0x10000
	v_add_u32_e32 v136, s45, v139
	ds_read_b128 v[142:145], v136
	ds_read_b128 v[146:149], v136 offset:1024
	ds_read_b128 v[150:153], v136 offset:2048
	ds_read_b128 v[154:157], v136 offset:3072
	s_cmp_eq_u32 s52, s34
	s_cselect_b32 s34, s4, s38
	s_cselect_b32 s35, s5, s35
	s_cselect_b32 s39, s11, s43
	s_cselect_b32 s38, s10, s42
	v_lshl_add_u64 v[136:137], s[28:29], 0, v[132:133]
	s_add_i32 m0, s22, 0xc000
	ds_read_b128 v[158:161], v141
	ds_read_b128 v[162:165], v141 offset:1024
	ds_read_b128 v[166:169], v141 offset:2048
	ds_read_b128 v[170:173], v141 offset:3072
	ds_read_b128 v[174:177], v141 offset:4096
	ds_read_b128 v[182:185], v141 offset:5120
	ds_read_b128 v[186:189], v141 offset:6144
	ds_read_b128 v[190:193], v141 offset:7168
	global_load_lds_dwordx4 v[136:137], off
	v_lshl_add_u64 v[136:137], s[28:29], 0, v[134:135]
	s_add_i32 m0, s22, 0xe000
	s_nop 0
	global_load_lds_dwordx4 v[136:137], off
	s_waitcnt lgkmcnt(8)
	s_barrier
	s_waitcnt lgkmcnt(0)
	v_mfma_f32_16x16x32_bf16 v[126:129], v[142:145], v[158:161], v[126:129]
	v_mfma_f32_16x16x32_bf16 v[122:125], v[150:153], v[158:161], v[122:125]
	v_mfma_f32_16x16x32_bf16 v[118:121], v[142:145], v[166:169], v[118:121]
	v_mfma_f32_16x16x32_bf16 v[110:113], v[150:153], v[166:169], v[110:113]
	v_mfma_f32_16x16x32_bf16 v[102:105], v[142:145], v[174:177], v[102:105]
	v_mfma_f32_16x16x32_bf16 v[94:97], v[150:153], v[174:177], v[94:97]
	v_mfma_f32_16x16x32_bf16 v[86:89], v[142:145], v[186:189], v[86:89]
	v_mfma_f32_16x16x32_bf16 v[78:81], v[150:153], v[186:189], v[78:81]
	v_mfma_f32_16x16x32_bf16 v[126:129], v[146:149], v[162:165], v[126:129]
	v_mfma_f32_16x16x32_bf16 v[122:125], v[154:157], v[162:165], v[122:125]
	v_mfma_f32_16x16x32_bf16 v[118:121], v[146:149], v[170:173], v[118:121]
	v_mfma_f32_16x16x32_bf16 v[110:113], v[154:157], v[170:173], v[110:113]
	v_mfma_f32_16x16x32_bf16 v[102:105], v[146:149], v[182:185], v[102:105]
	v_mfma_f32_16x16x32_bf16 v[94:97], v[154:157], v[182:185], v[94:97]
	v_mfma_f32_16x16x32_bf16 v[86:89], v[146:149], v[190:193], v[86:89]
	s_barrier
	v_mfma_f32_16x16x32_bf16 v[78:81], v[154:157], v[190:193], v[78:81]
	s_add_i32 s58, 0, 0x14000
	v_add_u32_e32 v136, s58, v139
	s_add_i32 s45, s45, s9
	ds_read_b128 v[194:197], v136
	ds_read_b128 v[220:223], v136 offset:1024
	ds_read_b128 v[224:227], v136 offset:2048
	ds_read_b128 v[228:231], v136 offset:3072
	v_lshl_add_u64 v[136:137], s[38:39], 0, v[0:1]
	s_mov_b32 m0, s45
	v_lshl_add_u64 v[198:199], s[38:39], 0, v[130:131]
	global_load_lds_dwordx4 v[136:137], off
	s_add_i32 m0, s45, 0x2000
	s_nop 0
	global_load_lds_dwordx4 v[198:199], off
	s_barrier
	s_waitcnt lgkmcnt(0)
	v_mfma_f32_16x16x32_bf16 v[114:117], v[194:197], v[158:161], v[114:117]
	v_mfma_f32_16x16x32_bf16 v[106:109], v[224:227], v[158:161], v[106:109]
	v_mfma_f32_16x16x32_bf16 v[98:101], v[194:197], v[166:169], v[98:101]
	v_mfma_f32_16x16x32_bf16 v[90:93], v[224:227], v[166:169], v[90:93]
	v_mfma_f32_16x16x32_bf16 v[82:85], v[194:197], v[174:177], v[82:85]
	v_mfma_f32_16x16x32_bf16 v[74:77], v[224:227], v[174:177], v[74:77]
	v_mfma_f32_16x16x32_bf16 v[70:73], v[194:197], v[186:189], v[70:73]
	v_mfma_f32_16x16x32_bf16 v[66:69], v[224:227], v[186:189], v[66:69]
	v_mfma_f32_16x16x32_bf16 v[114:117], v[220:223], v[162:165], v[114:117]
	v_mfma_f32_16x16x32_bf16 v[106:109], v[228:231], v[162:165], v[106:109]
	v_mfma_f32_16x16x32_bf16 v[98:101], v[220:223], v[170:173], v[98:101]
	v_mfma_f32_16x16x32_bf16 v[90:93], v[228:231], v[170:173], v[90:93]
	v_mfma_f32_16x16x32_bf16 v[82:85], v[220:223], v[182:185], v[82:85]
	v_mfma_f32_16x16x32_bf16 v[74:77], v[228:231], v[182:185], v[74:77]
	v_mfma_f32_16x16x32_bf16 v[70:73], v[220:223], v[190:193], v[70:73]
	s_barrier
	v_mfma_f32_16x16x32_bf16 v[66:69], v[228:231], v[190:193], v[66:69]
	s_mov_b32 m0, s22
	v_lshl_add_u64 v[232:233], s[34:35], 0, v[0:1]
	ds_read_b128 v[158:161], v141 offset:16384
	ds_read_b128 v[162:165], v141 offset:17408
	ds_read_b128 v[166:169], v141 offset:18432
	ds_read_b128 v[170:173], v141 offset:19456
	ds_read_b128 v[174:177], v141 offset:20480
	ds_read_b128 v[182:185], v141 offset:21504
	ds_read_b128 v[186:189], v141 offset:22528
	ds_read_b128 v[190:193], v141 offset:23552
	global_load_lds_dwordx4 v[232:233], off
	v_lshl_add_u64 v[234:235], s[34:35], 0, v[130:131]
	s_mov_b32 m0, s23
	s_nop 0
	global_load_lds_dwordx4 v[234:235], off
	s_barrier
	s_waitcnt lgkmcnt(0)
	v_mfma_f32_16x16x32_bf16 v[62:65], v[142:145], v[158:161], v[62:65]
	v_mfma_f32_16x16x32_bf16 v[58:61], v[150:153], v[158:161], v[58:61]
	v_mfma_f32_16x16x32_bf16 v[54:57], v[142:145], v[166:169], v[54:57]
	v_mfma_f32_16x16x32_bf16 v[46:49], v[150:153], v[166:169], v[46:49]
	v_mfma_f32_16x16x32_bf16 v[38:41], v[142:145], v[174:177], v[38:41]
	v_mfma_f32_16x16x32_bf16 v[30:33], v[150:153], v[174:177], v[30:33]
	v_mfma_f32_16x16x32_bf16 v[22:25], v[142:145], v[186:189], v[22:25]
	v_mfma_f32_16x16x32_bf16 v[14:17], v[150:153], v[186:189], v[14:17]
	v_mfma_f32_16x16x32_bf16 v[62:65], v[146:149], v[162:165], v[62:65]
	v_mfma_f32_16x16x32_bf16 v[58:61], v[154:157], v[162:165], v[58:61]
	v_mfma_f32_16x16x32_bf16 v[54:57], v[146:149], v[170:173], v[54:57]
	v_mfma_f32_16x16x32_bf16 v[46:49], v[154:157], v[170:173], v[46:49]
	v_mfma_f32_16x16x32_bf16 v[38:41], v[146:149], v[182:185], v[38:41]
	v_mfma_f32_16x16x32_bf16 v[30:33], v[154:157], v[182:185], v[30:33]
	v_mfma_f32_16x16x32_bf16 v[22:25], v[146:149], v[190:193], v[22:25]
	s_barrier
; #define PG8_STAGE(bufoff, gbase, voff) do { _Pragma("unroll") for (int _i = 0; _i < 2; ++_i) \
;         __builtin_amdgcn_global_load_lds((const unsigned*)((const char*)(gbase) + (voff)[_i]), (LAS unsigned*)(lds + (bufoff) + ldsw + _i * 8192), 16, 0, 0); } while (0)
; #define PG8_LDA(dst, b, h) do { _Pragma("unroll") for (int m = 0; m < 4; ++m) _Pragma("unroll") for (int k = 0; k < 2; ++k) dst[m][k] = *(const LAS bf16x8*)(lds + PG8_SA(b, h) + aoff + m * 2048 + k * 1024); } while (0)
; #define PG8_LDB(dst, b, h) do { _Pragma("unroll") for (int n = 0; n < 2; ++n) _Pragma("unroll") for (int k = 0; k < 2; ++k) dst[n][k] = *(const LAS bf16x8*)(lds + PG8_SB(b, h) + boff + n * 2048 + k * 1024); } while (0)
; #define PG8_WAIT_V(n) asm volatile("s_waitcnt vmcnt(" #n ")" ::: "memory")
; #define PG8_WAIT_L(n) asm volatile("s_waitcnt lgkmcnt(" #n ")" ::: "memory")
; #define PG8_BAR __builtin_amdgcn_s_barrier()
; #define PG8_SCHED __builtin_amdgcn_sched_barrier(0)
; template <int MODE, class EpiT, class Sched>
; __device__ __forceinline__ void gemm_phase(LAS unsigned char* lds, const Gemm g, const Sched& S, const EpiT& E) {
;     ...
;             PG8_LDB(B0, 0, 0); PG8_SCHED; PG8_LDA(At, 0, 0); PG8_STAGE(PG8_SA(1, 1), a1 + hstep, voffA);
;             PG8_WAIT_L(8); PG8_BAR; PG8_WAIT_L(0); PG8_MMA(0, 0, At, B0); PG8_BAR; PG8_SCHED;
;             PG8_LDB(B1, 0, 1); PG8_STAGE(PG8_SB(0, 0), b2, voffB);
;             PG8_BAR; PG8_WAIT_L(0); PG8_MMA(0, 1, At, B1); PG8_BAR;
;             PG8_LDA(At, 0, 1); PG8_STAGE(PG8_SA(0, 0), a2, voffA);
;             PG8_BAR; PG8_WAIT_L(0); PG8_MMA(1, 0, At, B0); PG8_BAR; PG8_SCHED;
;             PG8_STAGE(PG8_SB(0, 1), b2 + hstep, voffB);
;             PG8_WAIT_V(6); PG8_BAR; PG8_MMA(1, 1, At, B1); PG8_BAR;
;             PG8_LDB(B0, 1, 0); PG8_SCHED; PG8_LDA(At, 1, 0); PG8_STAGE(PG8_SA(0, 1), a2 + hstep, voffA);
;             PG8_WAIT_L(8); PG8_BAR; PG8_WAIT_L(0); PG8_MMA(0, 0, At, B0); PG8_BAR; PG8_SCHED;
;             PG8_LDB(B1, 1, 1); PG8_STAGE(PG8_SB(1, 0), b3, voffB);
;             PG8_BAR; PG8_WAIT_L(0); PG8_MMA(0, 1, At, B1); PG8_BAR;
;             PG8_LDA(At, 1, 1); PG8_STAGE(PG8_SA(1, 0), a3, voffA);
;             PG8_BAR; PG8_WAIT_L(0); PG8_MMA(1, 0, At, B0); PG8_BAR; PG8_SCHED;
;             PG8_STAGE(PG8_SB(1, 1), b3 + hstep, voffB);
;             PG8_WAIT_V(6); PG8_BAR; PG8_MMA(1, 1, At, B1); PG8_BAR;
	v_mfma_f32_16x16x32_bf16 v[14:17], v[154:157], v[190:193], v[14:17]
	s_add_u32 s38, s38, s24
	s_addc_u32 s39, s39, 0
	s_add_i32 s45, s58, s9
	v_lshl_add_u64 v[236:237], s[38:39], 0, v[0:1]
	s_mov_b32 m0, s45
	v_lshl_add_u64 v[238:239], s[38:39], 0, v[130:131]
	global_load_lds_dwordx4 v[236:237], off
	s_add_i32 m0, s45, 0x2000
	s_nop 0
	global_load_lds_dwordx4 v[238:239], off
	s_waitcnt vmcnt(6)
	s_barrier
	v_mfma_f32_16x16x32_bf16 v[50:53], v[194:197], v[158:161], v[50:53]
	v_mfma_f32_16x16x32_bf16 v[42:45], v[224:227], v[158:161], v[42:45]
	v_mfma_f32_16x16x32_bf16 v[34:37], v[194:197], v[166:169], v[34:37]
	v_mfma_f32_16x16x32_bf16 v[26:29], v[224:227], v[166:169], v[26:29]
	v_mfma_f32_16x16x32_bf16 v[18:21], v[194:197], v[174:177], v[18:21]
	v_mfma_f32_16x16x32_bf16 v[10:13], v[224:227], v[174:177], v[10:13]
	v_mfma_f32_16x16x32_bf16 v[6:9], v[194:197], v[186:189], v[6:9]
	v_mfma_f32_16x16x32_bf16 v[2:5], v[224:227], v[186:189], v[2:5]
	v_mfma_f32_16x16x32_bf16 v[50:53], v[220:223], v[162:165], v[50:53]
	v_mfma_f32_16x16x32_bf16 v[42:45], v[228:231], v[162:165], v[42:45]
	v_mfma_f32_16x16x32_bf16 v[34:37], v[220:223], v[170:173], v[34:37]
	v_mfma_f32_16x16x32_bf16 v[26:29], v[228:231], v[170:173], v[26:29]
	v_mfma_f32_16x16x32_bf16 v[18:21], v[220:223], v[182:185], v[18:21]
	v_mfma_f32_16x16x32_bf16 v[10:13], v[228:231], v[182:185], v[10:13]
	v_mfma_f32_16x16x32_bf16 v[6:9], v[220:223], v[190:193], v[6:9]
	s_barrier
	v_mfma_f32_16x16x32_bf16 v[2:5], v[228:231], v[190:193], v[2:5]
	s_add_i32 s38, 0, 0x18000
	v_add_u32_e32 v154, s38, v139
	ds_read_b128 v[142:145], v154
	ds_read_b128 v[146:149], v154 offset:1024
	ds_read_b128 v[150:153], v154 offset:2048
	ds_read_b128 v[154:157], v154 offset:3072
	s_add_u32 s34, s34, s24
	s_addc_u32 s35, s35, 0
	s_mov_b32 m0, s30
	v_lshl_add_u64 v[194:195], s[34:35], 0, v[0:1]
	ds_read_b128 v[158:161], v141 offset:32768
	ds_read_b128 v[162:165], v141 offset:33792
	ds_read_b128 v[166:169], v141 offset:34816
	ds_read_b128 v[170:173], v141 offset:35840
	ds_read_b128 v[174:177], v141 offset:36864
	ds_read_b128 v[182:185], v141 offset:37888
	ds_read_b128 v[186:189], v141 offset:38912
	ds_read_b128 v[190:193], v141 offset:39936
	global_load_lds_dwordx4 v[194:195], off
	v_lshl_add_u64 v[194:195], s[34:35], 0, v[130:131]
	s_mov_b32 m0, s46
	s_nop 0
	global_load_lds_dwordx4 v[194:195], off
	s_waitcnt lgkmcnt(8)
	s_barrier
	s_waitcnt lgkmcnt(0)
	v_mfma_f32_16x16x32_bf16 v[126:129], v[142:145], v[158:161], v[126:129]
	v_mfma_f32_16x16x32_bf16 v[122:125], v[150:153], v[158:161], v[122:125]
	v_mfma_f32_16x16x32_bf16 v[118:121], v[142:145], v[166:169], v[118:121]
	v_mfma_f32_16x16x32_bf16 v[110:113], v[150:153], v[166:169], v[110:113]
	v_mfma_f32_16x16x32_bf16 v[102:105], v[142:145], v[174:177], v[102:105]
	v_mfma_f32_16x16x32_bf16 v[94:97], v[150:153], v[174:177], v[94:97]
	v_mfma_f32_16x16x32_bf16 v[86:89], v[142:145], v[186:189], v[86:89]
	v_mfma_f32_16x16x32_bf16 v[78:81], v[150:153], v[186:189], v[78:81]
	v_mfma_f32_16x16x32_bf16 v[126:129], v[146:149], v[162:165], v[126:129]
	v_mfma_f32_16x16x32_bf16 v[122:125], v[154:157], v[162:165], v[122:125]
	v_mfma_f32_16x16x32_bf16 v[118:121], v[146:149], v[170:173], v[118:121]
	v_mfma_f32_16x16x32_bf16 v[110:113], v[154:157], v[170:173], v[110:113]
	v_mfma_f32_16x16x32_bf16 v[102:105], v[146:149], v[182:185], v[102:105]
	v_mfma_f32_16x16x32_bf16 v[94:97], v[154:157], v[182:185], v[94:97]
	v_mfma_f32_16x16x32_bf16 v[86:89], v[146:149], v[190:193], v[86:89]
	s_barrier
	v_mfma_f32_16x16x32_bf16 v[78:81], v[154:157], v[190:193], v[78:81]
	s_add_i32 s34, 0, 0x1c000
	s_add_i32 s35, s38, s9
	v_add_u32_e32 v181, s34, v139
	v_lshl_add_u64 v[136:137], v[136:137], 0, s[76:77]
	s_mov_b32 m0, s35
	ds_read_b128 v[194:197], v181
	ds_read_b128 v[220:223], v181 offset:1024
	ds_read_b128 v[224:227], v181 offset:2048
	ds_read_b128 v[228:231], v181 offset:3072
	global_load_lds_dwordx4 v[136:137], off
	v_lshl_add_u64 v[136:137], v[198:199], 0, s[76:77]
	s_add_i32 m0, s35, 0x2000
	s_nop 0
	global_load_lds_dwordx4 v[136:137], off
	s_barrier
	s_waitcnt lgkmcnt(0)
	v_mfma_f32_16x16x32_bf16 v[114:117], v[194:197], v[158:161], v[114:117]
	v_mfma_f32_16x16x32_bf16 v[106:109], v[224:227], v[158:161], v[106:109]
	v_mfma_f32_16x16x32_bf16 v[98:101], v[194:197], v[166:169], v[98:101]
	v_mfma_f32_16x16x32_bf16 v[90:93], v[224:227], v[166:169], v[90:93]
	v_mfma_f32_16x16x32_bf16 v[82:85], v[194:197], v[174:177], v[82:85]
	v_mfma_f32_16x16x32_bf16 v[74:77], v[224:227], v[174:177], v[74:77]
	v_mfma_f32_16x16x32_bf16 v[70:73], v[194:197], v[186:189], v[70:73]
	v_mfma_f32_16x16x32_bf16 v[66:69], v[224:227], v[186:189], v[66:69]
	v_mfma_f32_16x16x32_bf16 v[114:117], v[220:223], v[162:165], v[114:117]
	v_mfma_f32_16x16x32_bf16 v[106:109], v[228:231], v[162:165], v[106:109]
	v_mfma_f32_16x16x32_bf16 v[98:101], v[220:223], v[170:173], v[98:101]
	v_mfma_f32_16x16x32_bf16 v[90:93], v[228:231], v[170:173], v[90:93]
	v_mfma_f32_16x16x32_bf16 v[82:85], v[220:223], v[182:185], v[82:85]
	v_mfma_f32_16x16x32_bf16 v[74:77], v[228:231], v[182:185], v[74:77]
	v_mfma_f32_16x16x32_bf16 v[70:73], v[220:223], v[190:193], v[70:73]
	s_barrier
	v_mfma_f32_16x16x32_bf16 v[66:69], v[228:231], v[190:193], v[66:69]
	s_mov_b32 m0, s50
	v_lshl_add_u64 v[136:137], v[232:233], 0, s[76:77]
	ds_read_b128 v[158:161], v141 offset:49152
	ds_read_b128 v[162:165], v141 offset:50176
	ds_read_b128 v[166:169], v141 offset:51200
	ds_read_b128 v[170:173], v141 offset:52224
	ds_read_b128 v[174:177], v141 offset:53248
	ds_read_b128 v[182:185], v141 offset:54272
	ds_read_b128 v[186:189], v141 offset:55296
	ds_read_b128 v[190:193], v141 offset:56320
	global_load_lds_dwordx4 v[136:137], off
	v_lshl_add_u64 v[136:137], v[234:235], 0, s[76:77]
	s_mov_b32 m0, s51
	s_nop 0
	global_load_lds_dwordx4 v[136:137], off
	s_barrier
; #define PG8_STAGE(bufoff, gbase, voff) do { _Pragma("unroll") for (int _i = 0; _i < 2; ++_i) \
;         __builtin_amdgcn_global_load_lds((const unsigned*)((const char*)(gbase) + (voff)[_i]), (LAS unsigned*)(lds + (bufoff) + ldsw + _i * 8192), 16, 0, 0); } while (0)
; #define PG8_LDA(dst, b, h) do { _Pragma("unroll") for (int m = 0; m < 4; ++m) _Pragma("unroll") for (int k = 0; k < 2; ++k) dst[m][k] = *(const LAS bf16x8*)(lds + PG8_SA(b, h) + aoff + m * 2048 + k * 1024); } while (0)
; #define PG8_LDB(dst, b, h) do { _Pragma("unroll") for (int n = 0; n < 2; ++n) _Pragma("unroll") for (int k = 0; k < 2; ++k) dst[n][k] = *(const LAS bf16x8*)(lds + PG8_SB(b, h) + boff + n * 2048 + k * 1024); } while (0)
; #define PG8_MMA(ai, bj, At, Bt) do { __builtin_amdgcn_s_setprio(1); _Pragma("unroll") for (int m = 0; m < 4; ++m) _Pragma("unroll") for (int n = 0; n < 2; ++n) _Pragma("unroll") for (int k = 0; k < 2; ++k) \
;         acc[ai][bj][m][n] = __builtin_amdgcn_mfma_f32_16x16x32_bf16(Bt[n][k], At[m][k], acc[ai][bj][m][n], 0, 0, 0); __builtin_amdgcn_s_setprio(0); } while (0)
; #define PG8_WAIT_V(n) asm volatile("s_waitcnt vmcnt(" #n ")" ::: "memory")
; #define PG8_WAIT_L(n) asm volatile("s_waitcnt lgkmcnt(" #n ")" ::: "memory")
; #define PG8_BAR __builtin_amdgcn_s_barrier()
; #define PG8_SCHED __builtin_amdgcn_sched_barrier(0)
; template <int MODE, class EpiT, class Sched>
; __device__ __forceinline__ void gemm_phase(LAS unsigned char* lds, const Gemm g, const Sched& S, const EpiT& E) {
;     ...
;             PG8_WAIT_V(6); PG8_BAR; PG8_MMA(1, 1, At, B1); PG8_BAR;
;             PG8_LDB(B0, 1, 0); PG8_SCHED; PG8_LDA(At, 1, 0); PG8_STAGE(PG8_SA(0, 1), a2 + hstep, voffA);
;             PG8_WAIT_L(8); PG8_BAR; PG8_WAIT_L(0); PG8_MMA(0, 0, At, B0); PG8_BAR; PG8_SCHED;
;             PG8_LDB(B1, 1, 1); PG8_STAGE(PG8_SB(1, 0), b3, voffB);
;             PG8_BAR; PG8_WAIT_L(0); PG8_MMA(0, 1, At, B1); PG8_BAR;
;             PG8_LDA(At, 1, 1); PG8_STAGE(PG8_SA(1, 0), a3, voffA);
;             PG8_BAR; PG8_WAIT_L(0); PG8_MMA(1, 0, At, B0); PG8_BAR; PG8_SCHED;
;             PG8_STAGE(PG8_SB(1, 1), b3 + hstep, voffB);
;             PG8_WAIT_V(6); PG8_BAR; PG8_MMA(1, 1, At, B1); PG8_BAR;
	s_waitcnt lgkmcnt(0)
	v_mfma_f32_16x16x32_bf16 v[62:65], v[142:145], v[158:161], v[62:65]
	v_mfma_f32_16x16x32_bf16 v[58:61], v[150:153], v[158:161], v[58:61]
	v_mfma_f32_16x16x32_bf16 v[54:57], v[142:145], v[166:169], v[54:57]
	v_mfma_f32_16x16x32_bf16 v[46:49], v[150:153], v[166:169], v[46:49]
	v_mfma_f32_16x16x32_bf16 v[38:41], v[142:145], v[174:177], v[38:41]
	v_mfma_f32_16x16x32_bf16 v[30:33], v[150:153], v[174:177], v[30:33]
	v_mfma_f32_16x16x32_bf16 v[22:25], v[142:145], v[186:189], v[22:25]
	v_mfma_f32_16x16x32_bf16 v[14:17], v[150:153], v[186:189], v[14:17]
	v_mfma_f32_16x16x32_bf16 v[62:65], v[146:149], v[162:165], v[62:65]
	v_mfma_f32_16x16x32_bf16 v[58:61], v[154:157], v[162:165], v[58:61]
	v_mfma_f32_16x16x32_bf16 v[54:57], v[146:149], v[170:173], v[54:57]
	v_mfma_f32_16x16x32_bf16 v[46:49], v[154:157], v[170:173], v[46:49]
	v_mfma_f32_16x16x32_bf16 v[38:41], v[146:149], v[182:185], v[38:41]
	v_mfma_f32_16x16x32_bf16 v[30:33], v[154:157], v[182:185], v[30:33]
	v_mfma_f32_16x16x32_bf16 v[22:25], v[146:149], v[190:193], v[22:25]
	s_barrier
	v_mfma_f32_16x16x32_bf16 v[14:17], v[154:157], v[190:193], v[14:17]
	s_add_i32 s34, s34, s9
	v_lshl_add_u64 v[136:137], v[236:237], 0, s[76:77]
	s_mov_b32 m0, s34
	s_nop 0
	global_load_lds_dwordx4 v[136:137], off
	v_lshl_add_u64 v[136:137], v[238:239], 0, s[76:77]
	s_add_i32 m0, s34, 0x2000
	s_nop 0
	global_load_lds_dwordx4 v[136:137], off
	s_waitcnt vmcnt(6)
	s_barrier
	v_mfma_f32_16x16x32_bf16 v[50:53], v[194:197], v[158:161], v[50:53]
	v_mfma_f32_16x16x32_bf16 v[42:45], v[224:227], v[158:161], v[42:45]
	v_mfma_f32_16x16x32_bf16 v[34:37], v[194:197], v[166:169], v[34:37]
	v_mfma_f32_16x16x32_bf16 v[26:29], v[224:227], v[166:169], v[26:29]
	v_mfma_f32_16x16x32_bf16 v[18:21], v[194:197], v[174:177], v[18:21]
	v_mfma_f32_16x16x32_bf16 v[10:13], v[224:227], v[174:177], v[10:13]
	v_mfma_f32_16x16x32_bf16 v[6:9], v[194:197], v[186:189], v[6:9]
	v_mfma_f32_16x16x32_bf16 v[2:5], v[224:227], v[186:189], v[2:5]
	v_mfma_f32_16x16x32_bf16 v[50:53], v[220:223], v[162:165], v[50:53]
	v_mfma_f32_16x16x32_bf16 v[42:45], v[228:231], v[162:165], v[42:45]
	v_mfma_f32_16x16x32_bf16 v[34:37], v[220:223], v[170:173], v[34:37]
	v_mfma_f32_16x16x32_bf16 v[26:29], v[228:231], v[170:173], v[26:29]
	v_mfma_f32_16x16x32_bf16 v[18:21], v[220:223], v[182:185], v[18:21]
	v_mfma_f32_16x16x32_bf16 v[10:13], v[228:231], v[182:185], v[10:13]
	v_mfma_f32_16x16x32_bf16 v[6:9], v[220:223], v[190:193], v[6:9]
	s_barrier
	v_mfma_f32_16x16x32_bf16 v[2:5], v[228:231], v[190:193], v[2:5]
	s_add_u32 s28, s28, 0x100
	s_addc_u32 s29, s29, 0
	s_add_u32 s42, s42, 0x100
	s_addc_u32 s43, s43, 0
	s_cmp_ge_u32 s44, s47
	s_mov_b32 s34, s44
	s_cbranch_scc0 .LBB0_236
; __device__ __forceinline__ unsigned pk2(float lo, float hi) { unsigned r; asm volatile("v_cvt_pk_bf16_f32 %0, %1, %2" : "=v"(r) : "v"(lo), "v"(hi)); return r; }
; #define PG8_WAIT_V(n) asm volatile("s_waitcnt vmcnt(" #n ")" ::: "memory")
; #define PG8_BAR __builtin_amdgcn_s_barrier()
;     template <int mode> __device__ __forceinline__ void run(const f32x4 (&acc)[2][2][4][2], const Unit& u, int wr, int wc, int fr, int fq, const LAS float* sc) const {
;     ...
;         } else if (mode == 2) {
;             const int col0 = u.pn * BM + wc * 32 + 8 * fq;
; #pragma unroll
;             for (int ai = 0; ai < 2; ++ai)
; #pragma unroll
;                 for (int m = 0; m < 4; ++m) {
;                     bf16_t* rowp = ob + (size_t)(row0 + ai * HALF + m * 16) * D + col0;
; #pragma unroll
;                     for (int bj = 0; bj < 2; ++bj) {
;                         const f32x4 v0 = acc[ai][bj][m][0], v1 = acc[ai][bj][m][1];
;                         u32x4 w; w.x = pk2(v0[0], v0[1]); w.y = pk2(v0[2], v0[3]); w.z = pk2(v1[0], v1[1]); w.w = pk2(v1[2], v1[3]);
;                         *(u32x4*)(rowp + bj * HALF) = w;
;                     }
;                 }
; template <int MODE, class EpiT, class Sched>
; __device__ __forceinline__ void gemm_phase(LAS unsigned char* lds, const Gemm g, const Sched& S, const EpiT& E) {
;     ...
;     PG8_WAIT_V(0);
;     if (wr == 0) PG8_BAR;
;     PG8_BAR;
	v_lshl_add_u32 v142, s56, 8, v138
	v_lshl_or_b32 v136, s61, 8, v140
	v_ashrrev_i32_e32 v143, 31, v142
	v_ashrrev_i32_e32 v137, 31, v136
	v_lshlrev_b64 v[144:145], 11, v[142:143]
	v_lshl_add_u64 v[144:145], s[6:7], 0, v[144:145]
	v_lshlrev_b64 v[146:147], 1, v[136:137]
	v_lshl_add_u64 v[136:137], v[144:145], 0, v[146:147]
	v_cvt_pk_bf16_f32 v126, v126, v127
	v_cvt_pk_bf16_f32 v127, v128, v129
	v_cvt_pk_bf16_f32 v128, v122, v123
	v_cvt_pk_bf16_f32 v129, v124, v125
	global_store_dwordx4 v[136:137], v[126:129], off
	v_cvt_pk_bf16_f32 v114, v114, v115
	v_cvt_pk_bf16_f32 v115, v116, v117
	v_cvt_pk_bf16_f32 v116, v106, v107
	v_or_b32_e32 v106, 16, v142
	v_ashrrev_i32_e32 v107, 31, v106
	v_lshlrev_b64 v[106:107], 11, v[106:107]
	v_lshl_add_u64 v[106:107], s[6:7], 0, v[106:107]
	v_cvt_pk_bf16_f32 v117, v108, v109
	global_store_dwordx4 v[136:137], v[114:117], off offset:256
	s_mov_b64 s[28:29], 0x40000
	s_mov_b32 s61, s57
	v_lshl_add_u64 v[114:115], v[106:107], 0, v[146:147]
	v_cvt_pk_bf16_f32 v106, v118, v119
	v_cvt_pk_bf16_f32 v107, v120, v121
	v_cvt_pk_bf16_f32 v108, v110, v111
	v_cvt_pk_bf16_f32 v109, v112, v113
	global_store_dwordx4 v[114:115], v[106:109], off
	v_cvt_pk_bf16_f32 v98, v98, v99
	v_cvt_pk_bf16_f32 v99, v100, v101
	v_cvt_pk_bf16_f32 v100, v90, v91
	v_or_b32_e32 v90, 32, v142
	v_ashrrev_i32_e32 v91, 31, v90
	v_lshlrev_b64 v[90:91], 11, v[90:91]
	v_lshl_add_u64 v[90:91], s[6:7], 0, v[90:91]
	v_cvt_pk_bf16_f32 v101, v92, v93
	global_store_dwordx4 v[114:115], v[98:101], off offset:256
	s_mov_b32 s56, s60
	s_mov_b64 s[34:35], s[10:11]
	v_lshl_add_u64 v[98:99], v[90:91], 0, v[146:147]
	v_cvt_pk_bf16_f32 v90, v102, v103
	v_cvt_pk_bf16_f32 v91, v104, v105
	v_cvt_pk_bf16_f32 v92, v94, v95
	v_cvt_pk_bf16_f32 v93, v96, v97
	global_store_dwordx4 v[98:99], v[90:93], off
	v_cvt_pk_bf16_f32 v82, v82, v83
	v_cvt_pk_bf16_f32 v83, v84, v85
	v_cvt_pk_bf16_f32 v84, v74, v75
	v_or_b32_e32 v74, 48, v142
	v_ashrrev_i32_e32 v75, 31, v74
	v_lshlrev_b64 v[74:75], 11, v[74:75]
	v_lshl_add_u64 v[74:75], s[6:7], 0, v[74:75]
	v_cvt_pk_bf16_f32 v85, v76, v77
	global_store_dwordx4 v[98:99], v[82:85], off offset:256
	s_nop 1
	v_lshl_add_u64 v[82:83], v[74:75], 0, v[146:147]
	v_cvt_pk_bf16_f32 v74, v86, v87
	v_cvt_pk_bf16_f32 v75, v88, v89
	v_cvt_pk_bf16_f32 v76, v78, v79
	v_cvt_pk_bf16_f32 v77, v80, v81
	global_store_dwordx4 v[82:83], v[74:77], off
	v_cvt_pk_bf16_f32 v70, v70, v71
	v_cvt_pk_bf16_f32 v71, v72, v73
	v_cvt_pk_bf16_f32 v72, v66, v67
	v_cvt_pk_bf16_f32 v73, v68, v69
	global_store_dwordx4 v[82:83], v[70:73], off offset:256
	v_cvt_pk_bf16_f32 v62, v62, v63
	v_cvt_pk_bf16_f32 v63, v64, v65
	v_cvt_pk_bf16_f32 v64, v58, v59
	v_add_co_u32_e32 v58, vcc, s91, v136
	v_lshl_add_u64 v[66:67], v[136:137], 0, s[28:29]
	s_nop 0
	v_addc_co_u32_e32 v59, vcc, 0, v137, vcc
	v_cvt_pk_bf16_f32 v65, v60, v61
	global_store_dwordx4 v[58:59], v[62:65], off
	v_cvt_pk_bf16_f32 v50, v50, v51
	v_cvt_pk_bf16_f32 v51, v52, v53
	s_mov_b64 s[28:29], 0x48000
	v_cvt_pk_bf16_f32 v52, v42, v43
	v_cvt_pk_bf16_f32 v53, v44, v45
	global_store_dwordx4 v[66:67], v[50:53], off offset:256
	v_cvt_pk_bf16_f32 v42, v54, v55
	v_cvt_pk_bf16_f32 v43, v56, v57
	v_cvt_pk_bf16_f32 v44, v46, v47
	v_cvt_pk_bf16_f32 v45, v48, v49
	s_nop 1
	v_lshl_add_u64 v[50:51], v[136:137], 0, s[28:29]
	s_mov_b32 s28, 0x48000
	v_add_co_u32_e32 v46, vcc, s28, v136
	s_mov_b64 s[28:29], 0x50000
	s_nop 0
	v_addc_co_u32_e32 v47, vcc, 0, v137, vcc
	global_store_dwordx4 v[46:47], v[42:45], off
	v_cvt_pk_bf16_f32 v34, v34, v35
	v_cvt_pk_bf16_f32 v35, v36, v37
	v_cvt_pk_bf16_f32 v36, v26, v27
	v_cvt_pk_bf16_f32 v37, v28, v29
	global_store_dwordx4 v[50:51], v[34:37], off offset:256
	v_cvt_pk_bf16_f32 v26, v38, v39
	v_cvt_pk_bf16_f32 v27, v40, v41
	v_cvt_pk_bf16_f32 v28, v30, v31
	v_cvt_pk_bf16_f32 v29, v32, v33
	s_nop 1
	v_lshl_add_u64 v[34:35], v[136:137], 0, s[28:29]
	s_mov_b32 s28, 0x50000
	v_add_co_u32_e32 v30, vcc, s28, v136
	s_mov_b64 s[28:29], 0x58000
	s_nop 0
	v_addc_co_u32_e32 v31, vcc, 0, v137, vcc
	global_store_dwordx4 v[30:31], v[26:29], off
	v_cvt_pk_bf16_f32 v18, v18, v19
	v_cvt_pk_bf16_f32 v19, v20, v21
	v_cvt_pk_bf16_f32 v20, v10, v11
	v_cvt_pk_bf16_f32 v21, v12, v13
	global_store_dwordx4 v[34:35], v[18:21], off offset:256
	v_cvt_pk_bf16_f32 v10, v22, v23
	v_cvt_pk_bf16_f32 v11, v24, v25
	v_cvt_pk_bf16_f32 v12, v14, v15
	v_cvt_pk_bf16_f32 v13, v16, v17
	s_nop 1
	v_lshl_add_u64 v[18:19], v[136:137], 0, s[28:29]
	s_mov_b32 s28, 0x58000
	v_add_co_u32_e32 v14, vcc, s28, v136
	s_mov_b64 s[28:29], s[4:5]
	s_nop 0
	v_addc_co_u32_e32 v15, vcc, 0, v137, vcc
	s_and_b64 vcc, exec, s[40:41]
	global_store_dwordx4 v[14:15], v[10:13], off
	v_cvt_pk_bf16_f32 v6, v6, v7
	v_cvt_pk_bf16_f32 v7, v8, v9
	v_cvt_pk_bf16_f32 v8, v2, v3
	v_cvt_pk_bf16_f32 v9, v4, v5
	global_store_dwordx4 v[18:19], v[6:9], off offset:256
	s_cbranch_vccz .LBB0_229
	s_waitcnt vmcnt(0)
	v_readlane_b32 s46, v247, 49
	v_readlane_b32 s50, v246, 29
	v_readlane_b32 s56, v246, 31
	v_readlane_b32 s58, v246, 33
	v_readlane_b32 s60, v246, 35
	s_cmpk_gt_u32 s2, 0xff
	s_mov_b32 s52, 0x800000
	s_movk_i32 s53, 0x1000
	s_movk_i32 s23, 0x2000
	s_movk_i32 s30, 0x2840
	s_movk_i32 s42, 0x3000
	s_mov_b64 s[44:45], 0x1800
	v_readlane_b32 s47, v247, 50
	v_readlane_b32 s43, v247, 51
	v_readlane_b32 s51, v246, 30
	v_readlane_b32 s57, v246, 32
	v_readlane_b32 s59, v246, 34
	v_readlane_b32 s61, v246, 36
	s_cbranch_scc1 .LBB0_240
	s_barrier

; #define PG8_STAGE(bufoff, gbase, voff) do { _Pragma("unroll") for (int _i = 0; _i < 2; ++_i) \
;         __builtin_amdgcn_global_load_lds((const unsigned*)((const char*)(gbase) + (voff)[_i]), (LAS unsigned*)(lds + (bufoff) + ldsw + _i * 8192), 16, 0, 0); } while (0)
; #define PG8_LDA(dst, b, h) do { _Pragma("unroll") for (int m = 0; m < 4; ++m) _Pragma("unroll") for (int k = 0; k < 2; ++k) dst[m][k] = *(const LAS bf16x8*)(lds + PG8_SA(b, h) + aoff + m * 2048 + k * 1024); } while (0)
; #define PG8_LDB(dst, b, h) do { _Pragma("unroll") for (int n = 0; n < 2; ++n) _Pragma("unroll") for (int k = 0; k < 2; ++k) dst[n][k] = *(const LAS bf16x8*)(lds + PG8_SB(b, h) + boff + n * 2048 + k * 1024); } while (0)
; #define PG8_WAIT_V(n) asm volatile("s_waitcnt vmcnt(" #n ")" ::: "memory")
; #define PG8_WAIT_L(n) asm volatile("s_waitcnt lgkmcnt(" #n ")" ::: "memory")
; #define PG8_BAR __builtin_amdgcn_s_barrier()
; #define PG8_SCHED __builtin_amdgcn_sched_barrier(0)
; template <int MODE, class EpiT, class Sched>
; __device__ __forceinline__ void gemm_phase(LAS unsigned char* lds, const Gemm g, const Sched& S, const EpiT& E) {
;     ...
;             PG8_LDB(B0, 0, 0); PG8_SCHED; PG8_LDA(At, 0, 0); PG8_STAGE(PG8_SA(1, 1), a1 + hstep, voffA);
;             PG8_WAIT_L(8); PG8_BAR; PG8_WAIT_L(0); PG8_MMA(0, 0, At, B0); PG8_BAR; PG8_SCHED;
;             PG8_LDB(B1, 0, 1); PG8_STAGE(PG8_SB(0, 0), b2, voffB);
;             PG8_BAR; PG8_WAIT_L(0); PG8_MMA(0, 1, At, B1); PG8_BAR;
;             PG8_LDA(At, 0, 1); PG8_STAGE(PG8_SA(0, 0), a2, voffA);
;             PG8_BAR; PG8_WAIT_L(0); PG8_MMA(1, 0, At, B0); PG8_BAR; PG8_SCHED;
;             PG8_STAGE(PG8_SB(0, 1), b2 + hstep, voffB);
;             PG8_WAIT_V(6); PG8_BAR; PG8_MMA(1, 1, At, B1); PG8_BAR;
;             PG8_LDB(B0, 1, 0); PG8_SCHED; PG8_LDA(At, 1, 0); PG8_STAGE(PG8_SA(0, 1), a2 + hstep, voffA);
;             PG8_WAIT_L(8); PG8_BAR; PG8_WAIT_L(0); PG8_MMA(0, 0, At, B0); PG8_BAR; PG8_SCHED;
;             PG8_LDB(B1, 1, 1); PG8_STAGE(PG8_SB(1, 0), b3, voffB);
;             PG8_BAR; PG8_WAIT_L(0); PG8_MMA(0, 1, At, B1); PG8_BAR;
;             PG8_LDA(At, 1, 1); PG8_STAGE(PG8_SA(1, 0), a3, voffA);
;             PG8_BAR; PG8_WAIT_L(0); PG8_MMA(1, 0, At, B0); PG8_BAR; PG8_SCHED;
;             PG8_STAGE(PG8_SB(1, 1), b3 + hstep, voffB);
;             PG8_WAIT_V(6); PG8_BAR; PG8_MMA(1, 1, At, B1); PG8_BAR;
.LBB0_280:
	s_add_i32 s68, s46, 2
	s_add_u32 s52, s10, s44
	s_addc_u32 s47, s11, s45
	s_add_u32 s58, s4, s44
	s_addc_u32 s53, s5, s45
	s_add_i32 s59, 0, 0x10000
	v_add_u32_e32 v152, s59, v157
	ds_read_b128 v[134:137], v152
	ds_read_b128 v[138:141], v152 offset:1024
	ds_read_b128 v[142:145], v152 offset:2048
	ds_read_b128 v[152:155], v152 offset:3072
	s_cmp_eq_u32 s60, s46
	s_cselect_b32 s46, s34, s52
	s_cselect_b32 s47, s35, s47
	s_cselect_b32 s53, s39, s53
	s_cselect_b32 s52, s38, s58
	v_lshl_add_u64 v[198:199], s[10:11], 0, v[132:133]
	s_add_i32 m0, s30, 0xc000
	ds_read_b128 v[162:165], v160
	ds_read_b128 v[166:169], v160 offset:1024
	ds_read_b128 v[170:173], v160 offset:2048
	ds_read_b128 v[174:177], v160 offset:3072
	ds_read_b128 v[182:185], v160 offset:4096
	ds_read_b128 v[186:189], v160 offset:5120
	ds_read_b128 v[190:193], v160 offset:6144
	ds_read_b128 v[194:197], v160 offset:7168
	global_load_lds_dwordx4 v[198:199], off
	v_lshl_add_u64 v[198:199], s[10:11], 0, v[130:131]
	s_add_i32 m0, s30, 0xe000
	s_nop 0
	global_load_lds_dwordx4 v[198:199], off
	s_waitcnt lgkmcnt(8)
	s_barrier
	s_waitcnt lgkmcnt(0)
	v_mfma_f32_16x16x32_bf16 v[126:129], v[134:137], v[162:165], v[126:129]
	v_mfma_f32_16x16x32_bf16 v[122:125], v[142:145], v[162:165], v[122:125]
	v_mfma_f32_16x16x32_bf16 v[118:121], v[134:137], v[170:173], v[118:121]
	v_mfma_f32_16x16x32_bf16 v[114:117], v[142:145], v[170:173], v[114:117]
	v_mfma_f32_16x16x32_bf16 v[110:113], v[134:137], v[182:185], v[110:113]
	v_mfma_f32_16x16x32_bf16 v[106:109], v[142:145], v[182:185], v[106:109]
	v_mfma_f32_16x16x32_bf16 v[102:105], v[134:137], v[190:193], v[102:105]
	v_mfma_f32_16x16x32_bf16 v[98:101], v[142:145], v[190:193], v[98:101]
	v_mfma_f32_16x16x32_bf16 v[126:129], v[138:141], v[166:169], v[126:129]
	v_mfma_f32_16x16x32_bf16 v[122:125], v[152:155], v[166:169], v[122:125]
	v_mfma_f32_16x16x32_bf16 v[118:121], v[138:141], v[174:177], v[118:121]
	v_mfma_f32_16x16x32_bf16 v[114:117], v[152:155], v[174:177], v[114:117]
	v_mfma_f32_16x16x32_bf16 v[110:113], v[138:141], v[186:189], v[110:113]
	v_mfma_f32_16x16x32_bf16 v[106:109], v[152:155], v[186:189], v[106:109]
	v_mfma_f32_16x16x32_bf16 v[102:105], v[138:141], v[194:197], v[102:105]
	s_barrier
	v_mfma_f32_16x16x32_bf16 v[98:101], v[152:155], v[194:197], v[98:101]
	s_add_i32 s58, 0, 0x14000
	s_add_i32 s59, s59, s24
	v_add_u32_e32 v161, s58, v157
	v_lshl_add_u64 v[198:199], s[52:53], 0, v[0:1]
	s_mov_b32 m0, s59
	ds_read_b128 v[220:223], v161
	ds_read_b128 v[224:227], v161 offset:1024
	ds_read_b128 v[228:231], v161 offset:2048
	ds_read_b128 v[232:235], v161 offset:3072
	global_load_lds_dwordx4 v[198:199], off
	v_lshl_add_u64 v[236:237], s[52:53], 0, v[146:147]
	s_add_i32 m0, s59, 0x2000
	s_nop 0
	global_load_lds_dwordx4 v[236:237], off
	s_barrier
	s_waitcnt lgkmcnt(0)
	v_mfma_f32_16x16x32_bf16 v[94:97], v[220:223], v[162:165], v[94:97]
	v_mfma_f32_16x16x32_bf16 v[90:93], v[228:231], v[162:165], v[90:93]
	v_mfma_f32_16x16x32_bf16 v[86:89], v[220:223], v[170:173], v[86:89]
	v_mfma_f32_16x16x32_bf16 v[82:85], v[228:231], v[170:173], v[82:85]
	v_mfma_f32_16x16x32_bf16 v[78:81], v[220:223], v[182:185], v[78:81]
	v_mfma_f32_16x16x32_bf16 v[74:77], v[228:231], v[182:185], v[74:77]
	v_mfma_f32_16x16x32_bf16 v[70:73], v[220:223], v[190:193], v[70:73]
	v_mfma_f32_16x16x32_bf16 v[66:69], v[228:231], v[190:193], v[66:69]
	v_mfma_f32_16x16x32_bf16 v[94:97], v[224:227], v[166:169], v[94:97]
	v_mfma_f32_16x16x32_bf16 v[90:93], v[232:235], v[166:169], v[90:93]
	v_mfma_f32_16x16x32_bf16 v[86:89], v[224:227], v[174:177], v[86:89]
	v_mfma_f32_16x16x32_bf16 v[82:85], v[232:235], v[174:177], v[82:85]
	v_mfma_f32_16x16x32_bf16 v[78:81], v[224:227], v[186:189], v[78:81]
	v_mfma_f32_16x16x32_bf16 v[74:77], v[232:235], v[186:189], v[74:77]
	v_mfma_f32_16x16x32_bf16 v[70:73], v[224:227], v[194:197], v[70:73]
	s_barrier
	v_mfma_f32_16x16x32_bf16 v[66:69], v[232:235], v[194:197], v[66:69]
	s_mov_b32 m0, s30
	v_lshl_add_u64 v[238:239], s[46:47], 0, v[0:1]
	ds_read_b128 v[162:165], v160 offset:16384
	ds_read_b128 v[166:169], v160 offset:17408
	ds_read_b128 v[170:173], v160 offset:18432
	ds_read_b128 v[174:177], v160 offset:19456
	ds_read_b128 v[182:185], v160 offset:20480
	ds_read_b128 v[186:189], v160 offset:21504
	ds_read_b128 v[190:193], v160 offset:22528
	ds_read_b128 v[194:197], v160 offset:23552
	global_load_lds_dwordx4 v[238:239], off
	v_lshl_add_u64 v[240:241], s[46:47], 0, v[146:147]
	s_mov_b32 m0, s50
	s_nop 0
	global_load_lds_dwordx4 v[240:241], off
	s_barrier
	s_waitcnt lgkmcnt(0)
	v_mfma_f32_16x16x32_bf16 v[62:65], v[134:137], v[162:165], v[62:65]
	v_mfma_f32_16x16x32_bf16 v[58:61], v[142:145], v[162:165], v[58:61]
	v_mfma_f32_16x16x32_bf16 v[54:57], v[134:137], v[170:173], v[54:57]
	v_mfma_f32_16x16x32_bf16 v[50:53], v[142:145], v[170:173], v[50:53]
	v_mfma_f32_16x16x32_bf16 v[46:49], v[134:137], v[182:185], v[46:49]
	v_mfma_f32_16x16x32_bf16 v[42:45], v[142:145], v[182:185], v[42:45]
	v_mfma_f32_16x16x32_bf16 v[38:41], v[134:137], v[190:193], v[38:41]
	v_mfma_f32_16x16x32_bf16 v[34:37], v[142:145], v[190:193], v[34:37]
	v_mfma_f32_16x16x32_bf16 v[62:65], v[138:141], v[166:169], v[62:65]
	v_mfma_f32_16x16x32_bf16 v[58:61], v[152:155], v[166:169], v[58:61]
	v_mfma_f32_16x16x32_bf16 v[54:57], v[138:141], v[174:177], v[54:57]
	v_mfma_f32_16x16x32_bf16 v[50:53], v[152:155], v[174:177], v[50:53]
	v_mfma_f32_16x16x32_bf16 v[46:49], v[138:141], v[186:189], v[46:49]
	v_mfma_f32_16x16x32_bf16 v[42:45], v[152:155], v[186:189], v[42:45]
	v_mfma_f32_16x16x32_bf16 v[38:41], v[138:141], v[194:197], v[38:41]
	s_barrier
; #define PG8_STAGE(bufoff, gbase, voff) do { _Pragma("unroll") for (int _i = 0; _i < 2; ++_i) \
;         __builtin_amdgcn_global_load_lds((const unsigned*)((const char*)(gbase) + (voff)[_i]), (LAS unsigned*)(lds + (bufoff) + ldsw + _i * 8192), 16, 0, 0); } while (0)
; #define PG8_LDA(dst, b, h) do { _Pragma("unroll") for (int m = 0; m < 4; ++m) _Pragma("unroll") for (int k = 0; k < 2; ++k) dst[m][k] = *(const LAS bf16x8*)(lds + PG8_SA(b, h) + aoff + m * 2048 + k * 1024); } while (0)
; #define PG8_LDB(dst, b, h) do { _Pragma("unroll") for (int n = 0; n < 2; ++n) _Pragma("unroll") for (int k = 0; k < 2; ++k) dst[n][k] = *(const LAS bf16x8*)(lds + PG8_SB(b, h) + boff + n * 2048 + k * 1024); } while (0)
; #define PG8_WAIT_V(n) asm volatile("s_waitcnt vmcnt(" #n ")" ::: "memory")
; #define PG8_WAIT_L(n) asm volatile("s_waitcnt lgkmcnt(" #n ")" ::: "memory")
; #define PG8_BAR __builtin_amdgcn_s_barrier()
; #define PG8_SCHED __builtin_amdgcn_sched_barrier(0)
; template <int MODE, class EpiT, class Sched>
; __device__ __forceinline__ void gemm_phase(LAS unsigned char* lds, const Gemm g, const Sched& S, const EpiT& E) {
;     ...
;             PG8_LDB(B0, 0, 0); PG8_SCHED; PG8_LDA(At, 0, 0); PG8_STAGE(PG8_SA(1, 1), a1 + hstep, voffA);
;             PG8_WAIT_L(8); PG8_BAR; PG8_WAIT_L(0); PG8_MMA(0, 0, At, B0); PG8_BAR; PG8_SCHED;
;             PG8_LDB(B1, 0, 1); PG8_STAGE(PG8_SB(0, 0), b2, voffB);
;             PG8_BAR; PG8_WAIT_L(0); PG8_MMA(0, 1, At, B1); PG8_BAR;
;             PG8_LDA(At, 0, 1); PG8_STAGE(PG8_SA(0, 0), a2, voffA);
;             PG8_BAR; PG8_WAIT_L(0); PG8_MMA(1, 0, At, B0); PG8_BAR; PG8_SCHED;
;             PG8_STAGE(PG8_SB(0, 1), b2 + hstep, voffB);
;             PG8_WAIT_V(6); PG8_BAR; PG8_MMA(1, 1, At, B1); PG8_BAR;
;             PG8_LDB(B0, 1, 0); PG8_SCHED; PG8_LDA(At, 1, 0); PG8_STAGE(PG8_SA(0, 1), a2 + hstep, voffA);
;             PG8_WAIT_L(8); PG8_BAR; PG8_WAIT_L(0); PG8_MMA(0, 0, At, B0); PG8_BAR; PG8_SCHED;
;             PG8_LDB(B1, 1, 1); PG8_STAGE(PG8_SB(1, 0), b3, voffB);
;             PG8_BAR; PG8_WAIT_L(0); PG8_MMA(0, 1, At, B1); PG8_BAR;
;             PG8_LDA(At, 1, 1); PG8_STAGE(PG8_SA(1, 0), a3, voffA);
;             PG8_BAR; PG8_WAIT_L(0); PG8_MMA(1, 0, At, B0); PG8_BAR; PG8_SCHED;
;             PG8_STAGE(PG8_SB(1, 1), b3 + hstep, voffB);
;             PG8_WAIT_V(6); PG8_BAR; PG8_MMA(1, 1, At, B1); PG8_BAR;
	v_mfma_f32_16x16x32_bf16 v[34:37], v[152:155], v[194:197], v[34:37]
	s_add_u32 s52, s52, s22
	s_addc_u32 s53, s53, 0
	s_add_i32 s58, s58, s24
	v_lshl_add_u64 v[242:243], s[52:53], 0, v[0:1]
	s_mov_b32 m0, s58
	v_lshl_add_u64 v[244:245], s[52:53], 0, v[146:147]
	global_load_lds_dwordx4 v[242:243], off
	s_add_i32 m0, s58, 0x2000
	s_nop 0
	global_load_lds_dwordx4 v[244:245], off
	s_waitcnt vmcnt(6)
	s_barrier
	v_mfma_f32_16x16x32_bf16 v[30:33], v[220:223], v[162:165], v[30:33]
	v_mfma_f32_16x16x32_bf16 v[26:29], v[228:231], v[162:165], v[26:29]
	v_mfma_f32_16x16x32_bf16 v[22:25], v[220:223], v[170:173], v[22:25]
	v_mfma_f32_16x16x32_bf16 v[18:21], v[228:231], v[170:173], v[18:21]
	v_mfma_f32_16x16x32_bf16 v[14:17], v[220:223], v[182:185], v[14:17]
	v_mfma_f32_16x16x32_bf16 v[10:13], v[228:231], v[182:185], v[10:13]
	v_mfma_f32_16x16x32_bf16 v[6:9], v[220:223], v[190:193], v[6:9]
	v_mfma_f32_16x16x32_bf16 v[2:5], v[228:231], v[190:193], v[2:5]
	v_mfma_f32_16x16x32_bf16 v[30:33], v[224:227], v[166:169], v[30:33]
	v_mfma_f32_16x16x32_bf16 v[26:29], v[232:235], v[166:169], v[26:29]
	v_mfma_f32_16x16x32_bf16 v[22:25], v[224:227], v[174:177], v[22:25]
	v_mfma_f32_16x16x32_bf16 v[18:21], v[232:235], v[174:177], v[18:21]
	v_mfma_f32_16x16x32_bf16 v[14:17], v[224:227], v[186:189], v[14:17]
	v_mfma_f32_16x16x32_bf16 v[10:13], v[232:235], v[186:189], v[10:13]
	v_mfma_f32_16x16x32_bf16 v[6:9], v[224:227], v[194:197], v[6:9]
	s_barrier
	v_mfma_f32_16x16x32_bf16 v[2:5], v[232:235], v[194:197], v[2:5]
	s_add_i32 s52, 0, 0x18000
	v_add_u32_e32 v152, s52, v157
	ds_read_b128 v[134:137], v152
	ds_read_b128 v[138:141], v152 offset:1024
	ds_read_b128 v[142:145], v152 offset:2048
	ds_read_b128 v[152:155], v152 offset:3072
	s_add_u32 s46, s46, s22
	s_addc_u32 s47, s47, 0
	s_mov_b32 m0, s51
	v_lshl_add_u64 v[220:221], s[46:47], 0, v[0:1]
	ds_read_b128 v[162:165], v160 offset:32768
	ds_read_b128 v[166:169], v160 offset:33792
	ds_read_b128 v[170:173], v160 offset:34816
	ds_read_b128 v[174:177], v160 offset:35840
	ds_read_b128 v[182:185], v160 offset:36864
	ds_read_b128 v[186:189], v160 offset:37888
	ds_read_b128 v[190:193], v160 offset:38912
	ds_read_b128 v[194:197], v160 offset:39936
	global_load_lds_dwordx4 v[220:221], off
	v_lshl_add_u64 v[220:221], s[46:47], 0, v[146:147]
	s_mov_b32 m0, s54
	s_nop 0
	global_load_lds_dwordx4 v[220:221], off
	s_waitcnt lgkmcnt(8)
	s_barrier
	s_waitcnt lgkmcnt(0)
	v_mfma_f32_16x16x32_bf16 v[126:129], v[134:137], v[162:165], v[126:129]
	v_mfma_f32_16x16x32_bf16 v[122:125], v[142:145], v[162:165], v[122:125]
	v_mfma_f32_16x16x32_bf16 v[118:121], v[134:137], v[170:173], v[118:121]
	v_mfma_f32_16x16x32_bf16 v[114:117], v[142:145], v[170:173], v[114:117]
	v_mfma_f32_16x16x32_bf16 v[110:113], v[134:137], v[182:185], v[110:113]
	v_mfma_f32_16x16x32_bf16 v[106:109], v[142:145], v[182:185], v[106:109]
	v_mfma_f32_16x16x32_bf16 v[102:105], v[134:137], v[190:193], v[102:105]
	v_mfma_f32_16x16x32_bf16 v[98:101], v[142:145], v[190:193], v[98:101]
	v_mfma_f32_16x16x32_bf16 v[126:129], v[138:141], v[166:169], v[126:129]
	v_mfma_f32_16x16x32_bf16 v[122:125], v[152:155], v[166:169], v[122:125]
	v_mfma_f32_16x16x32_bf16 v[118:121], v[138:141], v[174:177], v[118:121]
	v_mfma_f32_16x16x32_bf16 v[114:117], v[152:155], v[174:177], v[114:117]
	v_mfma_f32_16x16x32_bf16 v[110:113], v[138:141], v[186:189], v[110:113]
	v_mfma_f32_16x16x32_bf16 v[106:109], v[152:155], v[186:189], v[106:109]
	v_mfma_f32_16x16x32_bf16 v[102:105], v[138:141], v[194:197], v[102:105]
	s_barrier
	v_mfma_f32_16x16x32_bf16 v[98:101], v[152:155], v[194:197], v[98:101]
	s_add_i32 s46, 0, 0x1c000
	s_add_i32 s47, s52, s24
	v_add_u32_e32 v161, s46, v157
	v_lshl_add_u64 v[198:199], v[198:199], 0, s[76:77]
	s_mov_b32 m0, s47
	ds_read_b128 v[220:223], v161
	ds_read_b128 v[224:227], v161 offset:1024
	ds_read_b128 v[228:231], v161 offset:2048
	ds_read_b128 v[232:235], v161 offset:3072
	global_load_lds_dwordx4 v[198:199], off
	v_lshl_add_u64 v[198:199], v[236:237], 0, s[76:77]
	s_add_i32 m0, s47, 0x2000
	s_nop 0
	global_load_lds_dwordx4 v[198:199], off
	s_barrier
; #define PG8_STAGE(bufoff, gbase, voff) do { _Pragma("unroll") for (int _i = 0; _i < 2; ++_i) \
;         __builtin_amdgcn_global_load_lds((const unsigned*)((const char*)(gbase) + (voff)[_i]), (LAS unsigned*)(lds + (bufoff) + ldsw + _i * 8192), 16, 0, 0); } while (0)
; #define PG8_LDA(dst, b, h) do { _Pragma("unroll") for (int m = 0; m < 4; ++m) _Pragma("unroll") for (int k = 0; k < 2; ++k) dst[m][k] = *(const LAS bf16x8*)(lds + PG8_SA(b, h) + aoff + m * 2048 + k * 1024); } while (0)
; #define PG8_LDB(dst, b, h) do { _Pragma("unroll") for (int n = 0; n < 2; ++n) _Pragma("unroll") for (int k = 0; k < 2; ++k) dst[n][k] = *(const LAS bf16x8*)(lds + PG8_SB(b, h) + boff + n * 2048 + k * 1024); } while (0)
; #define PG8_WAIT_V(n) asm volatile("s_waitcnt vmcnt(" #n ")" ::: "memory")
; #define PG8_WAIT_L(n) asm volatile("s_waitcnt lgkmcnt(" #n ")" ::: "memory")
; #define PG8_BAR __builtin_amdgcn_s_barrier()
; #define PG8_SCHED __builtin_amdgcn_sched_barrier(0)
;     template <int mode> __device__ __forceinline__ void run(const f32x4 (&acc)[2][2][4][2], const Unit& u, int wr, int wc, int fr, int fq, const LAS float* sc) const {
;     ...
;             const int col0 = u.pn * BM + wc * 32 + 8 * fq;
;             f32x4 bv[2][2];
; #pragma unroll
;             for (int bj = 0; bj < 2; ++bj)
; #pragma unroll
;                 for (int n = 0; n < 2; ++n) bv[bj][n] = bias ? *(const f32x4*)(bias + col0 + bj * HALF + 4 * n) : (f32x4){0.f, 0.f, 0.f, 0.f};
; template <int MODE, class EpiT, class Sched>
; __device__ __forceinline__ void gemm_phase(LAS unsigned char* lds, const Gemm g, const Sched& S, const EpiT& E) {
;     ...
;             PG8_WAIT_V(6); PG8_BAR; PG8_MMA(1, 1, At, B1); PG8_BAR;
;             PG8_LDB(B0, 1, 0); PG8_SCHED; PG8_LDA(At, 1, 0); PG8_STAGE(PG8_SA(0, 1), a2 + hstep, voffA);
;             PG8_WAIT_L(8); PG8_BAR; PG8_WAIT_L(0); PG8_MMA(0, 0, At, B0); PG8_BAR; PG8_SCHED;
;             PG8_LDB(B1, 1, 1); PG8_STAGE(PG8_SB(1, 0), b3, voffB);
;             PG8_BAR; PG8_WAIT_L(0); PG8_MMA(0, 1, At, B1); PG8_BAR;
;             PG8_LDA(At, 1, 1); PG8_STAGE(PG8_SA(1, 0), a3, voffA);
;             PG8_BAR; PG8_WAIT_L(0); PG8_MMA(1, 0, At, B0); PG8_BAR; PG8_SCHED;
;             PG8_STAGE(PG8_SB(1, 1), b3 + hstep, voffB);
;             PG8_WAIT_V(6); PG8_BAR; PG8_MMA(1, 1, At, B1); PG8_BAR;
	s_waitcnt lgkmcnt(0)
	v_mfma_f32_16x16x32_bf16 v[94:97], v[220:223], v[162:165], v[94:97]
	v_mfma_f32_16x16x32_bf16 v[90:93], v[228:231], v[162:165], v[90:93]
	v_mfma_f32_16x16x32_bf16 v[86:89], v[220:223], v[170:173], v[86:89]
	v_mfma_f32_16x16x32_bf16 v[82:85], v[228:231], v[170:173], v[82:85]
	v_mfma_f32_16x16x32_bf16 v[78:81], v[220:223], v[182:185], v[78:81]
	v_mfma_f32_16x16x32_bf16 v[74:77], v[228:231], v[182:185], v[74:77]
	v_mfma_f32_16x16x32_bf16 v[70:73], v[220:223], v[190:193], v[70:73]
	v_mfma_f32_16x16x32_bf16 v[66:69], v[228:231], v[190:193], v[66:69]
	v_mfma_f32_16x16x32_bf16 v[94:97], v[224:227], v[166:169], v[94:97]
	v_mfma_f32_16x16x32_bf16 v[90:93], v[232:235], v[166:169], v[90:93]
	v_mfma_f32_16x16x32_bf16 v[86:89], v[224:227], v[174:177], v[86:89]
	v_mfma_f32_16x16x32_bf16 v[82:85], v[232:235], v[174:177], v[82:85]
	v_mfma_f32_16x16x32_bf16 v[78:81], v[224:227], v[186:189], v[78:81]
	v_mfma_f32_16x16x32_bf16 v[74:77], v[232:235], v[186:189], v[74:77]
	v_mfma_f32_16x16x32_bf16 v[70:73], v[224:227], v[194:197], v[70:73]
	s_barrier
	v_mfma_f32_16x16x32_bf16 v[66:69], v[232:235], v[194:197], v[66:69]
	s_mov_b32 m0, s56
	v_lshl_add_u64 v[198:199], v[238:239], 0, s[76:77]
	ds_read_b128 v[162:165], v160 offset:49152
	ds_read_b128 v[166:169], v160 offset:50176
	ds_read_b128 v[170:173], v160 offset:51200
	ds_read_b128 v[174:177], v160 offset:52224
	ds_read_b128 v[182:185], v160 offset:53248
	ds_read_b128 v[186:189], v160 offset:54272
	ds_read_b128 v[190:193], v160 offset:55296
	ds_read_b128 v[194:197], v160 offset:56320
	global_load_lds_dwordx4 v[198:199], off
	v_lshl_add_u64 v[198:199], v[240:241], 0, s[76:77]
	s_mov_b32 m0, s57
	s_nop 0
	global_load_lds_dwordx4 v[198:199], off
	s_barrier
	s_waitcnt lgkmcnt(0)
	v_mfma_f32_16x16x32_bf16 v[62:65], v[134:137], v[162:165], v[62:65]
	v_mfma_f32_16x16x32_bf16 v[58:61], v[142:145], v[162:165], v[58:61]
	v_mfma_f32_16x16x32_bf16 v[54:57], v[134:137], v[170:173], v[54:57]
	v_mfma_f32_16x16x32_bf16 v[50:53], v[142:145], v[170:173], v[50:53]
	v_mfma_f32_16x16x32_bf16 v[46:49], v[134:137], v[182:185], v[46:49]
	v_mfma_f32_16x16x32_bf16 v[42:45], v[142:145], v[182:185], v[42:45]
	v_mfma_f32_16x16x32_bf16 v[38:41], v[134:137], v[190:193], v[38:41]
	v_mfma_f32_16x16x32_bf16 v[34:37], v[142:145], v[190:193], v[34:37]
	v_mfma_f32_16x16x32_bf16 v[62:65], v[138:141], v[166:169], v[62:65]
	v_mfma_f32_16x16x32_bf16 v[58:61], v[152:155], v[166:169], v[58:61]
	v_mfma_f32_16x16x32_bf16 v[54:57], v[138:141], v[174:177], v[54:57]
	v_mfma_f32_16x16x32_bf16 v[50:53], v[152:155], v[174:177], v[50:53]
	v_mfma_f32_16x16x32_bf16 v[46:49], v[138:141], v[186:189], v[46:49]
	v_mfma_f32_16x16x32_bf16 v[42:45], v[152:155], v[186:189], v[42:45]
	v_mfma_f32_16x16x32_bf16 v[38:41], v[138:141], v[194:197], v[38:41]
	s_barrier
	v_mfma_f32_16x16x32_bf16 v[34:37], v[152:155], v[194:197], v[34:37]
	s_add_i32 s46, s46, s24
	v_lshl_add_u64 v[134:135], v[242:243], 0, s[76:77]
	s_mov_b32 m0, s46
	s_nop 0
	global_load_lds_dwordx4 v[134:135], off
	v_lshl_add_u64 v[134:135], v[244:245], 0, s[76:77]
	s_add_i32 m0, s46, 0x2000
	s_nop 0
	global_load_lds_dwordx4 v[134:135], off
	s_waitcnt vmcnt(6)
	s_barrier
	v_mfma_f32_16x16x32_bf16 v[30:33], v[220:223], v[162:165], v[30:33]
	v_mfma_f32_16x16x32_bf16 v[26:29], v[228:231], v[162:165], v[26:29]
	v_mfma_f32_16x16x32_bf16 v[22:25], v[220:223], v[170:173], v[22:25]
	v_mfma_f32_16x16x32_bf16 v[18:21], v[228:231], v[170:173], v[18:21]
	v_mfma_f32_16x16x32_bf16 v[14:17], v[220:223], v[182:185], v[14:17]
	v_mfma_f32_16x16x32_bf16 v[10:13], v[228:231], v[182:185], v[10:13]
	v_mfma_f32_16x16x32_bf16 v[6:9], v[220:223], v[190:193], v[6:9]
	v_mfma_f32_16x16x32_bf16 v[2:5], v[228:231], v[190:193], v[2:5]
	v_mfma_f32_16x16x32_bf16 v[30:33], v[224:227], v[166:169], v[30:33]
	v_mfma_f32_16x16x32_bf16 v[26:29], v[232:235], v[166:169], v[26:29]
	v_mfma_f32_16x16x32_bf16 v[22:25], v[224:227], v[174:177], v[22:25]
	v_mfma_f32_16x16x32_bf16 v[18:21], v[232:235], v[174:177], v[18:21]
	v_mfma_f32_16x16x32_bf16 v[14:17], v[224:227], v[186:189], v[14:17]
	v_mfma_f32_16x16x32_bf16 v[10:13], v[232:235], v[186:189], v[10:13]
	v_mfma_f32_16x16x32_bf16 v[6:9], v[224:227], v[194:197], v[6:9]
	s_barrier
	v_mfma_f32_16x16x32_bf16 v[2:5], v[232:235], v[194:197], v[2:5]
	s_add_u32 s44, s44, 0x100
	s_addc_u32 s45, s45, 0
	v_lshl_add_u64 v[132:133], v[132:133], 0, s[80:81]
	v_lshl_add_u64 v[130:131], v[130:131], 0, s[80:81]
	s_cmp_ge_u32 s68, s55
	s_mov_b32 s46, s68
	s_cbranch_scc0 .LBB0_280
	v_lshl_or_b32 v152, s3, 8, v159
	v_ashrrev_i32_e32 v153, 31, v152
	v_cndmask_b32_e64 v131, 0, 1, s[28:29]
	v_lshl_add_u64 v[154:155], v[152:153], 2, s[12:13]
	v_mov_b32_e32 v130, 0
	v_cmp_ne_u32_e64 s[44:45], 1, v131
	s_andn2_b64 vcc, exec, s[28:29]
	v_mov_b32_e32 v134, 0
	v_mov_b32_e32 v135, 0
	v_mov_b32_e32 v136, 0
	v_mov_b32_e32 v137, 0
	s_cbranch_vccnz .LBB0_283
	global_load_dwordx4 v[134:137], v[154:155], off

; #define PG8_STAGE(bufoff, gbase, voff) do { _Pragma("unroll") for (int _i = 0; _i < 2; ++_i) \
;         __builtin_amdgcn_global_load_lds((const unsigned*)((const char*)(gbase) + (voff)[_i]), (LAS unsigned*)(lds + (bufoff) + ldsw + _i * 8192), 16, 0, 0); } while (0)
; #define PG8_LDA(dst, b, h) do { _Pragma("unroll") for (int m = 0; m < 4; ++m) _Pragma("unroll") for (int k = 0; k < 2; ++k) dst[m][k] = *(const LAS bf16x8*)(lds + PG8_SA(b, h) + aoff + m * 2048 + k * 1024); } while (0)
; #define PG8_LDB(dst, b, h) do { _Pragma("unroll") for (int n = 0; n < 2; ++n) _Pragma("unroll") for (int k = 0; k < 2; ++k) dst[n][k] = *(const LAS bf16x8*)(lds + PG8_SB(b, h) + boff + n * 2048 + k * 1024); } while (0)
; #define PG8_MMA(ai, bj, At, Bt) do { __builtin_amdgcn_s_setprio(1); _Pragma("unroll") for (int m = 0; m < 4; ++m) _Pragma("unroll") for (int n = 0; n < 2; ++n) _Pragma("unroll") for (int k = 0; k < 2; ++k) \
;         acc[ai][bj][m][n] = __builtin_amdgcn_mfma_f32_16x16x32_bf16(Bt[n][k], At[m][k], acc[ai][bj][m][n], 0, 0, 0); __builtin_amdgcn_s_setprio(0); } while (0)
; #define PG8_WAIT_L(n) asm volatile("s_waitcnt lgkmcnt(" #n ")" ::: "memory")
; #define PG8_BAR __builtin_amdgcn_s_barrier()
; #define PG8_SCHED __builtin_amdgcn_sched_barrier(0)
; template <int MODE, class EpiT, class Sched>
; __device__ __forceinline__ void gemm_phase(LAS unsigned char* lds, const Gemm g, const Sched& S, const EpiT& E) {
;     ...
;         for (int t = 0; t < nt; t += 2) {
;             const bool last = (t == nt - 2);
;             const char* a1 = cA + (size_t)(t + 1) * kstep;
;             const char* a2 = last ? nA : cA + (size_t)(t + 2) * kstep; const char* b2 = last ? nB : cB + (size_t)(t + 2) * kstep;
;             const char* a3 = a2 + kstep; const char* b3 = b2 + kstep;
;             PG8_LDB(B0, 0, 0); PG8_SCHED; PG8_LDA(At, 0, 0); PG8_STAGE(PG8_SA(1, 1), a1 + hstep, voffA);
;             PG8_WAIT_L(8); PG8_BAR; PG8_WAIT_L(0); PG8_MMA(0, 0, At, B0); PG8_BAR; PG8_SCHED;
;             PG8_LDB(B1, 0, 1); PG8_STAGE(PG8_SB(0, 0), b2, voffB);
;             PG8_BAR; PG8_WAIT_L(0); PG8_MMA(0, 1, At, B1); PG8_BAR;
;             PG8_LDA(At, 0, 1); PG8_STAGE(PG8_SA(0, 0), a2, voffA);
;             PG8_BAR; PG8_WAIT_L(0); PG8_MMA(1, 0, At, B0); PG8_BAR; PG8_SCHED;
.LBB0_332:
	s_add_i32 s23, s22, 2
	s_add_u32 s30, s12, s4
	s_addc_u32 s38, s13, s5
	s_add_u32 s44, s10, s4
	s_addc_u32 s45, s11, s5
	s_add_i32 s58, 0, 0x10000
	v_add_u32_e32 v145, s58, v141
	ds_read_b128 v[146:149], v145
	ds_read_b128 v[150:153], v145 offset:1024
	ds_read_b128 v[154:157], v145 offset:2048
	ds_read_b128 v[158:161], v145 offset:3072
	s_cmp_eq_u32 s55, s22
	s_cselect_b32 s39, s29, s38
	s_cselect_b32 s38, s28, s30
	s_cselect_b32 s45, s35, s45
	s_cselect_b32 s44, s34, s44
	v_lshl_add_u64 v[198:199], s[12:13], 0, v[138:139]
	s_add_i32 m0, s47, 0xc000
	ds_read_b128 v[162:165], v144
	ds_read_b128 v[166:169], v144 offset:1024
	ds_read_b128 v[170:173], v144 offset:2048
	ds_read_b128 v[174:177], v144 offset:3072
	ds_read_b128 v[182:185], v144 offset:4096
	ds_read_b128 v[186:189], v144 offset:5120
	ds_read_b128 v[190:193], v144 offset:6144
	ds_read_b128 v[194:197], v144 offset:7168
	global_load_lds_dwordx4 v[198:199], off
	v_lshl_add_u64 v[198:199], s[12:13], 0, v[136:137]
	s_add_i32 m0, s47, 0xe000
	s_nop 0
	global_load_lds_dwordx4 v[198:199], off
	s_waitcnt lgkmcnt(8)
	s_barrier
	s_waitcnt lgkmcnt(0)
	v_mfma_f32_16x16x32_bf16 v[126:129], v[146:149], v[162:165], v[126:129]
	v_mfma_f32_16x16x32_bf16 v[122:125], v[154:157], v[162:165], v[122:125]
	v_mfma_f32_16x16x32_bf16 v[118:121], v[146:149], v[170:173], v[118:121]
	v_mfma_f32_16x16x32_bf16 v[114:117], v[154:157], v[170:173], v[114:117]
	v_mfma_f32_16x16x32_bf16 v[110:113], v[146:149], v[182:185], v[110:113]
	v_mfma_f32_16x16x32_bf16 v[106:109], v[154:157], v[182:185], v[106:109]
	v_mfma_f32_16x16x32_bf16 v[102:105], v[146:149], v[190:193], v[102:105]
	v_mfma_f32_16x16x32_bf16 v[98:101], v[154:157], v[190:193], v[98:101]
	v_mfma_f32_16x16x32_bf16 v[126:129], v[150:153], v[166:169], v[126:129]
	v_mfma_f32_16x16x32_bf16 v[122:125], v[158:161], v[166:169], v[122:125]
	v_mfma_f32_16x16x32_bf16 v[118:121], v[150:153], v[174:177], v[118:121]
	v_mfma_f32_16x16x32_bf16 v[114:117], v[158:161], v[174:177], v[114:117]
	v_mfma_f32_16x16x32_bf16 v[110:113], v[150:153], v[186:189], v[110:113]
	v_mfma_f32_16x16x32_bf16 v[106:109], v[158:161], v[186:189], v[106:109]
	v_mfma_f32_16x16x32_bf16 v[102:105], v[150:153], v[194:197], v[102:105]
	s_barrier
	v_mfma_f32_16x16x32_bf16 v[98:101], v[158:161], v[194:197], v[98:101]
	s_add_i32 s22, 0, 0x14000
	s_add_i32 s30, s58, s46
	v_add_u32_e32 v145, s22, v141
	v_lshl_add_u64 v[198:199], s[44:45], 0, v[0:1]
	s_mov_b32 m0, s30
	ds_read_b128 v[220:223], v145
	ds_read_b128 v[224:227], v145 offset:1024
	ds_read_b128 v[228:231], v145 offset:2048
	ds_read_b128 v[232:235], v145 offset:3072
	global_load_lds_dwordx4 v[198:199], off
	v_lshl_add_u64 v[236:237], s[44:45], 0, v[130:131]
	s_add_i32 m0, s30, 0x2000
	s_nop 0
	global_load_lds_dwordx4 v[236:237], off
	s_barrier
	s_waitcnt lgkmcnt(0)
	v_mfma_f32_16x16x32_bf16 v[94:97], v[220:223], v[162:165], v[94:97]
	v_mfma_f32_16x16x32_bf16 v[90:93], v[228:231], v[162:165], v[90:93]
	v_mfma_f32_16x16x32_bf16 v[86:89], v[220:223], v[170:173], v[86:89]
	v_mfma_f32_16x16x32_bf16 v[82:85], v[228:231], v[170:173], v[82:85]
	v_mfma_f32_16x16x32_bf16 v[78:81], v[220:223], v[182:185], v[78:81]
	v_mfma_f32_16x16x32_bf16 v[74:77], v[228:231], v[182:185], v[74:77]
	v_mfma_f32_16x16x32_bf16 v[70:73], v[220:223], v[190:193], v[70:73]
	v_mfma_f32_16x16x32_bf16 v[66:69], v[228:231], v[190:193], v[66:69]
	v_mfma_f32_16x16x32_bf16 v[94:97], v[224:227], v[166:169], v[94:97]
	v_mfma_f32_16x16x32_bf16 v[90:93], v[232:235], v[166:169], v[90:93]
	v_mfma_f32_16x16x32_bf16 v[86:89], v[224:227], v[174:177], v[86:89]
	v_mfma_f32_16x16x32_bf16 v[82:85], v[232:235], v[174:177], v[82:85]
	v_mfma_f32_16x16x32_bf16 v[78:81], v[224:227], v[186:189], v[78:81]
	v_mfma_f32_16x16x32_bf16 v[74:77], v[232:235], v[186:189], v[74:77]
	v_mfma_f32_16x16x32_bf16 v[70:73], v[224:227], v[194:197], v[70:73]
	s_barrier
	v_mfma_f32_16x16x32_bf16 v[66:69], v[232:235], v[194:197], v[66:69]
	s_mov_b32 m0, s47
	v_lshl_add_u64 v[238:239], s[38:39], 0, v[0:1]
	ds_read_b128 v[162:165], v144 offset:16384
	ds_read_b128 v[166:169], v144 offset:17408
	ds_read_b128 v[170:173], v144 offset:18432
	ds_read_b128 v[174:177], v144 offset:19456
	ds_read_b128 v[182:185], v144 offset:20480
	ds_read_b128 v[186:189], v144 offset:21504
	ds_read_b128 v[190:193], v144 offset:22528
	ds_read_b128 v[194:197], v144 offset:23552
	global_load_lds_dwordx4 v[238:239], off
	v_lshl_add_u64 v[240:241], s[38:39], 0, v[130:131]
	s_mov_b32 m0, s50
	s_nop 0
	global_load_lds_dwordx4 v[240:241], off
	s_barrier
	s_waitcnt lgkmcnt(0)
	v_mfma_f32_16x16x32_bf16 v[62:65], v[146:149], v[162:165], v[62:65]
	v_mfma_f32_16x16x32_bf16 v[58:61], v[154:157], v[162:165], v[58:61]
	v_mfma_f32_16x16x32_bf16 v[54:57], v[146:149], v[170:173], v[54:57]
	v_mfma_f32_16x16x32_bf16 v[50:53], v[154:157], v[170:173], v[50:53]
	v_mfma_f32_16x16x32_bf16 v[46:49], v[146:149], v[182:185], v[46:49]
	v_mfma_f32_16x16x32_bf16 v[42:45], v[154:157], v[182:185], v[42:45]
	v_mfma_f32_16x16x32_bf16 v[38:41], v[146:149], v[190:193], v[38:41]
	v_mfma_f32_16x16x32_bf16 v[34:37], v[154:157], v[190:193], v[34:37]
	v_mfma_f32_16x16x32_bf16 v[62:65], v[150:153], v[166:169], v[62:65]
	v_mfma_f32_16x16x32_bf16 v[58:61], v[158:161], v[166:169], v[58:61]
	v_mfma_f32_16x16x32_bf16 v[54:57], v[150:153], v[174:177], v[54:57]
	v_mfma_f32_16x16x32_bf16 v[50:53], v[158:161], v[174:177], v[50:53]
	v_mfma_f32_16x16x32_bf16 v[46:49], v[150:153], v[186:189], v[46:49]
	v_mfma_f32_16x16x32_bf16 v[42:45], v[158:161], v[186:189], v[42:45]
	v_mfma_f32_16x16x32_bf16 v[38:41], v[150:153], v[194:197], v[38:41]
	s_barrier
; #define PG8_STAGE(bufoff, gbase, voff) do { _Pragma("unroll") for (int _i = 0; _i < 2; ++_i) \
;         __builtin_amdgcn_global_load_lds((const unsigned*)((const char*)(gbase) + (voff)[_i]), (LAS unsigned*)(lds + (bufoff) + ldsw + _i * 8192), 16, 0, 0); } while (0)
; #define PG8_LDA(dst, b, h) do { _Pragma("unroll") for (int m = 0; m < 4; ++m) _Pragma("unroll") for (int k = 0; k < 2; ++k) dst[m][k] = *(const LAS bf16x8*)(lds + PG8_SA(b, h) + aoff + m * 2048 + k * 1024); } while (0)
; #define PG8_LDB(dst, b, h) do { _Pragma("unroll") for (int n = 0; n < 2; ++n) _Pragma("unroll") for (int k = 0; k < 2; ++k) dst[n][k] = *(const LAS bf16x8*)(lds + PG8_SB(b, h) + boff + n * 2048 + k * 1024); } while (0)
; #define PG8_MMA(ai, bj, At, Bt) do { __builtin_amdgcn_s_setprio(1); _Pragma("unroll") for (int m = 0; m < 4; ++m) _Pragma("unroll") for (int n = 0; n < 2; ++n) _Pragma("unroll") for (int k = 0; k < 2; ++k) \
;         acc[ai][bj][m][n] = __builtin_amdgcn_mfma_f32_16x16x32_bf16(Bt[n][k], At[m][k], acc[ai][bj][m][n], 0, 0, 0); __builtin_amdgcn_s_setprio(0); } while (0)
; #define PG8_WAIT_V(n) asm volatile("s_waitcnt vmcnt(" #n ")" ::: "memory")
; #define PG8_WAIT_L(n) asm volatile("s_waitcnt lgkmcnt(" #n ")" ::: "memory")
; #define PG8_BAR __builtin_amdgcn_s_barrier()
; #define PG8_SCHED __builtin_amdgcn_sched_barrier(0)
; template <int MODE, class EpiT, class Sched>
; __device__ __forceinline__ void gemm_phase(LAS unsigned char* lds, const Gemm g, const Sched& S, const EpiT& E) {
;     ...
;             PG8_BAR; PG8_WAIT_L(0); PG8_MMA(1, 0, At, B0); PG8_BAR; PG8_SCHED;
;             PG8_STAGE(PG8_SB(0, 1), b2 + hstep, voffB);
;             PG8_WAIT_V(6); PG8_BAR; PG8_MMA(1, 1, At, B1); PG8_BAR;
;             PG8_LDB(B0, 1, 0); PG8_SCHED; PG8_LDA(At, 1, 0); PG8_STAGE(PG8_SA(0, 1), a2 + hstep, voffA);
;             PG8_WAIT_L(8); PG8_BAR; PG8_WAIT_L(0); PG8_MMA(0, 0, At, B0); PG8_BAR; PG8_SCHED;
;             PG8_LDB(B1, 1, 1); PG8_STAGE(PG8_SB(1, 0), b3, voffB);
;             PG8_BAR; PG8_WAIT_L(0); PG8_MMA(0, 1, At, B1); PG8_BAR;
;             PG8_LDA(At, 1, 1); PG8_STAGE(PG8_SA(1, 0), a3, voffA);
;             PG8_BAR; PG8_WAIT_L(0); PG8_MMA(1, 0, At, B0); PG8_BAR; PG8_SCHED;
	v_mfma_f32_16x16x32_bf16 v[34:37], v[158:161], v[194:197], v[34:37]
	s_add_u32 s44, s44, s21
	s_addc_u32 s45, s45, 0
	s_add_i32 s22, s22, s46
	v_lshl_add_u64 v[242:243], s[44:45], 0, v[0:1]
	s_mov_b32 m0, s22
	v_lshl_add_u64 v[244:245], s[44:45], 0, v[130:131]
	global_load_lds_dwordx4 v[242:243], off
	s_add_i32 m0, s22, 0x2000
	s_nop 0
	global_load_lds_dwordx4 v[244:245], off
	s_waitcnt vmcnt(6)
	s_barrier
	v_mfma_f32_16x16x32_bf16 v[30:33], v[220:223], v[162:165], v[30:33]
	v_mfma_f32_16x16x32_bf16 v[26:29], v[228:231], v[162:165], v[26:29]
	v_mfma_f32_16x16x32_bf16 v[22:25], v[220:223], v[170:173], v[22:25]
	v_mfma_f32_16x16x32_bf16 v[18:21], v[228:231], v[170:173], v[18:21]
	v_mfma_f32_16x16x32_bf16 v[14:17], v[220:223], v[182:185], v[14:17]
	v_mfma_f32_16x16x32_bf16 v[10:13], v[228:231], v[182:185], v[10:13]
	v_mfma_f32_16x16x32_bf16 v[6:9], v[220:223], v[190:193], v[6:9]
	v_mfma_f32_16x16x32_bf16 v[2:5], v[228:231], v[190:193], v[2:5]
	v_mfma_f32_16x16x32_bf16 v[30:33], v[224:227], v[166:169], v[30:33]
	v_mfma_f32_16x16x32_bf16 v[26:29], v[232:235], v[166:169], v[26:29]
	v_mfma_f32_16x16x32_bf16 v[22:25], v[224:227], v[174:177], v[22:25]
	v_mfma_f32_16x16x32_bf16 v[18:21], v[232:235], v[174:177], v[18:21]
	v_mfma_f32_16x16x32_bf16 v[14:17], v[224:227], v[186:189], v[14:17]
	v_mfma_f32_16x16x32_bf16 v[10:13], v[232:235], v[186:189], v[10:13]
	v_mfma_f32_16x16x32_bf16 v[6:9], v[224:227], v[194:197], v[6:9]
	s_barrier
	v_mfma_f32_16x16x32_bf16 v[2:5], v[232:235], v[194:197], v[2:5]
	s_add_i32 s22, 0, 0x18000
	v_add_u32_e32 v145, s22, v141
	ds_read_b128 v[146:149], v145
	ds_read_b128 v[150:153], v145 offset:1024
	ds_read_b128 v[154:157], v145 offset:2048
	ds_read_b128 v[158:161], v145 offset:3072
	s_add_u32 s38, s38, s21
	s_addc_u32 s39, s39, 0
	s_mov_b32 m0, s51
	v_lshl_add_u64 v[220:221], s[38:39], 0, v[0:1]
	ds_read_b128 v[162:165], v144 offset:32768
	ds_read_b128 v[166:169], v144 offset:33792
	ds_read_b128 v[170:173], v144 offset:34816
	ds_read_b128 v[174:177], v144 offset:35840
	ds_read_b128 v[182:185], v144 offset:36864
	ds_read_b128 v[186:189], v144 offset:37888
	ds_read_b128 v[190:193], v144 offset:38912
	ds_read_b128 v[194:197], v144 offset:39936
	global_load_lds_dwordx4 v[220:221], off
	v_lshl_add_u64 v[220:221], s[38:39], 0, v[130:131]
	s_mov_b32 m0, s52
	s_nop 0
	global_load_lds_dwordx4 v[220:221], off
	s_waitcnt lgkmcnt(8)
	s_barrier
	s_waitcnt lgkmcnt(0)
	v_mfma_f32_16x16x32_bf16 v[126:129], v[146:149], v[162:165], v[126:129]
	v_mfma_f32_16x16x32_bf16 v[122:125], v[154:157], v[162:165], v[122:125]
	v_mfma_f32_16x16x32_bf16 v[118:121], v[146:149], v[170:173], v[118:121]
	v_mfma_f32_16x16x32_bf16 v[114:117], v[154:157], v[170:173], v[114:117]
	v_mfma_f32_16x16x32_bf16 v[110:113], v[146:149], v[182:185], v[110:113]
	v_mfma_f32_16x16x32_bf16 v[106:109], v[154:157], v[182:185], v[106:109]
	v_mfma_f32_16x16x32_bf16 v[102:105], v[146:149], v[190:193], v[102:105]
	v_mfma_f32_16x16x32_bf16 v[98:101], v[154:157], v[190:193], v[98:101]
	v_mfma_f32_16x16x32_bf16 v[126:129], v[150:153], v[166:169], v[126:129]
	v_mfma_f32_16x16x32_bf16 v[122:125], v[158:161], v[166:169], v[122:125]
	v_mfma_f32_16x16x32_bf16 v[118:121], v[150:153], v[174:177], v[118:121]
	v_mfma_f32_16x16x32_bf16 v[114:117], v[158:161], v[174:177], v[114:117]
	v_mfma_f32_16x16x32_bf16 v[110:113], v[150:153], v[186:189], v[110:113]
	v_mfma_f32_16x16x32_bf16 v[106:109], v[158:161], v[186:189], v[106:109]
	v_mfma_f32_16x16x32_bf16 v[102:105], v[150:153], v[194:197], v[102:105]
	s_barrier
	v_mfma_f32_16x16x32_bf16 v[98:101], v[158:161], v[194:197], v[98:101]
	s_add_i32 s30, 0, 0x1c000
	s_add_i32 s22, s22, s46
	v_add_u32_e32 v145, s30, v141
	v_lshl_add_u64 v[198:199], v[198:199], 0, s[76:77]
	s_mov_b32 m0, s22
	ds_read_b128 v[220:223], v145
	ds_read_b128 v[224:227], v145 offset:1024
	ds_read_b128 v[228:231], v145 offset:2048
	ds_read_b128 v[232:235], v145 offset:3072
	global_load_lds_dwordx4 v[198:199], off
	v_lshl_add_u64 v[198:199], v[236:237], 0, s[76:77]
	s_add_i32 m0, s22, 0x2000
	s_nop 0
	global_load_lds_dwordx4 v[198:199], off
	s_barrier
	s_waitcnt lgkmcnt(0)
	v_mfma_f32_16x16x32_bf16 v[94:97], v[220:223], v[162:165], v[94:97]
	v_mfma_f32_16x16x32_bf16 v[90:93], v[228:231], v[162:165], v[90:93]
	v_mfma_f32_16x16x32_bf16 v[86:89], v[220:223], v[170:173], v[86:89]
	v_mfma_f32_16x16x32_bf16 v[82:85], v[228:231], v[170:173], v[82:85]
	v_mfma_f32_16x16x32_bf16 v[78:81], v[220:223], v[182:185], v[78:81]
	v_mfma_f32_16x16x32_bf16 v[74:77], v[228:231], v[182:185], v[74:77]
	v_mfma_f32_16x16x32_bf16 v[70:73], v[220:223], v[190:193], v[70:73]
	v_mfma_f32_16x16x32_bf16 v[66:69], v[228:231], v[190:193], v[66:69]
	v_mfma_f32_16x16x32_bf16 v[94:97], v[224:227], v[166:169], v[94:97]
	v_mfma_f32_16x16x32_bf16 v[90:93], v[232:235], v[166:169], v[90:93]
	v_mfma_f32_16x16x32_bf16 v[86:89], v[224:227], v[174:177], v[86:89]
	v_mfma_f32_16x16x32_bf16 v[82:85], v[232:235], v[174:177], v[82:85]
	v_mfma_f32_16x16x32_bf16 v[78:81], v[224:227], v[186:189], v[78:81]
	v_mfma_f32_16x16x32_bf16 v[74:77], v[232:235], v[186:189], v[74:77]
	v_mfma_f32_16x16x32_bf16 v[70:73], v[224:227], v[194:197], v[70:73]
	s_barrier
	v_mfma_f32_16x16x32_bf16 v[66:69], v[232:235], v[194:197], v[66:69]
	s_mov_b32 m0, s53
	v_lshl_add_u64 v[198:199], v[238:239], 0, s[76:77]
	ds_read_b128 v[162:165], v144 offset:49152
	ds_read_b128 v[166:169], v144 offset:50176
	ds_read_b128 v[170:173], v144 offset:51200
	ds_read_b128 v[174:177], v144 offset:52224
	ds_read_b128 v[182:185], v144 offset:53248
	ds_read_b128 v[186:189], v144 offset:54272
	ds_read_b128 v[190:193], v144 offset:55296
	ds_read_b128 v[194:197], v144 offset:56320
	global_load_lds_dwordx4 v[198:199], off
	v_lshl_add_u64 v[198:199], v[240:241], 0, s[76:77]
	s_mov_b32 m0, s54
	s_nop 0
	global_load_lds_dwordx4 v[198:199], off
	s_barrier
; __device__ __forceinline__ unsigned pk2(float lo, float hi) { unsigned r; asm volatile("v_cvt_pk_bf16_f32 %0, %1, %2" : "=v"(r) : "v"(lo), "v"(hi)); return r; }
; __device__ __forceinline__ float siluf_(float x) { return x * __builtin_amdgcn_rcpf(1.0f + __expf(-x)); }
; #define PG8_STAGE(bufoff, gbase, voff) do { _Pragma("unroll") for (int _i = 0; _i < 2; ++_i) \
;         __builtin_amdgcn_global_load_lds((const unsigned*)((const char*)(gbase) + (voff)[_i]), (LAS unsigned*)(lds + (bufoff) + ldsw + _i * 8192), 16, 0, 0); } while (0)
; #define PG8_MMA(ai, bj, At, Bt) do { __builtin_amdgcn_s_setprio(1); _Pragma("unroll") for (int m = 0; m < 4; ++m) _Pragma("unroll") for (int n = 0; n < 2; ++n) _Pragma("unroll") for (int k = 0; k < 2; ++k) \
;         acc[ai][bj][m][n] = __builtin_amdgcn_mfma_f32_16x16x32_bf16(Bt[n][k], At[m][k], acc[ai][bj][m][n], 0, 0, 0); __builtin_amdgcn_s_setprio(0); } while (0)
; #define PG8_BAR __builtin_amdgcn_s_barrier()
;     template <int mode> __device__ __forceinline__ void run(const f32x4 (&acc)[2][2][4][2], const Unit& u, int wr, int wc, int fr, int fq, const LAS float* sc) const {
;     ...
;         if (mode == 0) {
;             const int col0 = u.pn * HALF + wc * 32 + 8 * fq;
; #pragma unroll
;             for (int ai = 0; ai < 2; ++ai)
; #pragma unroll
;                 for (int m = 0; m < 4; ++m) {
;                     const int row = row0 + ai * HALF + m * 16;
;                     const float s = sc[ai * HALF + wr * 64 + m * 16 + fr];
;                     const f32x4 g0 = acc[ai][0][m][0] * s, u0 = acc[ai][1][m][0] * s, g1 = acc[ai][0][m][1] * s, u1 = acc[ai][1][m][1] * s;
;                     u32x4 w;
;                     w.x = pk2(siluf_(g0[0]) * u0[0], siluf_(g0[1]) * u0[1]); w.y = pk2(siluf_(g0[2]) * u0[2], siluf_(g0[3]) * u0[3]);
;                     w.z = pk2(siluf_(g1[0]) * u1[0], siluf_(g1[1]) * u1[1]); w.w = pk2(siluf_(g1[2]) * u1[2], siluf_(g1[3]) * u1[3]);
;                     *(u32x4*)(ob + (size_t)row * FF + col0) = w;
; template <int MODE, class EpiT, class Sched>
; __device__ __forceinline__ void gemm_phase(LAS unsigned char* lds, const Gemm g, const Sched& S, const EpiT& E) {
;     ...
;             PG8_BAR; PG8_WAIT_L(0); PG8_MMA(1, 0, At, B0); PG8_BAR; PG8_SCHED;
;             PG8_STAGE(PG8_SB(1, 1), b3 + hstep, voffB);
;             PG8_WAIT_V(6); PG8_BAR; PG8_MMA(1, 1, At, B1); PG8_BAR;
	s_waitcnt lgkmcnt(0)
	v_mfma_f32_16x16x32_bf16 v[62:65], v[146:149], v[162:165], v[62:65]
	v_mfma_f32_16x16x32_bf16 v[58:61], v[154:157], v[162:165], v[58:61]
	v_mfma_f32_16x16x32_bf16 v[54:57], v[146:149], v[170:173], v[54:57]
	v_mfma_f32_16x16x32_bf16 v[50:53], v[154:157], v[170:173], v[50:53]
	v_mfma_f32_16x16x32_bf16 v[46:49], v[146:149], v[182:185], v[46:49]
	v_mfma_f32_16x16x32_bf16 v[42:45], v[154:157], v[182:185], v[42:45]
	v_mfma_f32_16x16x32_bf16 v[38:41], v[146:149], v[190:193], v[38:41]
	v_mfma_f32_16x16x32_bf16 v[34:37], v[154:157], v[190:193], v[34:37]
	v_mfma_f32_16x16x32_bf16 v[62:65], v[150:153], v[166:169], v[62:65]
	v_mfma_f32_16x16x32_bf16 v[58:61], v[158:161], v[166:169], v[58:61]
	v_mfma_f32_16x16x32_bf16 v[54:57], v[150:153], v[174:177], v[54:57]
	v_mfma_f32_16x16x32_bf16 v[50:53], v[158:161], v[174:177], v[50:53]
	v_mfma_f32_16x16x32_bf16 v[46:49], v[150:153], v[186:189], v[46:49]
	v_mfma_f32_16x16x32_bf16 v[42:45], v[158:161], v[186:189], v[42:45]
	v_mfma_f32_16x16x32_bf16 v[38:41], v[150:153], v[194:197], v[38:41]
	s_barrier
	v_mfma_f32_16x16x32_bf16 v[34:37], v[158:161], v[194:197], v[34:37]
	s_add_i32 s22, s30, s46
	v_lshl_add_u64 v[146:147], v[242:243], 0, s[76:77]
	s_mov_b32 m0, s22
	s_nop 0
	global_load_lds_dwordx4 v[146:147], off
	v_lshl_add_u64 v[146:147], v[244:245], 0, s[76:77]
	s_add_i32 m0, s22, 0x2000
	s_nop 0
	global_load_lds_dwordx4 v[146:147], off
	s_waitcnt vmcnt(6)
	s_barrier
	v_mfma_f32_16x16x32_bf16 v[30:33], v[220:223], v[162:165], v[30:33]
	v_mfma_f32_16x16x32_bf16 v[26:29], v[228:231], v[162:165], v[26:29]
	v_mfma_f32_16x16x32_bf16 v[22:25], v[220:223], v[170:173], v[22:25]
	v_mfma_f32_16x16x32_bf16 v[18:21], v[228:231], v[170:173], v[18:21]
	v_mfma_f32_16x16x32_bf16 v[14:17], v[220:223], v[182:185], v[14:17]
	v_mfma_f32_16x16x32_bf16 v[10:13], v[228:231], v[182:185], v[10:13]
	v_mfma_f32_16x16x32_bf16 v[6:9], v[220:223], v[190:193], v[6:9]
	v_mfma_f32_16x16x32_bf16 v[2:5], v[228:231], v[190:193], v[2:5]
	v_mfma_f32_16x16x32_bf16 v[30:33], v[224:227], v[166:169], v[30:33]
	v_mfma_f32_16x16x32_bf16 v[26:29], v[232:235], v[166:169], v[26:29]
	v_mfma_f32_16x16x32_bf16 v[22:25], v[224:227], v[174:177], v[22:25]
	v_mfma_f32_16x16x32_bf16 v[18:21], v[232:235], v[174:177], v[18:21]
	v_mfma_f32_16x16x32_bf16 v[14:17], v[224:227], v[186:189], v[14:17]
	v_mfma_f32_16x16x32_bf16 v[10:13], v[232:235], v[186:189], v[10:13]
	v_mfma_f32_16x16x32_bf16 v[6:9], v[224:227], v[194:197], v[6:9]
	s_barrier
	v_mfma_f32_16x16x32_bf16 v[2:5], v[232:235], v[194:197], v[2:5]
	s_add_u32 s4, s4, 0x100
	s_addc_u32 s5, s5, 0
	v_lshl_add_u64 v[138:139], v[138:139], 0, s[80:81]
	v_lshl_add_u64 v[136:137], v[136:137], 0, s[80:81]
	s_cmp_ge_u32 s23, s16
	s_mov_b32 s22, s23
	s_cbranch_scc0 .LBB0_332
	v_lshl_add_u32 v145, s57, 10, v142
	ds_read_b32 v136, v145
	v_lshl_or_b32 v138, s8, 7, v143
	v_lshl_add_u32 v146, s9, 8, v140
	v_ashrrev_i32_e32 v139, 31, v138
	v_lshlrev_b64 v[138:139], 1, v[138:139]
	s_waitcnt lgkmcnt(0)
	v_pk_mul_f32 v[148:149], v[126:127], v[136:137] op_sel_hi:[1,0]
	v_pk_mul_f32 v[154:155], v[94:95], v[136:137] op_sel_hi:[1,0]
	v_mul_f32_e32 v147, 0xbfb8aa3b, v148
	v_exp_f32_e32 v147, v147
	v_pk_mul_f32 v[150:151], v[128:129], v[136:137] op_sel_hi:[1,0]
	v_pk_mul_f32 v[152:153], v[96:97], v[136:137] op_sel_hi:[1,0]
	v_pk_mul_f32 v[158:159], v[122:123], v[136:137] op_sel_hi:[1,0]
	v_add_f32_e32 v147, 1.0, v147
	v_rcp_f32_e32 v147, v147
	v_pk_mul_f32 v[156:157], v[124:125], v[136:137] op_sel_hi:[1,0]
	v_pk_mul_f32 v[160:161], v[92:93], v[136:137] op_sel_hi:[1,0]
	v_pk_mul_f32 v[136:137], v[90:91], v[136:137] op_sel_hi:[1,0]
	v_mul_f32_e32 v147, v148, v147
	v_mul_f32_e32 v148, 0xbfb8aa3b, v149
	v_exp_f32_e32 v148, v148
	v_mul_f32_e32 v147, v154, v147
	s_and_b64 vcc, exec, s[42:43]
	v_add_f32_e32 v148, 1.0, v148
	v_rcp_f32_e32 v148, v148
	s_nop 0
	v_mul_f32_e32 v148, v149, v148
	v_mul_f32_e32 v148, v155, v148
	v_cvt_pk_bf16_f32 v148, v147, v148
	v_mul_f32_e32 v147, 0xbfb8aa3b, v150
	v_mul_f32_e32 v149, 0xbfb8aa3b, v151
	v_exp_f32_e32 v147, v147
	v_exp_f32_e32 v149, v149
	v_add_f32_e32 v147, 1.0, v147
	v_add_f32_e32 v149, 1.0, v149
	v_rcp_f32_e32 v147, v147
	v_rcp_f32_e32 v149, v149
	v_mul_f32_e32 v147, v150, v147
	v_mul_f32_e32 v149, v151, v149
	v_mul_f32_e32 v147, v152, v147
	v_mul_f32_e32 v149, v153, v149
	v_cvt_pk_bf16_f32 v149, v147, v149
	v_mul_f32_e32 v147, 0xbfb8aa3b, v158
	v_exp_f32_e32 v147, v147
	s_nop 0
	v_add_f32_e32 v147, 1.0, v147
	v_rcp_f32_e32 v147, v147
	s_nop 0
	v_mul_f32_e32 v147, v158, v147
	v_mul_f32_e32 v136, v136, v147
	v_mul_f32_e32 v147, 0xbfb8aa3b, v159
	v_exp_f32_e32 v147, v147
	s_nop 0
	v_add_f32_e32 v147, 1.0, v147
	v_rcp_f32_e32 v147, v147
	s_nop 0
	v_mul_f32_e32 v147, v159, v147
	v_mul_f32_e32 v137, v137, v147
	v_cvt_pk_bf16_f32 v150, v136, v137
	v_mul_f32_e32 v136, 0xbfb8aa3b, v156
	v_mul_f32_e32 v137, 0xbfb8aa3b, v157
	v_exp_f32_e32 v136, v136
	v_exp_f32_e32 v137, v137
	v_or_b32_e32 v147, 16, v146
	v_add_f32_e32 v136, 1.0, v136
	v_add_f32_e32 v137, 1.0, v137
	v_rcp_f32_e32 v136, v136
	v_rcp_f32_e32 v137, v137
	v_mul_f32_e32 v136, v156, v136
	v_mul_f32_e32 v137, v157, v137
	v_mul_f32_e32 v136, v160, v136
	v_mul_f32_e32 v137, v161, v137
	v_cvt_pk_bf16_f32 v151, v136, v137
	v_mov_b64_e32 v[136:137], s[6:7]
	v_mad_i64_i32 v[152:153], s[4:5], v146, s33, v[136:137]
	v_lshl_add_u64 v[152:153], v[152:153], 0, v[138:139]
	global_store_dwordx4 v[152:153], v[148:151], off
	ds_read_b32 v148, v145 offset:64
	s_waitcnt lgkmcnt(0)
; __device__ __forceinline__ unsigned pk2(float lo, float hi) { unsigned r; asm volatile("v_cvt_pk_bf16_f32 %0, %1, %2" : "=v"(r) : "v"(lo), "v"(hi)); return r; }
; __device__ __forceinline__ float siluf_(float x) { return x * __builtin_amdgcn_rcpf(1.0f + __expf(-x)); }
;     template <int mode> __device__ __forceinline__ void run(const f32x4 (&acc)[2][2][4][2], const Unit& u, int wr, int wc, int fr, int fq, const LAS float* sc) const {
;     ...
;                 for (int m = 0; m < 4; ++m) {
;                     const int row = row0 + ai * HALF + m * 16;
;                     const float s = sc[ai * HALF + wr * 64 + m * 16 + fr];
;                     const f32x4 g0 = acc[ai][0][m][0] * s, u0 = acc[ai][1][m][0] * s, g1 = acc[ai][0][m][1] * s, u1 = acc[ai][1][m][1] * s;
;                     u32x4 w;
;                     w.x = pk2(siluf_(g0[0]) * u0[0], siluf_(g0[1]) * u0[1]); w.y = pk2(siluf_(g0[2]) * u0[2], siluf_(g0[3]) * u0[3]);
;                     w.z = pk2(siluf_(g1[0]) * u1[0], siluf_(g1[1]) * u1[1]); w.w = pk2(siluf_(g1[2]) * u1[2], siluf_(g1[3]) * u1[3]);
;                     *(u32x4*)(ob + (size_t)row * FF + col0) = w;
	v_pk_mul_f32 v[152:153], v[118:119], v[148:149] op_sel_hi:[1,0]
	v_pk_mul_f32 v[150:151], v[120:121], v[148:149] op_sel_hi:[1,0]
	v_pk_mul_f32 v[154:155], v[88:89], v[148:149] op_sel_hi:[1,0]
	v_pk_mul_f32 v[156:157], v[86:87], v[148:149] op_sel_hi:[1,0]
	v_pk_mul_f32 v[158:159], v[116:117], v[148:149] op_sel_hi:[1,0]
	v_pk_mul_f32 v[160:161], v[114:115], v[148:149] op_sel_hi:[1,0]
	v_pk_mul_f32 v[162:163], v[84:85], v[148:149] op_sel_hi:[1,0]
	v_pk_mul_f32 v[164:165], v[82:83], v[148:149] op_sel_hi:[1,0]
	v_mul_f32_e32 v148, 0xbfb8aa3b, v152
	v_mul_f32_e32 v149, 0xbfb8aa3b, v153
	v_exp_f32_e32 v148, v148
	v_exp_f32_e32 v149, v149
	v_add_f32_e32 v148, 1.0, v148
	v_add_f32_e32 v149, 1.0, v149
	v_rcp_f32_e32 v148, v148
	v_rcp_f32_e32 v149, v149
	v_mul_f32_e32 v148, v152, v148
	v_mul_f32_e32 v149, v153, v149
	v_mul_f32_e32 v148, v156, v148
	v_mul_f32_e32 v149, v157, v149
	v_cvt_pk_bf16_f32 v148, v148, v149
	v_mul_f32_e32 v149, 0xbfb8aa3b, v150
	v_exp_f32_e32 v149, v149
	v_mul_f32_e32 v152, 0xbfb8aa3b, v159
	v_exp_f32_e32 v152, v152
	v_add_f32_e32 v149, 1.0, v149
	v_rcp_f32_e32 v149, v149
	v_add_f32_e32 v152, 1.0, v152
	v_rcp_f32_e32 v152, v152
	v_mul_f32_e32 v149, v150, v149
	v_mul_f32_e32 v150, 0xbfb8aa3b, v151
	v_exp_f32_e32 v150, v150
	v_mul_f32_e32 v149, v154, v149
	v_mul_f32_e32 v152, v159, v152
	v_mul_f32_e32 v152, v163, v152
	v_add_f32_e32 v150, 1.0, v150
	v_rcp_f32_e32 v150, v150
	s_nop 0
	v_mul_f32_e32 v150, v151, v150
	v_mul_f32_e32 v150, v155, v150
	v_cvt_pk_bf16_f32 v149, v149, v150
	v_mul_f32_e32 v150, 0xbfb8aa3b, v160
	v_mul_f32_e32 v151, 0xbfb8aa3b, v161
	v_exp_f32_e32 v150, v150
	v_exp_f32_e32 v151, v151
	v_add_f32_e32 v150, 1.0, v150
	v_add_f32_e32 v151, 1.0, v151
	v_rcp_f32_e32 v150, v150
	v_rcp_f32_e32 v151, v151
	v_mul_f32_e32 v150, v160, v150
	v_mul_f32_e32 v151, v161, v151
	v_mul_f32_e32 v150, v164, v150
	v_mul_f32_e32 v151, v165, v151
	v_cvt_pk_bf16_f32 v150, v150, v151
	v_mul_f32_e32 v151, 0xbfb8aa3b, v158
	v_exp_f32_e32 v151, v151
	s_nop 0
	v_add_f32_e32 v151, 1.0, v151
	v_rcp_f32_e32 v151, v151
	s_nop 0
	v_mul_f32_e32 v151, v158, v151
	v_mul_f32_e32 v151, v162, v151
	v_cvt_pk_bf16_f32 v151, v151, v152
	v_mad_i64_i32 v[152:153], s[4:5], v147, s33, v[136:137]
	v_lshl_add_u64 v[152:153], v[152:153], 0, v[138:139]
	global_store_dwordx4 v[152:153], v[148:151], off
	ds_read_b32 v148, v145 offset:128
	v_or_b32_e32 v147, 32, v146
	s_waitcnt lgkmcnt(0)
	v_pk_mul_f32 v[152:153], v[110:111], v[148:149] op_sel_hi:[1,0]
	v_pk_mul_f32 v[150:151], v[112:113], v[148:149] op_sel_hi:[1,0]
	v_pk_mul_f32 v[154:155], v[80:81], v[148:149] op_sel_hi:[1,0]
	v_pk_mul_f32 v[156:157], v[78:79], v[148:149] op_sel_hi:[1,0]
	v_pk_mul_f32 v[158:159], v[108:109], v[148:149] op_sel_hi:[1,0]
	v_pk_mul_f32 v[160:161], v[106:107], v[148:149] op_sel_hi:[1,0]
	v_pk_mul_f32 v[162:163], v[76:77], v[148:149] op_sel_hi:[1,0]
	v_pk_mul_f32 v[164:165], v[74:75], v[148:149] op_sel_hi:[1,0]
	v_mul_f32_e32 v148, 0xbfb8aa3b, v152
	v_mul_f32_e32 v149, 0xbfb8aa3b, v153
	v_exp_f32_e32 v148, v148
	v_exp_f32_e32 v149, v149
	v_add_f32_e32 v148, 1.0, v148
	v_add_f32_e32 v149, 1.0, v149
	v_rcp_f32_e32 v148, v148
	v_rcp_f32_e32 v149, v149
	v_mul_f32_e32 v148, v152, v148
	v_mul_f32_e32 v149, v153, v149
	v_mul_f32_e32 v148, v156, v148
	v_mul_f32_e32 v149, v157, v149
	v_cvt_pk_bf16_f32 v148, v148, v149
	v_mul_f32_e32 v149, 0xbfb8aa3b, v150
	v_exp_f32_e32 v149, v149
	v_mul_f32_e32 v152, 0xbfb8aa3b, v159
	v_exp_f32_e32 v152, v152
	v_add_f32_e32 v149, 1.0, v149
	v_rcp_f32_e32 v149, v149
	v_add_f32_e32 v152, 1.0, v152
	v_rcp_f32_e32 v152, v152
	v_mul_f32_e32 v149, v150, v149
	v_mul_f32_e32 v150, 0xbfb8aa3b, v151
	v_exp_f32_e32 v150, v150
	v_mul_f32_e32 v149, v154, v149
	v_mul_f32_e32 v152, v159, v152
	v_mul_f32_e32 v152, v163, v152
	v_add_f32_e32 v150, 1.0, v150
	v_rcp_f32_e32 v150, v150
	s_nop 0
	v_mul_f32_e32 v150, v151, v150
	v_mul_f32_e32 v150, v155, v150
	v_cvt_pk_bf16_f32 v149, v149, v150
	v_mul_f32_e32 v150, 0xbfb8aa3b, v160
	v_mul_f32_e32 v151, 0xbfb8aa3b, v161
	v_exp_f32_e32 v150, v150
	v_exp_f32_e32 v151, v151
	v_add_f32_e32 v150, 1.0, v150
	v_add_f32_e32 v151, 1.0, v151
	v_rcp_f32_e32 v150, v150
	v_rcp_f32_e32 v151, v151
	v_mul_f32_e32 v150, v160, v150
	v_mul_f32_e32 v151, v161, v151
	v_mul_f32_e32 v150, v164, v150
	v_mul_f32_e32 v151, v165, v151
	v_cvt_pk_bf16_f32 v150, v150, v151
	v_mul_f32_e32 v151, 0xbfb8aa3b, v158
	v_exp_f32_e32 v151, v151
	s_nop 0
	v_add_f32_e32 v151, 1.0, v151
	v_rcp_f32_e32 v151, v151
	s_nop 0
	v_mul_f32_e32 v151, v158, v151
	v_mul_f32_e32 v151, v162, v151
	v_cvt_pk_bf16_f32 v151, v151, v152
	v_mad_i64_i32 v[152:153], s[4:5], v147, s33, v[136:137]
	v_lshl_add_u64 v[152:153], v[152:153], 0, v[138:139]
	global_store_dwordx4 v[152:153], v[148:151], off
	ds_read_b32 v148, v145 offset:192
	v_or_b32_e32 v147, 48, v146
	s_waitcnt lgkmcnt(0)
; __device__ __forceinline__ unsigned pk2(float lo, float hi) { unsigned r; asm volatile("v_cvt_pk_bf16_f32 %0, %1, %2" : "=v"(r) : "v"(lo), "v"(hi)); return r; }
; __device__ __forceinline__ float siluf_(float x) { return x * __builtin_amdgcn_rcpf(1.0f + __expf(-x)); }
;     template <int mode> __device__ __forceinline__ void run(const f32x4 (&acc)[2][2][4][2], const Unit& u, int wr, int wc, int fr, int fq, const LAS float* sc) const {
;     ...
;                 for (int m = 0; m < 4; ++m) {
;                     const int row = row0 + ai * HALF + m * 16;
;                     const float s = sc[ai * HALF + wr * 64 + m * 16 + fr];
;                     const f32x4 g0 = acc[ai][0][m][0] * s, u0 = acc[ai][1][m][0] * s, g1 = acc[ai][0][m][1] * s, u1 = acc[ai][1][m][1] * s;
;                     u32x4 w;
;                     w.x = pk2(siluf_(g0[0]) * u0[0], siluf_(g0[1]) * u0[1]); w.y = pk2(siluf_(g0[2]) * u0[2], siluf_(g0[3]) * u0[3]);
;                     w.z = pk2(siluf_(g1[0]) * u1[0], siluf_(g1[1]) * u1[1]); w.w = pk2(siluf_(g1[2]) * u1[2], siluf_(g1[3]) * u1[3]);
;                     *(u32x4*)(ob + (size_t)row * FF + col0) = w;
	v_pk_mul_f32 v[152:153], v[102:103], v[148:149] op_sel_hi:[1,0]
	v_pk_mul_f32 v[150:151], v[104:105], v[148:149] op_sel_hi:[1,0]
	v_pk_mul_f32 v[154:155], v[72:73], v[148:149] op_sel_hi:[1,0]
	v_pk_mul_f32 v[156:157], v[70:71], v[148:149] op_sel_hi:[1,0]
	v_pk_mul_f32 v[158:159], v[100:101], v[148:149] op_sel_hi:[1,0]
	v_pk_mul_f32 v[160:161], v[98:99], v[148:149] op_sel_hi:[1,0]
	v_pk_mul_f32 v[162:163], v[68:69], v[148:149] op_sel_hi:[1,0]
	v_pk_mul_f32 v[164:165], v[66:67], v[148:149] op_sel_hi:[1,0]
	v_mul_f32_e32 v148, 0xbfb8aa3b, v152
	v_mul_f32_e32 v149, 0xbfb8aa3b, v153
	v_exp_f32_e32 v148, v148
	v_exp_f32_e32 v149, v149
	v_add_f32_e32 v148, 1.0, v148
	v_add_f32_e32 v149, 1.0, v149
	v_rcp_f32_e32 v148, v148
	v_rcp_f32_e32 v149, v149
	v_mul_f32_e32 v148, v152, v148
	v_mul_f32_e32 v149, v153, v149
	v_mul_f32_e32 v148, v156, v148
	v_mul_f32_e32 v149, v157, v149
	v_cvt_pk_bf16_f32 v148, v148, v149
	v_mul_f32_e32 v149, 0xbfb8aa3b, v150
	v_exp_f32_e32 v149, v149
	v_mul_f32_e32 v152, 0xbfb8aa3b, v159
	v_exp_f32_e32 v152, v152
	v_add_f32_e32 v149, 1.0, v149
	v_rcp_f32_e32 v149, v149
	v_add_f32_e32 v152, 1.0, v152
	v_rcp_f32_e32 v152, v152
	v_mul_f32_e32 v149, v150, v149
	v_mul_f32_e32 v150, 0xbfb8aa3b, v151
	v_exp_f32_e32 v150, v150
	v_mul_f32_e32 v149, v154, v149
	v_mul_f32_e32 v152, v159, v152
	v_mul_f32_e32 v152, v163, v152
	v_add_f32_e32 v150, 1.0, v150
	v_rcp_f32_e32 v150, v150
	s_nop 0
	v_mul_f32_e32 v150, v151, v150
	v_mul_f32_e32 v150, v155, v150
	v_cvt_pk_bf16_f32 v149, v149, v150
	v_mul_f32_e32 v150, 0xbfb8aa3b, v160
	v_mul_f32_e32 v151, 0xbfb8aa3b, v161
	v_exp_f32_e32 v150, v150
	v_exp_f32_e32 v151, v151
	v_add_f32_e32 v150, 1.0, v150
	v_add_f32_e32 v151, 1.0, v151
	v_rcp_f32_e32 v150, v150
	v_rcp_f32_e32 v151, v151
	v_mul_f32_e32 v150, v160, v150
	v_mul_f32_e32 v151, v161, v151
	v_mul_f32_e32 v150, v164, v150
	v_mul_f32_e32 v151, v165, v151
	v_cvt_pk_bf16_f32 v150, v150, v151
	v_mul_f32_e32 v151, 0xbfb8aa3b, v158
	v_exp_f32_e32 v151, v151
	s_nop 0
	v_add_f32_e32 v151, 1.0, v151
	v_rcp_f32_e32 v151, v151
	s_nop 0
	v_mul_f32_e32 v151, v158, v151
	v_mul_f32_e32 v151, v162, v151
	v_cvt_pk_bf16_f32 v151, v151, v152
	v_mad_i64_i32 v[152:153], s[4:5], v147, s33, v[136:137]
	v_lshl_add_u64 v[152:153], v[152:153], 0, v[138:139]
	global_store_dwordx4 v[152:153], v[148:151], off
	ds_read_b32 v148, v145 offset:512
	v_add_u32_e32 v147, 0x80, v146
	s_waitcnt lgkmcnt(0)
	v_pk_mul_f32 v[152:153], v[62:63], v[148:149] op_sel_hi:[1,0]
	v_pk_mul_f32 v[150:151], v[64:65], v[148:149] op_sel_hi:[1,0]
	v_pk_mul_f32 v[154:155], v[32:33], v[148:149] op_sel_hi:[1,0]
	v_pk_mul_f32 v[156:157], v[30:31], v[148:149] op_sel_hi:[1,0]
	v_pk_mul_f32 v[158:159], v[60:61], v[148:149] op_sel_hi:[1,0]
	v_pk_mul_f32 v[160:161], v[58:59], v[148:149] op_sel_hi:[1,0]
	v_pk_mul_f32 v[162:163], v[28:29], v[148:149] op_sel_hi:[1,0]
	v_pk_mul_f32 v[164:165], v[26:27], v[148:149] op_sel_hi:[1,0]
	v_mul_f32_e32 v148, 0xbfb8aa3b, v152
	v_mul_f32_e32 v149, 0xbfb8aa3b, v153
	v_exp_f32_e32 v148, v148
	v_exp_f32_e32 v149, v149
	v_add_f32_e32 v148, 1.0, v148
	v_add_f32_e32 v149, 1.0, v149
	v_rcp_f32_e32 v148, v148
	v_rcp_f32_e32 v149, v149
	v_mul_f32_e32 v148, v152, v148
	v_mul_f32_e32 v149, v153, v149
	v_mul_f32_e32 v148, v156, v148
	v_mul_f32_e32 v149, v157, v149
	v_cvt_pk_bf16_f32 v148, v148, v149
	v_mul_f32_e32 v149, 0xbfb8aa3b, v150
	v_exp_f32_e32 v149, v149
	v_mul_f32_e32 v152, 0xbfb8aa3b, v159
	v_exp_f32_e32 v152, v152
	v_add_f32_e32 v149, 1.0, v149
	v_rcp_f32_e32 v149, v149
	v_add_f32_e32 v152, 1.0, v152
	v_rcp_f32_e32 v152, v152
	v_mul_f32_e32 v149, v150, v149
	v_mul_f32_e32 v150, 0xbfb8aa3b, v151
	v_exp_f32_e32 v150, v150
	v_mul_f32_e32 v149, v154, v149
	v_mul_f32_e32 v152, v159, v152
	v_mul_f32_e32 v152, v163, v152
	v_add_f32_e32 v150, 1.0, v150
	v_rcp_f32_e32 v150, v150
	s_nop 0
	v_mul_f32_e32 v150, v151, v150
	v_mul_f32_e32 v150, v155, v150
	v_cvt_pk_bf16_f32 v149, v149, v150
	v_mul_f32_e32 v150, 0xbfb8aa3b, v160
	v_mul_f32_e32 v151, 0xbfb8aa3b, v161
	v_exp_f32_e32 v150, v150
	v_exp_f32_e32 v151, v151
	v_add_f32_e32 v150, 1.0, v150
	v_add_f32_e32 v151, 1.0, v151
	v_rcp_f32_e32 v150, v150
	v_rcp_f32_e32 v151, v151
	v_mul_f32_e32 v150, v160, v150
	v_mul_f32_e32 v151, v161, v151
	v_mul_f32_e32 v150, v164, v150
	v_mul_f32_e32 v151, v165, v151
	v_cvt_pk_bf16_f32 v150, v150, v151
	v_mul_f32_e32 v151, 0xbfb8aa3b, v158
	v_exp_f32_e32 v151, v151
	s_nop 0
	v_add_f32_e32 v151, 1.0, v151
	v_rcp_f32_e32 v151, v151
	s_nop 0
	v_mul_f32_e32 v151, v158, v151
	v_mul_f32_e32 v151, v162, v151
	v_cvt_pk_bf16_f32 v151, v151, v152
	v_mad_i64_i32 v[152:153], s[4:5], v147, s33, v[136:137]
	v_lshl_add_u64 v[152:153], v[152:153], 0, v[138:139]
	global_store_dwordx4 v[152:153], v[148:151], off
	ds_read_b32 v148, v145 offset:576
	v_add_u32_e32 v147, 0x90, v146
	s_waitcnt lgkmcnt(0)
; __device__ __forceinline__ unsigned pk2(float lo, float hi) { unsigned r; asm volatile("v_cvt_pk_bf16_f32 %0, %1, %2" : "=v"(r) : "v"(lo), "v"(hi)); return r; }
; __device__ __forceinline__ float siluf_(float x) { return x * __builtin_amdgcn_rcpf(1.0f + __expf(-x)); }
;     template <int mode> __device__ __forceinline__ void run(const f32x4 (&acc)[2][2][4][2], const Unit& u, int wr, int wc, int fr, int fq, const LAS float* sc) const {
;     ...
;                 for (int m = 0; m < 4; ++m) {
;                     const int row = row0 + ai * HALF + m * 16;
;                     const float s = sc[ai * HALF + wr * 64 + m * 16 + fr];
;                     const f32x4 g0 = acc[ai][0][m][0] * s, u0 = acc[ai][1][m][0] * s, g1 = acc[ai][0][m][1] * s, u1 = acc[ai][1][m][1] * s;
;                     u32x4 w;
;                     w.x = pk2(siluf_(g0[0]) * u0[0], siluf_(g0[1]) * u0[1]); w.y = pk2(siluf_(g0[2]) * u0[2], siluf_(g0[3]) * u0[3]);
;                     w.z = pk2(siluf_(g1[0]) * u1[0], siluf_(g1[1]) * u1[1]); w.w = pk2(siluf_(g1[2]) * u1[2], siluf_(g1[3]) * u1[3]);
;                     *(u32x4*)(ob + (size_t)row * FF + col0) = w;
	v_pk_mul_f32 v[152:153], v[54:55], v[148:149] op_sel_hi:[1,0]
	v_pk_mul_f32 v[150:151], v[56:57], v[148:149] op_sel_hi:[1,0]
	v_pk_mul_f32 v[154:155], v[24:25], v[148:149] op_sel_hi:[1,0]
	v_pk_mul_f32 v[156:157], v[22:23], v[148:149] op_sel_hi:[1,0]
	v_pk_mul_f32 v[158:159], v[52:53], v[148:149] op_sel_hi:[1,0]
	v_pk_mul_f32 v[160:161], v[50:51], v[148:149] op_sel_hi:[1,0]
	v_pk_mul_f32 v[162:163], v[20:21], v[148:149] op_sel_hi:[1,0]
	v_pk_mul_f32 v[164:165], v[18:19], v[148:149] op_sel_hi:[1,0]
	v_mul_f32_e32 v148, 0xbfb8aa3b, v152
	v_mul_f32_e32 v149, 0xbfb8aa3b, v153
	v_exp_f32_e32 v148, v148
	v_exp_f32_e32 v149, v149
	v_add_f32_e32 v148, 1.0, v148
	v_add_f32_e32 v149, 1.0, v149
	v_rcp_f32_e32 v148, v148
	v_rcp_f32_e32 v149, v149
	v_mul_f32_e32 v148, v152, v148
	v_mul_f32_e32 v149, v153, v149
	v_mul_f32_e32 v148, v156, v148
	v_mul_f32_e32 v149, v157, v149
	v_cvt_pk_bf16_f32 v148, v148, v149
	v_mul_f32_e32 v149, 0xbfb8aa3b, v150
	v_exp_f32_e32 v149, v149
	v_mul_f32_e32 v152, 0xbfb8aa3b, v159
	v_exp_f32_e32 v152, v152
	v_add_f32_e32 v149, 1.0, v149
	v_rcp_f32_e32 v149, v149
	v_add_f32_e32 v152, 1.0, v152
	v_rcp_f32_e32 v152, v152
	v_mul_f32_e32 v149, v150, v149
	v_mul_f32_e32 v150, 0xbfb8aa3b, v151
	v_exp_f32_e32 v150, v150
	v_mul_f32_e32 v149, v154, v149
	v_mul_f32_e32 v152, v159, v152
	v_mul_f32_e32 v152, v163, v152
	v_add_f32_e32 v150, 1.0, v150
	v_rcp_f32_e32 v150, v150
	s_nop 0
	v_mul_f32_e32 v150, v151, v150
	v_mul_f32_e32 v150, v155, v150
	v_cvt_pk_bf16_f32 v149, v149, v150
	v_mul_f32_e32 v150, 0xbfb8aa3b, v160
	v_mul_f32_e32 v151, 0xbfb8aa3b, v161
	v_exp_f32_e32 v150, v150
	v_exp_f32_e32 v151, v151
	v_add_f32_e32 v150, 1.0, v150
	v_add_f32_e32 v151, 1.0, v151
	v_rcp_f32_e32 v150, v150
	v_rcp_f32_e32 v151, v151
	v_mul_f32_e32 v150, v160, v150
	v_mul_f32_e32 v151, v161, v151
	v_mul_f32_e32 v150, v164, v150
	v_mul_f32_e32 v151, v165, v151
	v_cvt_pk_bf16_f32 v150, v150, v151
	v_mul_f32_e32 v151, 0xbfb8aa3b, v158
	v_exp_f32_e32 v151, v151
	s_nop 0
	v_add_f32_e32 v151, 1.0, v151
	v_rcp_f32_e32 v151, v151
	s_nop 0
	v_mul_f32_e32 v151, v158, v151
	v_mul_f32_e32 v151, v162, v151
	v_cvt_pk_bf16_f32 v151, v151, v152
	v_mad_i64_i32 v[152:153], s[4:5], v147, s33, v[136:137]
	v_lshl_add_u64 v[152:153], v[152:153], 0, v[138:139]
	global_store_dwordx4 v[152:153], v[148:151], off
	ds_read_b32 v148, v145 offset:640
	v_add_u32_e32 v147, 0xa0, v146
	s_waitcnt lgkmcnt(0)
	v_pk_mul_f32 v[152:153], v[46:47], v[148:149] op_sel_hi:[1,0]
	v_pk_mul_f32 v[150:151], v[48:49], v[148:149] op_sel_hi:[1,0]
	v_pk_mul_f32 v[154:155], v[16:17], v[148:149] op_sel_hi:[1,0]
	v_pk_mul_f32 v[156:157], v[14:15], v[148:149] op_sel_hi:[1,0]
	v_pk_mul_f32 v[158:159], v[44:45], v[148:149] op_sel_hi:[1,0]
	v_pk_mul_f32 v[160:161], v[42:43], v[148:149] op_sel_hi:[1,0]
	v_pk_mul_f32 v[162:163], v[12:13], v[148:149] op_sel_hi:[1,0]
	v_pk_mul_f32 v[164:165], v[10:11], v[148:149] op_sel_hi:[1,0]
	v_mul_f32_e32 v148, 0xbfb8aa3b, v152
	v_mul_f32_e32 v149, 0xbfb8aa3b, v153
	v_exp_f32_e32 v148, v148
	v_exp_f32_e32 v149, v149
	v_add_f32_e32 v148, 1.0, v148
	v_add_f32_e32 v149, 1.0, v149
	v_rcp_f32_e32 v148, v148
	v_rcp_f32_e32 v149, v149
	v_mul_f32_e32 v148, v152, v148
	v_mul_f32_e32 v149, v153, v149
	v_mul_f32_e32 v148, v156, v148
	v_mul_f32_e32 v149, v157, v149
	v_cvt_pk_bf16_f32 v148, v148, v149
	v_mul_f32_e32 v149, 0xbfb8aa3b, v150
	v_exp_f32_e32 v149, v149
	v_mul_f32_e32 v152, 0xbfb8aa3b, v159
	v_exp_f32_e32 v152, v152
	v_add_f32_e32 v149, 1.0, v149
	v_rcp_f32_e32 v149, v149
	v_add_f32_e32 v152, 1.0, v152
	v_rcp_f32_e32 v152, v152
	v_mul_f32_e32 v149, v150, v149
	v_mul_f32_e32 v150, 0xbfb8aa3b, v151
	v_exp_f32_e32 v150, v150
	v_mul_f32_e32 v149, v154, v149
	v_mul_f32_e32 v152, v159, v152
	v_mul_f32_e32 v152, v163, v152
	v_add_f32_e32 v150, 1.0, v150
	v_rcp_f32_e32 v150, v150
	s_nop 0
	v_mul_f32_e32 v150, v151, v150
	v_mul_f32_e32 v150, v155, v150
	v_cvt_pk_bf16_f32 v149, v149, v150
	v_mul_f32_e32 v150, 0xbfb8aa3b, v160
	v_mul_f32_e32 v151, 0xbfb8aa3b, v161
	v_exp_f32_e32 v150, v150
	v_exp_f32_e32 v151, v151
	v_add_f32_e32 v150, 1.0, v150
	v_add_f32_e32 v151, 1.0, v151
	v_rcp_f32_e32 v150, v150
	v_rcp_f32_e32 v151, v151
	v_mul_f32_e32 v150, v160, v150
	v_mul_f32_e32 v151, v161, v151
	v_mul_f32_e32 v150, v164, v150
	v_mul_f32_e32 v151, v165, v151
	v_cvt_pk_bf16_f32 v150, v150, v151
	v_mul_f32_e32 v151, 0xbfb8aa3b, v158
	v_exp_f32_e32 v151, v151
	v_add_u32_e32 v164, 0xb0, v146
	v_add_f32_e32 v151, 1.0, v151
	v_rcp_f32_e32 v151, v151
	s_nop 0
	v_mul_f32_e32 v151, v158, v151
	v_mul_f32_e32 v151, v162, v151
	v_cvt_pk_bf16_f32 v151, v151, v152
	ds_read_b32 v146, v145 offset:704
	v_mad_i64_i32 v[152:153], s[4:5], v147, s33, v[136:137]
	v_lshl_add_u64 v[152:153], v[152:153], 0, v[138:139]
	global_store_dwordx4 v[152:153], v[148:151], off
	s_waitcnt lgkmcnt(0)
; __device__ __forceinline__ unsigned pk2(float lo, float hi) { unsigned r; asm volatile("v_cvt_pk_bf16_f32 %0, %1, %2" : "=v"(r) : "v"(lo), "v"(hi)); return r; }
; __device__ __forceinline__ float siluf_(float x) { return x * __builtin_amdgcn_rcpf(1.0f + __expf(-x)); }
;     template <int mode> __device__ __forceinline__ void run(const f32x4 (&acc)[2][2][4][2], const Unit& u, int wr, int wc, int fr, int fq, const LAS float* sc) const {
;     ...
;                 for (int m = 0; m < 4; ++m) {
;                     const int row = row0 + ai * HALF + m * 16;
;                     const float s = sc[ai * HALF + wr * 64 + m * 16 + fr];
;                     const f32x4 g0 = acc[ai][0][m][0] * s, u0 = acc[ai][1][m][0] * s, g1 = acc[ai][0][m][1] * s, u1 = acc[ai][1][m][1] * s;
;                     u32x4 w;
;                     w.x = pk2(siluf_(g0[0]) * u0[0], siluf_(g0[1]) * u0[1]); w.y = pk2(siluf_(g0[2]) * u0[2], siluf_(g0[3]) * u0[3]);
;                     w.z = pk2(siluf_(g1[0]) * u1[0], siluf_(g1[1]) * u1[1]); w.w = pk2(siluf_(g1[2]) * u1[2], siluf_(g1[3]) * u1[3]);
;                     *(u32x4*)(ob + (size_t)row * FF + col0) = w;
; template <int MODE, class EpiT, class Sched>
; __device__ __forceinline__ void gemm_phase(LAS unsigned char* lds, const Gemm g, const Sched& S, const EpiT& E) {
;     ...
;         E.template run<MODE>(acc, cur, wr, wc, fr, fq, SC + ui * 256);
;         if (!has_next) break;
; #pragma unroll
;         for (int a = 0; a < 2; ++a)
; #pragma unroll
;             for (int b = 0; b < 2; ++b)
; #pragma unroll
;                 for (int m = 0; m < 4; ++m)
; #pragma unroll
;                     for (int n = 0; n < 2; ++n) acc[a][b][m][n] = (f32x4){0.f, 0.f, 0.f, 0.f};
;         cur = nxt; cA = nA; cB = nB; ++ui;
	v_pk_mul_f32 v[152:153], v[8:9], v[146:147] op_sel_hi:[1,0]
	v_pk_mul_f32 v[154:155], v[6:7], v[146:147] op_sel_hi:[1,0]
	v_pk_mul_f32 v[150:151], v[38:39], v[146:147] op_sel_hi:[1,0]
	v_pk_mul_f32 v[148:149], v[40:41], v[146:147] op_sel_hi:[1,0]
	v_pk_mul_f32 v[156:157], v[36:37], v[146:147] op_sel_hi:[1,0]
	v_pk_mul_f32 v[158:159], v[34:35], v[146:147] op_sel_hi:[1,0]
	v_pk_mul_f32 v[160:161], v[4:5], v[146:147] op_sel_hi:[1,0]
	v_pk_mul_f32 v[162:163], v[2:3], v[146:147] op_sel_hi:[1,0]
	v_mul_f32_e32 v145, 0xbfb8aa3b, v150
	v_mul_f32_e32 v146, 0xbfb8aa3b, v151
	v_exp_f32_e32 v145, v145
	v_exp_f32_e32 v146, v146
	v_mul_f32_e32 v147, 0xbfb8aa3b, v149
	v_exp_f32_e32 v147, v147
	v_add_f32_e32 v145, 1.0, v145
	v_add_f32_e32 v146, 1.0, v146
	v_rcp_f32_e32 v145, v145
	v_rcp_f32_e32 v146, v146
	v_add_f32_e32 v147, 1.0, v147
	v_rcp_f32_e32 v147, v147
	v_mul_f32_e32 v145, v150, v145
	v_mul_f32_e32 v146, v151, v146
	v_mul_f32_e32 v145, v154, v145
	v_mul_f32_e32 v146, v155, v146
	v_cvt_pk_bf16_f32 v146, v145, v146
	v_mul_f32_e32 v145, 0xbfb8aa3b, v148
	v_exp_f32_e32 v145, v145
	v_mul_f32_e32 v147, v149, v147
	v_mul_f32_e32 v147, v153, v147
	v_mul_f32_e32 v149, 0xbfb8aa3b, v157
	v_add_f32_e32 v145, 1.0, v145
	v_rcp_f32_e32 v145, v145
	v_exp_f32_e32 v149, v149
	v_mad_i64_i32 v[136:137], s[4:5], v164, s33, v[136:137]
	v_mul_f32_e32 v145, v148, v145
	v_mul_f32_e32 v145, v152, v145
	v_cvt_pk_bf16_f32 v147, v145, v147
	v_mul_f32_e32 v145, 0xbfb8aa3b, v158
	v_mul_f32_e32 v148, 0xbfb8aa3b, v159
	v_exp_f32_e32 v145, v145
	v_exp_f32_e32 v148, v148
	v_add_f32_e32 v149, 1.0, v149
	v_rcp_f32_e32 v149, v149
	v_add_f32_e32 v145, 1.0, v145
	v_add_f32_e32 v148, 1.0, v148
	v_rcp_f32_e32 v145, v145
	v_rcp_f32_e32 v148, v148
	v_mul_f32_e32 v149, v157, v149
	v_mul_f32_e32 v149, v161, v149
	v_mul_f32_e32 v145, v158, v145
	v_mul_f32_e32 v148, v159, v148
	v_mul_f32_e32 v145, v162, v145
	v_mul_f32_e32 v148, v163, v148
	v_cvt_pk_bf16_f32 v148, v145, v148
	v_mul_f32_e32 v145, 0xbfb8aa3b, v156
	v_exp_f32_e32 v145, v145
	v_lshl_add_u64 v[136:137], v[136:137], 0, v[138:139]
	v_add_f32_e32 v145, 1.0, v145
	v_rcp_f32_e32 v145, v145
	s_nop 0
	v_mul_f32_e32 v145, v156, v145
	v_mul_f32_e32 v145, v160, v145
	v_cvt_pk_bf16_f32 v149, v145, v149
	global_store_dwordx4 v[136:137], v[146:149], off
	s_cbranch_vccnz .LBB0_324
	v_mov_b32_e32 v2, 0
	s_mov_b32 s9, s61
	s_mov_b32 s8, s60
	s_mov_b64 s[12:13], s[28:29]
	s_mov_b64 s[10:11], s[34:35]
	s_mov_b32 s57, s2
	v_mov_b32_e32 v3, v2
	v_mov_b32_e32 v4, v2
	v_mov_b32_e32 v5, v2
	v_mov_b32_e32 v6, v2
	v_mov_b32_e32 v7, v2
	v_mov_b32_e32 v8, v2
	v_mov_b32_e32 v9, v2
	v_mov_b32_e32 v10, v2
	v_mov_b32_e32 v11, v2
	v_mov_b32_e32 v12, v2
	v_mov_b32_e32 v13, v2
	v_mov_b32_e32 v14, v2
	v_mov_b32_e32 v15, v2
	v_mov_b32_e32 v16, v2
	v_mov_b32_e32 v17, v2
	v_mov_b32_e32 v18, v2
	v_mov_b32_e32 v19, v2
	v_mov_b32_e32 v20, v2
	v_mov_b32_e32 v21, v2
	v_mov_b32_e32 v22, v2
	v_mov_b32_e32 v23, v2
	v_mov_b32_e32 v24, v2
	v_mov_b32_e32 v25, v2
	v_mov_b32_e32 v26, v2
	v_mov_b32_e32 v27, v2
	v_mov_b32_e32 v28, v2
	v_mov_b32_e32 v29, v2
	v_mov_b32_e32 v30, v2
	v_mov_b32_e32 v31, v2
	v_mov_b32_e32 v32, v2
	v_mov_b32_e32 v33, v2
	v_mov_b32_e32 v34, v2
	v_mov_b32_e32 v35, v2
	v_mov_b32_e32 v36, v2
	v_mov_b32_e32 v37, v2
	v_mov_b32_e32 v38, v2
	v_mov_b32_e32 v39, v2
	v_mov_b32_e32 v40, v2
	v_mov_b32_e32 v41, v2
	v_mov_b32_e32 v42, v2
	v_mov_b32_e32 v43, v2
	v_mov_b32_e32 v44, v2
	v_mov_b32_e32 v45, v2
	v_mov_b32_e32 v46, v2
	v_mov_b32_e32 v47, v2
	v_mov_b32_e32 v48, v2
	v_mov_b32_e32 v49, v2
	v_mov_b32_e32 v50, v2
	v_mov_b32_e32 v51, v2
	v_mov_b32_e32 v52, v2
	v_mov_b32_e32 v53, v2
	v_mov_b32_e32 v54, v2
	v_mov_b32_e32 v55, v2
	v_mov_b32_e32 v56, v2
	v_mov_b32_e32 v57, v2
	v_mov_b32_e32 v58, v2
	v_mov_b32_e32 v59, v2
	v_mov_b32_e32 v60, v2
	v_mov_b32_e32 v61, v2
	v_mov_b32_e32 v62, v2
	v_mov_b32_e32 v63, v2
	v_mov_b32_e32 v64, v2
	v_mov_b32_e32 v65, v2
	v_mov_b32_e32 v66, v2
	v_mov_b32_e32 v67, v2
	v_mov_b32_e32 v68, v2
	v_mov_b32_e32 v69, v2
	v_mov_b32_e32 v70, v2
	v_mov_b32_e32 v71, v2
	v_mov_b32_e32 v72, v2
	v_mov_b32_e32 v73, v2
	v_mov_b32_e32 v74, v2
	v_mov_b32_e32 v75, v2
	v_mov_b32_e32 v76, v2
	v_mov_b32_e32 v77, v2
	v_mov_b32_e32 v78, v2
	v_mov_b32_e32 v79, v2
	v_mov_b32_e32 v80, v2
	v_mov_b32_e32 v81, v2
	v_mov_b32_e32 v82, v2
	v_mov_b32_e32 v83, v2
	v_mov_b32_e32 v84, v2
	v_mov_b32_e32 v85, v2
	v_mov_b32_e32 v86, v2
	v_mov_b32_e32 v87, v2
	v_mov_b32_e32 v88, v2
	v_mov_b32_e32 v89, v2
	v_mov_b32_e32 v90, v2
	v_mov_b32_e32 v91, v2
	v_mov_b32_e32 v92, v2
	v_mov_b32_e32 v93, v2
	v_mov_b32_e32 v94, v2
	v_mov_b32_e32 v95, v2
	v_mov_b32_e32 v96, v2
	v_mov_b32_e32 v97, v2
	v_mov_b32_e32 v98, v2
	v_mov_b32_e32 v99, v2
	v_mov_b32_e32 v100, v2
	v_mov_b32_e32 v101, v2
	v_mov_b32_e32 v102, v2
	v_mov_b32_e32 v103, v2
	v_mov_b32_e32 v104, v2
	v_mov_b32_e32 v105, v2
	v_mov_b32_e32 v106, v2
	v_mov_b32_e32 v107, v2
	v_mov_b32_e32 v108, v2
	v_mov_b32_e32 v109, v2
	v_mov_b32_e32 v110, v2
	v_mov_b32_e32 v111, v2
	v_mov_b32_e32 v112, v2
	v_mov_b32_e32 v113, v2
	v_mov_b32_e32 v114, v2
	v_mov_b32_e32 v115, v2
	v_mov_b32_e32 v116, v2
	v_mov_b32_e32 v117, v2
	v_mov_b32_e32 v118, v2
	v_mov_b32_e32 v119, v2
	v_mov_b32_e32 v120, v2
	v_mov_b32_e32 v121, v2
	v_mov_b32_e32 v122, v2
	v_mov_b32_e32 v123, v2
	v_mov_b32_e32 v124, v2
	v_mov_b32_e32 v125, v2
	v_mov_b32_e32 v126, v2
	v_mov_b32_e32 v127, v2
	v_mov_b32_e32 v128, v2
	v_mov_b32_e32 v129, v2
	s_branch .LBB0_324
